# reduction steps use v_add_f32 with DPP operand (one instr per element per step)
# speedup vs baseline: 1.0053x; 1.0053x over previous
; DI float wave_sum(float v) { for (int o = 32; o; o >>= 1) v += __shfl_xor(v, o); return v; }
; DI void rmsnorm_phase(const float* x, const float* g, bf16_t* h, int ntok, const int tid) {
;     ...
;     for (int t0 = (blockIdx.x * 8 + wv) * 2; t0 < ntok; t0 += gridDim.x * 16) {
;         f32x4 v[2][4];
; #pragma unroll
;         for (int u = 0; u < 2; ++u)
; #pragma unroll
;             for (int c = 0; c < 4; ++c) v[u][c] = ((const f32x4*)(x + (size_t)(t0 + u) * 1024))[lane + 64 * c];
; #pragma unroll
;         for (int u = 0; u < 2; ++u) { float ss = 0.f;
; #pragma unroll
;             for (int c = 0; c < 4; ++c) ss += v[u][c][0] * v[u][c][0] + v[u][c][1] * v[u][c][1] + v[u][c][2] * v[u][c][2] + v[u][c][3] * v[u][c][3];
;             ss = wave_sum(ss);
;             const float rs = rsqrtf(ss * (1.f / 1024.f) + NEPS);
.LBB0_127:
	v_ashrrev_i32_e32 v51, 31, v50
	v_lshlrev_b64 v[18:19], 12, v[50:51]
	v_add_u32_e32 v56, 1, v50
	v_lshl_add_u64 v[18:19], v[52:53], 0, v[18:19]
	v_ashrrev_i32_e32 v57, 31, v56
	global_load_dwordx4 v[46:49], v[18:19], off
	global_load_dwordx4 v[42:45], v[18:19], off offset:1024
	global_load_dwordx4 v[38:41], v[18:19], off offset:2048
	global_load_dwordx4 v[34:37], v[18:19], off offset:3072
	v_lshlrev_b64 v[18:19], 12, v[56:57]
	v_lshl_add_u64 v[18:19], v[52:53], 0, v[18:19]
	global_load_dwordx4 v[30:33], v[18:19], off
	global_load_dwordx4 v[26:29], v[18:19], off offset:1024
	global_load_dwordx4 v[22:25], v[18:19], off offset:2048
	s_nop 0
	global_load_dwordx4 v[18:21], v[18:19], off offset:3072
	s_waitcnt vmcnt(0)
	v_mov_b32_e32 v66, v47
	v_mov_b32_e32 v67, v43
	v_mov_b32_e32 v58, v46
	v_mov_b32_e32 v72, v31
	v_mov_b32_e32 v73, v27
	v_mov_b32_e32 v59, v42
	v_pk_mul_f32 v[66:67], v[66:67], v[66:67]
	v_mov_b32_e32 v70, v30
	v_mov_b32_e32 v71, v26
	v_pk_mul_f32 v[72:73], v[72:73], v[72:73]
	v_pk_fma_f32 v[58:59], v[58:59], v[58:59], v[66:67]
	v_mov_b32_e32 v66, v48
	v_mov_b32_e32 v67, v44
	v_pk_fma_f32 v[70:71], v[70:71], v[70:71], v[72:73]
	v_mov_b32_e32 v72, v32
	v_mov_b32_e32 v73, v28
	v_pk_fma_f32 v[58:59], v[66:67], v[66:67], v[58:59]
	v_mov_b32_e32 v66, v49
	v_mov_b32_e32 v67, v45
	v_mov_b32_e32 v68, v39
	v_mov_b32_e32 v69, v35
	v_pk_fma_f32 v[70:71], v[72:73], v[72:73], v[70:71]
	v_mov_b32_e32 v72, v33
	v_mov_b32_e32 v73, v29
	v_mov_b32_e32 v74, v23
	v_mov_b32_e32 v75, v19
	v_pk_fma_f32 v[66:67], v[66:67], v[66:67], v[58:59]
	v_mov_b32_e32 v58, v38
	v_mov_b32_e32 v59, v34
	v_pk_mul_f32 v[68:69], v[68:69], v[68:69]
	v_pk_fma_f32 v[70:71], v[72:73], v[72:73], v[70:71]
	v_mov_b32_e32 v72, v22
	v_mov_b32_e32 v73, v18
	v_pk_mul_f32 v[74:75], v[74:75], v[74:75]
	v_pk_fma_f32 v[58:59], v[58:59], v[58:59], v[68:69]
	v_mov_b32_e32 v68, v40
	v_mov_b32_e32 v69, v36
	v_pk_fma_f32 v[72:73], v[72:73], v[72:73], v[74:75]
	v_mov_b32_e32 v74, v24
	v_mov_b32_e32 v75, v20
	v_pk_fma_f32 v[58:59], v[68:69], v[68:69], v[58:59]
	v_mov_b32_e32 v68, v41
	v_mov_b32_e32 v69, v37
	v_pk_fma_f32 v[72:73], v[74:75], v[74:75], v[72:73]
	v_mov_b32_e32 v74, v25
	v_mov_b32_e32 v75, v21
	v_pk_fma_f32 v[68:69], v[68:69], v[68:69], v[58:59]
	v_pk_fma_f32 v[72:73], v[74:75], v[74:75], v[72:73]
	v_mov_b32_e32 v74, v70
	v_mov_b32_e32 v75, v66
	v_mov_b32_e32 v66, v71
	v_pk_add_f32 v[66:67], v[74:75], v[66:67]
	v_mov_b32_e32 v70, v72
	v_mov_b32_e32 v71, v68
	v_pk_add_f32 v[66:67], v[66:67], v[70:71]
	v_mov_b32_e32 v68, v73
	v_pk_add_f32 v[66:67], v[66:67], v[68:69]
	v_mov_b32_e32 v69, v67
	v_mov_b32_e32 v68, v66
	s_nop 0
	v_permlane32_swap_b32_e32 v69, v67
	v_permlane32_swap_b32_e32 v68, v66
	v_lshlrev_b64 v[58:59], 11, v[50:51]
	v_lshl_add_u64 v[58:59], v[54:55], 0, v[58:59]
	v_add_u32_e32 v50, s17, v50
	s_waitcnt lgkmcnt(0)
	v_pk_add_f32 v[66:67], v[66:67], v[68:69]
	v_mov_b32_e32 v69, v67
	v_mov_b32_e32 v68, v66
	s_nop 0
	v_permlane16_swap_b32_e32 v69, v67
	v_permlane16_swap_b32_e32 v68, v66
	s_waitcnt lgkmcnt(0)
	v_pk_add_f32 v[66:67], v[66:67], v[68:69]
	s_nop 1
	v_add_f32_dpp v67, v67, v67 row_ror:8 row_mask:0xf bank_mask:0xf
	v_add_f32_dpp v66, v66, v66 row_ror:8 row_mask:0xf bank_mask:0xf
	s_waitcnt lgkmcnt(0)
	s_nop 1
	v_add_f32_dpp v67, v67, v67 row_ror:4 row_mask:0xf bank_mask:0xf
	v_add_f32_dpp v66, v66, v66 row_ror:4 row_mask:0xf bank_mask:0xf
	s_waitcnt lgkmcnt(0)
	s_nop 1
	v_add_f32_dpp v67, v67, v67 quad_perm:[2,3,0,1] row_mask:0xf bank_mask:0xf
	v_add_f32_dpp v66, v66, v66 quad_perm:[2,3,0,1] row_mask:0xf bank_mask:0xf
	s_waitcnt lgkmcnt(0)
; DI unsigned pk2(float lo, float hi) { const f32x2 v = {lo, hi}; return __builtin_bit_cast(unsigned, __builtin_convertvector(v, bf16v2_t)); }
; DI float wave_sum(float v) { for (int o = 32; o; o >>= 1) v += __shfl_xor(v, o); return v; }
; DI void rmsnorm_phase(const float* x, const float* g, bf16_t* h, int ntok, const int tid) {
;     ...
;             ss = wave_sum(ss);
;             const float rs = rsqrtf(ss * (1.f / 1024.f) + NEPS);
; #pragma unroll
;             for (int c = 0; c < 4; ++c) { u32x2 o; o[0] = pk2(v[u][c][0] * rs * gg[c][0], v[u][c][1] * rs * gg[c][1]); o[1] = pk2(v[u][c][2] * rs * gg[c][2], v[u][c][3] * rs * gg[c][3]);
;                 *(u32x2*)(h + (size_t)(t0 + u) * 1024 + (lane + 64 * c) * 4) = o; } }
	s_nop 1
	v_add_f32_dpp v67, v67, v67 quad_perm:[1,0,3,2] row_mask:0xf bank_mask:0xf
	v_add_f32_dpp v66, v66, v66 quad_perm:[1,0,3,2] row_mask:0xf bank_mask:0xf
	s_waitcnt lgkmcnt(0)
	s_nop 0
	v_pk_fma_f32 v[66:67], v[66:67], s[12:13], v[190:191] op_sel_hi:[1,0,0]
	s_nop 0
	v_mul_f32_e32 v0, 0x4b800000, v67
	v_cmp_gt_f32_e64 s[0:1], s77, v67
	v_cmp_gt_f32_e32 vcc, s77, v66
	s_nop 0
	v_cndmask_b32_e64 v0, v67, v0, s[0:1]
	v_rsq_f32_e32 v0, v0
	s_nop 0
	v_mul_f32_e32 v51, 0x45800000, v0
	v_cndmask_b32_e64 v0, v0, v51, s[0:1]
	v_pk_mul_f32 v[46:47], v[46:47], v[0:1] op_sel_hi:[1,0]
	v_pk_mul_f32 v[48:49], v[48:49], v[0:1] op_sel_hi:[1,0]
	v_pk_mul_f32 v[42:43], v[42:43], v[0:1] op_sel_hi:[1,0]
	v_pk_mul_f32 v[44:45], v[44:45], v[0:1] op_sel_hi:[1,0]
	v_pk_mul_f32 v[38:39], v[38:39], v[0:1] op_sel_hi:[1,0]
	v_pk_mul_f32 v[40:41], v[40:41], v[0:1] op_sel_hi:[1,0]
	v_pk_mul_f32 v[34:35], v[34:35], v[0:1] op_sel_hi:[1,0]
	v_pk_mul_f32 v[36:37], v[36:37], v[0:1] op_sel_hi:[1,0]
	v_mul_f32_e32 v0, 0x4b800000, v66
	v_cndmask_b32_e32 v0, v66, v0, vcc
	v_rsq_f32_e32 v0, v0
	v_pk_mul_f32 v[34:35], v[2:3], v[34:35]
	v_pk_mul_f32 v[36:37], v[4:5], v[36:37]
	v_cvt_pk_bf16_f32 v34, v34, v35
	v_cvt_pk_bf16_f32 v35, v36, v37
	global_store_dwordx2 v[58:59], v[34:35], off offset:1536
	v_mul_f32_e32 v34, 0x45800000, v0
	v_cndmask_b32_e32 v0, v0, v34, vcc
	v_pk_mul_f32 v[30:31], v[30:31], v[0:1] op_sel_hi:[1,0]
	v_pk_mul_f32 v[32:33], v[32:33], v[0:1] op_sel_hi:[1,0]
	v_pk_mul_f32 v[26:27], v[26:27], v[0:1] op_sel_hi:[1,0]
	v_pk_mul_f32 v[28:29], v[28:29], v[0:1] op_sel_hi:[1,0]
	v_pk_mul_f32 v[22:23], v[22:23], v[0:1] op_sel_hi:[1,0]
	v_pk_mul_f32 v[24:25], v[24:25], v[0:1] op_sel_hi:[1,0]
	v_pk_mul_f32 v[18:19], v[18:19], v[0:1] op_sel_hi:[1,0]
	v_pk_mul_f32 v[20:21], v[20:21], v[0:1] op_sel_hi:[1,0]
	v_pk_mul_f32 v[46:47], v[14:15], v[46:47]
	v_pk_mul_f32 v[48:49], v[16:17], v[48:49]
	v_pk_mul_f32 v[42:43], v[10:11], v[42:43]
	v_pk_mul_f32 v[44:45], v[12:13], v[44:45]
	v_pk_mul_f32 v[38:39], v[6:7], v[38:39]
	v_pk_mul_f32 v[40:41], v[8:9], v[40:41]
	v_lshlrev_b64 v[34:35], 11, v[56:57]
	v_pk_mul_f32 v[30:31], v[14:15], v[30:31]
	v_pk_mul_f32 v[32:33], v[16:17], v[32:33]
	v_pk_mul_f32 v[26:27], v[10:11], v[26:27]
	v_pk_mul_f32 v[28:29], v[12:13], v[28:29]
	v_pk_mul_f32 v[22:23], v[6:7], v[22:23]
	v_pk_mul_f32 v[24:25], v[8:9], v[24:25]
	v_pk_mul_f32 v[18:19], v[2:3], v[18:19]
	v_pk_mul_f32 v[20:21], v[4:5], v[20:21]
	v_cmp_lt_i32_e32 vcc, s16, v50
	v_cvt_pk_bf16_f32 v46, v46, v47
	v_cvt_pk_bf16_f32 v47, v48, v49
	v_cvt_pk_bf16_f32 v42, v42, v43
	v_cvt_pk_bf16_f32 v43, v44, v45
	v_cvt_pk_bf16_f32 v38, v38, v39
	v_cvt_pk_bf16_f32 v39, v40, v41
	v_cvt_pk_bf16_f32 v30, v30, v31
	v_cvt_pk_bf16_f32 v31, v32, v33
	v_lshl_add_u64 v[32:33], v[54:55], 0, v[34:35]
	v_cvt_pk_bf16_f32 v26, v26, v27
	v_cvt_pk_bf16_f32 v27, v28, v29
	v_cvt_pk_bf16_f32 v22, v22, v23
	v_cvt_pk_bf16_f32 v23, v24, v25
	v_cvt_pk_bf16_f32 v18, v18, v19
	v_cvt_pk_bf16_f32 v19, v20, v21
	s_or_b64 s[34:35], vcc, s[34:35]
	global_store_dwordx2 v[58:59], v[46:47], off
	global_store_dwordx2 v[58:59], v[42:43], off offset:512
	global_store_dwordx2 v[58:59], v[38:39], off offset:1024
	global_store_dwordx2 v[32:33], v[30:31], off
	global_store_dwordx2 v[32:33], v[26:27], off offset:512
	global_store_dwordx2 v[32:33], v[22:23], off offset:1024
	global_store_dwordx2 v[32:33], v[18:19], off offset:1536
	s_andn2_b64 exec, exec, s[34:35]
	s_cbranch_execnz .LBB0_127

.LBB0_207:
	v_add_u32_e32 v0, 0xfc0, v8
	v_mov_b64_e32 v[10:11], s[30:31]
	v_mad_u64_u32 v[10:11], s[0:1], v0, s3, v[10:11]
	s_lshl_b32 s4, s34, 1
	v_lshlrev_b64 v[38:39], 12, v[0:1]
	v_lshl_add_u64 v[10:11], v[10:11], 0, s[4:5]
	v_lshlrev_b32_e32 v0, 1, v6
	v_lshl_add_u64 v[6:7], v[10:11], 0, v[0:1]
	v_or_b32_e32 v10, 0x1000, v38
	v_mov_b32_e32 v11, v39
	v_lshl_add_u64 v[8:9], v[4:5], 0, v[38:39]
	v_lshl_add_u64 v[10:11], v[4:5], 0, v[10:11]
	global_load_dword v37, v[8:9], off
	global_load_dword v43, v[10:11], off
	global_load_dword v42, v[6:7], off offset:3072
	s_movk_i32 s0, 0x3000
	v_add_co_u32_e32 v10, vcc, s0, v6
	s_movk_i32 s0, 0x5000
	s_nop 0
	v_addc_co_u32_e32 v11, vcc, 0, v7, vcc
	global_load_dword v45, v[10:11], off offset:896
	v_or_b32_e32 v10, 0x2000, v38
	v_mov_b32_e32 v11, v39
	v_lshl_add_u64 v[10:11], v[4:5], 0, v[10:11]
	global_load_dword v35, v[10:11], off
	v_add_co_u32_e32 v10, vcc, s0, v6
	s_mov_b32 s4, 0x8000
	s_nop 0
	v_addc_co_u32_e32 v11, vcc, 0, v7, vcc
	global_load_dword v36, v[10:11], off offset:2816
	v_or_b32_e32 v10, 0x3000, v38
	v_mov_b32_e32 v11, v39
	v_lshl_add_u64 v[10:11], v[4:5], 0, v[10:11]
	global_load_dword v33, v[10:11], off
	v_add_co_u32_e32 v10, vcc, s4, v6
	s_mov_b32 s12, 0xa000
	s_nop 0
	v_addc_co_u32_e32 v11, vcc, 0, v7, vcc
	global_load_dword v34, v[10:11], off offset:640
	v_or_b32_e32 v10, 0x4000, v38
	v_mov_b32_e32 v11, v39
	v_lshl_add_u64 v[10:11], v[4:5], 0, v[10:11]
	global_load_dword v31, v[10:11], off
	v_add_co_u32_e32 v10, vcc, s12, v6
	s_mov_b32 s0, 0xd000
	s_nop 0
	v_addc_co_u32_e32 v11, vcc, 0, v7, vcc
	global_load_dword v32, v[10:11], off offset:2560
	v_or_b32_e32 v10, 0x5000, v38
	v_mov_b32_e32 v11, v39
	v_lshl_add_u64 v[10:11], v[4:5], 0, v[10:11]
	global_load_dword v29, v[10:11], off
	v_add_co_u32_e32 v10, vcc, s0, v6
	s_mov_b32 s0, 0xf000
	s_nop 0
	v_addc_co_u32_e32 v11, vcc, 0, v7, vcc
	global_load_dword v30, v[10:11], off offset:384
	v_or_b32_e32 v10, 0x6000, v38
	v_mov_b32_e32 v11, v39
	v_lshl_add_u64 v[10:11], v[4:5], 0, v[10:11]
	global_load_dword v27, v[10:11], off
	v_add_co_u32_e32 v10, vcc, s0, v6
	s_mov_b32 s0, 0x12000
	s_nop 0
	v_addc_co_u32_e32 v11, vcc, 0, v7, vcc
	global_load_dword v28, v[10:11], off offset:2304
	v_or_b32_e32 v10, 0x7000, v38
	v_mov_b32_e32 v11, v39
	v_lshl_add_u64 v[10:11], v[4:5], 0, v[10:11]
	global_load_dword v25, v[10:11], off
	v_add_co_u32_e32 v10, vcc, s0, v6
	s_mov_b32 s0, 0x14000
	s_nop 0
	v_addc_co_u32_e32 v11, vcc, 0, v7, vcc
	global_load_dword v26, v[10:11], off offset:128
	v_or_b32_e32 v10, 0x8000, v38
	v_mov_b32_e32 v11, v39
	v_lshl_add_u64 v[10:11], v[4:5], 0, v[10:11]
	global_load_dword v23, v[10:11], off
	v_add_co_u32_e32 v10, vcc, s0, v6
	s_mov_b32 s0, 0x16000
	s_nop 0
	v_addc_co_u32_e32 v11, vcc, 0, v7, vcc
	global_load_dword v24, v[10:11], off offset:2048
	v_or_b32_e32 v10, 0x9000, v38
	v_mov_b32_e32 v11, v39
	v_lshl_add_u64 v[10:11], v[4:5], 0, v[10:11]
	global_load_dword v21, v[10:11], off
	v_add_co_u32_e32 v10, vcc, s0, v6
	s_mov_b32 s0, 0x19000
	s_nop 0
	v_addc_co_u32_e32 v11, vcc, 0, v7, vcc
	global_load_dword v22, v[10:11], off offset:3968
	v_or_b32_e32 v10, 0xa000, v38
	v_mov_b32_e32 v11, v39
	v_lshl_add_u64 v[10:11], v[4:5], 0, v[10:11]
	global_load_dword v19, v[10:11], off
	v_add_co_u32_e32 v10, vcc, s0, v6
	s_mov_b32 s0, 0x1b000
	s_nop 0
	v_addc_co_u32_e32 v11, vcc, 0, v7, vcc
	global_load_dword v20, v[10:11], off offset:1792
	v_or_b32_e32 v10, 0xb000, v38
	v_mov_b32_e32 v11, v39
	v_lshl_add_u64 v[10:11], v[4:5], 0, v[10:11]
	global_load_dword v17, v[10:11], off
	v_add_co_u32_e32 v10, vcc, s0, v6
	s_mov_b32 s0, 0x1e000
	s_nop 0
	v_addc_co_u32_e32 v11, vcc, 0, v7, vcc
	global_load_dword v18, v[10:11], off offset:3712
	v_or_b32_e32 v10, 0xc000, v38
	v_mov_b32_e32 v11, v39
	v_lshl_add_u64 v[10:11], v[4:5], 0, v[10:11]
	global_load_dword v15, v[10:11], off
	v_add_co_u32_e32 v10, vcc, s0, v6
	s_mov_b32 s0, 0x20000
	s_nop 0
	v_addc_co_u32_e32 v11, vcc, 0, v7, vcc
	global_load_dword v16, v[10:11], off offset:1536
	v_or_b32_e32 v10, 0xd000, v38
	v_mov_b32_e32 v11, v39
	v_lshl_add_u64 v[10:11], v[4:5], 0, v[10:11]
	global_load_dword v13, v[10:11], off
	v_add_co_u32_e32 v10, vcc, s0, v6
	s_mov_b32 s0, 0x23000
	s_nop 0
	v_addc_co_u32_e32 v11, vcc, 0, v7, vcc
	global_load_dword v14, v[10:11], off offset:3456
	v_or_b32_e32 v10, 0xe000, v38
	v_mov_b32_e32 v11, v39
	v_add_co_u32_e32 v40, vcc, s0, v6
	v_or_b32_e32 v38, 0xf000, v38
	v_lshl_add_u64 v[10:11], v[4:5], 0, v[10:11]
	v_addc_co_u32_e32 v41, vcc, 0, v7, vcc
	v_lshl_add_u64 v[4:5], v[4:5], 0, v[38:39]
	s_mov_b32 s0, 0x25000
	global_load_dword v0, v[4:5], off
	v_add_co_u32_e32 v4, vcc, s0, v6
	global_load_dword v11, v[10:11], off
	s_nop 0
	v_addc_co_u32_e32 v5, vcc, 0, v7, vcc
	global_load_dword v10, v[4:5], off offset:3200
	s_waitcnt vmcnt(28)
	v_lshlrev_b32_e32 v4, 16, v42
	v_lshlrev_b32_e32 v6, 16, v37
	v_and_b32_e32 v7, 0xffff0000, v37
	v_mul_f32_e32 v37, 0xbfb8aa3b, v4
	v_exp_f32_e32 v37, v37
	v_and_b32_e32 v5, 0xffff0000, v42
	global_load_dword v12, v[40:41], off offset:1280
	v_lshlrev_b32_e32 v42, 16, v43
	v_add_f32_e32 v37, 1.0, v37
	v_rcp_f32_e32 v40, v37
	v_mul_f32_e32 v37, 0xbfb8aa3b, v5
	v_exp_f32_e32 v37, v37
	v_and_b32_e32 v43, 0xffff0000, v43
	v_pk_mul_f32 v[38:39], v[6:7], v[6:7]
	s_waitcnt vmcnt(28)
	v_lshlrev_b32_e32 v44, 16, v45
	v_add_f32_e32 v37, 1.0, v37
	v_rcp_f32_e32 v41, v37
	v_mov_b32_e32 v47, v38
	v_and_b32_e32 v45, 0xffff0000, v45
	v_pk_mul_f32 v[40:41], v[40:41], v[4:5]
	v_pk_mul_f32 v[4:5], v[42:43], v[42:43]
	s_nop 0
	v_mov_b32_e32 v46, v4
	v_mov_b32_e32 v38, v5
	v_pk_add_f32 v[4:5], v[46:47], v[38:39]
	v_mov_b32_e32 v39, v5
	v_mov_b32_e32 v38, v4
	s_nop 0
	v_permlane32_swap_b32_e32 v39, v5
	v_permlane32_swap_b32_e32 v38, v4
	s_waitcnt lgkmcnt(0)
	v_pk_add_f32 v[4:5], v[4:5], v[38:39]
	v_mov_b32_e32 v39, v5
	v_mov_b32_e32 v38, v4
	s_nop 0
	v_permlane16_swap_b32_e32 v39, v5
	v_permlane16_swap_b32_e32 v38, v4
	s_waitcnt lgkmcnt(0)
	v_pk_add_f32 v[4:5], v[4:5], v[38:39]
	s_nop 1
	v_add_f32_dpp v5, v5, v5 row_ror:8 row_mask:0xf bank_mask:0xf
	v_add_f32_dpp v4, v4, v4 row_ror:8 row_mask:0xf bank_mask:0xf
	s_waitcnt lgkmcnt(0)
	s_nop 1
	v_add_f32_dpp v5, v5, v5 row_ror:4 row_mask:0xf bank_mask:0xf
	v_add_f32_dpp v4, v4, v4 row_ror:4 row_mask:0xf bank_mask:0xf
	s_waitcnt lgkmcnt(0)
	s_nop 1
	v_add_f32_dpp v5, v5, v5 quad_perm:[2,3,0,1] row_mask:0xf bank_mask:0xf
	v_add_f32_dpp v4, v4, v4 quad_perm:[2,3,0,1] row_mask:0xf bank_mask:0xf
	s_waitcnt lgkmcnt(0)
	s_nop 1
	v_add_f32_dpp v39, v5, v5 quad_perm:[1,0,3,2] row_mask:0xf bank_mask:0xf
	v_add_f32_dpp v38, v4, v4 quad_perm:[1,0,3,2] row_mask:0xf bank_mask:0xf
	s_waitcnt lgkmcnt(0)
	v_mov_b64_e32 v[4:5], s[72:73]
	v_pk_fma_f32 v[38:39], v[38:39], s[96:97], v[4:5] op_sel_hi:[1,0,0]
	s_nop 0
	v_mul_f32_e32 v37, 0x4b800000, v39
	v_cmp_gt_f32_e64 s[0:1], s77, v39
	v_cmp_gt_f32_e32 vcc, s77, v38
	s_nop 0
	v_cndmask_b32_e64 v37, v39, v37, s[0:1]
	v_rsq_f32_e32 v37, v37
	s_nop 0
	v_mul_f32_e32 v39, 0x45800000, v37
	v_cndmask_b32_e64 v46, v37, v39, s[0:1]
	v_pk_mul_f32 v[6:7], v[46:47], v[6:7] op_sel_hi:[0,1]
	v_pk_mul_f32 v[6:7], v[2:3], v[6:7]
	v_mul_f32_e32 v37, 0xbfb8aa3b, v45
	v_pk_mul_f32 v[6:7], v[40:41], v[6:7]
	v_exp_f32_e32 v37, v37
	v_cvt_pk_bf16_f32 v6, v6, v7
	global_store_dword v[8:9], v6, off
	v_mul_f32_e32 v6, 0x4b800000, v38
	v_cndmask_b32_e32 v6, v38, v6, vcc
	v_rsq_f32_e32 v6, v6
	v_add_f32_e32 v37, 1.0, v37
	v_rcp_f32_e32 v39, v37
	s_waitcnt vmcnt(27)
	v_lshlrev_b32_e32 v40, 16, v36
	v_mul_f32_e32 v7, 0x45800000, v6
	v_cndmask_b32_e32 v6, v6, v7, vcc
	v_mul_f32_e32 v7, 0xbfb8aa3b, v44
	v_exp_f32_e32 v7, v7
	v_and_b32_e32 v41, 0xffff0000, v36
	s_movk_i32 s0, 0x2000
	v_add_f32_e32 v7, 1.0, v7
	v_rcp_f32_e32 v38, v7
	v_pk_mul_f32 v[6:7], v[6:7], v[42:43] op_sel_hi:[0,1]
	v_pk_mul_f32 v[6:7], v[2:3], v[6:7]
	v_pk_mul_f32 v[38:39], v[38:39], v[44:45]
	s_nop 0
	v_pk_mul_f32 v[6:7], v[38:39], v[6:7]
	v_lshlrev_b32_e32 v38, 16, v35
	v_and_b32_e32 v39, 0xffff0000, v35
	v_mul_f32_e32 v35, 0xbfb8aa3b, v40
	v_exp_f32_e32 v35, v35
	v_cvt_pk_bf16_f32 v37, v6, v7
	v_add_co_u32_e32 v6, vcc, s0, v8
	v_add_f32_e32 v35, 1.0, v35
	v_rcp_f32_e32 v42, v35
	v_mul_f32_e32 v35, 0xbfb8aa3b, v41
	v_exp_f32_e32 v35, v35
	v_addc_co_u32_e32 v7, vcc, 0, v9, vcc
	global_store_dword v[6:7], v37, off offset:-4096
	v_add_f32_e32 v35, 1.0, v35
	v_rcp_f32_e32 v43, v35
	v_pk_mul_f32 v[36:37], v[38:39], v[38:39]
	s_waitcnt vmcnt(26)
	v_lshlrev_b32_e32 v44, 16, v34
	v_and_b32_e32 v45, 0xffff0000, v34
	v_pk_mul_f32 v[40:41], v[42:43], v[40:41]
	v_lshlrev_b32_e32 v42, 16, v33
	v_and_b32_e32 v43, 0xffff0000, v33
	v_pk_mul_f32 v[34:35], v[42:43], v[42:43]
	v_mov_b32_e32 v47, v36
	v_mov_b32_e32 v46, v34
	v_mov_b32_e32 v36, v35
	v_pk_add_f32 v[34:35], v[46:47], v[36:37]
	v_mov_b32_e32 v37, v35
	v_mov_b32_e32 v36, v34
	s_nop 0
	v_permlane32_swap_b32_e32 v37, v35
	v_permlane32_swap_b32_e32 v36, v34
	s_waitcnt lgkmcnt(0)
	v_pk_add_f32 v[34:35], v[34:35], v[36:37]
	v_mov_b32_e32 v37, v35
	v_mov_b32_e32 v36, v34
	s_nop 0
	v_permlane16_swap_b32_e32 v37, v35
	v_permlane16_swap_b32_e32 v36, v34
	s_waitcnt lgkmcnt(0)
	v_pk_add_f32 v[34:35], v[34:35], v[36:37]
	s_nop 1
	v_add_f32_dpp v35, v35, v35 row_ror:8 row_mask:0xf bank_mask:0xf
	v_add_f32_dpp v34, v34, v34 row_ror:8 row_mask:0xf bank_mask:0xf
	s_waitcnt lgkmcnt(0)
	s_nop 1
	v_add_f32_dpp v35, v35, v35 row_ror:4 row_mask:0xf bank_mask:0xf
	v_add_f32_dpp v34, v34, v34 row_ror:4 row_mask:0xf bank_mask:0xf
	s_waitcnt lgkmcnt(0)
	s_nop 1
	v_add_f32_dpp v35, v35, v35 quad_perm:[2,3,0,1] row_mask:0xf bank_mask:0xf
	v_add_f32_dpp v34, v34, v34 quad_perm:[2,3,0,1] row_mask:0xf bank_mask:0xf
	s_waitcnt lgkmcnt(0)
	s_nop 1
	v_add_f32_dpp v35, v35, v35 quad_perm:[1,0,3,2] row_mask:0xf bank_mask:0xf
	v_add_f32_dpp v34, v34, v34 quad_perm:[1,0,3,2] row_mask:0xf bank_mask:0xf
	s_waitcnt lgkmcnt(0)
	s_nop 0
	v_pk_fma_f32 v[34:35], v[34:35], s[96:97], v[4:5] op_sel_hi:[1,0,0]
	s_nop 0
	v_mul_f32_e32 v33, 0x4b800000, v35
	v_cmp_gt_f32_e64 s[0:1], s77, v35
	v_cmp_gt_f32_e32 vcc, s77, v34
	s_nop 0
	v_cndmask_b32_e64 v33, v35, v33, s[0:1]
	v_rsq_f32_e32 v33, v33
	s_nop 0
	v_mul_f32_e32 v35, 0x45800000, v33
	v_cndmask_b32_e64 v36, v33, v35, s[0:1]
	v_pk_mul_f32 v[36:37], v[36:37], v[38:39] op_sel_hi:[0,1]
	v_pk_mul_f32 v[36:37], v[2:3], v[36:37]
	s_nop 0
	v_pk_mul_f32 v[36:37], v[40:41], v[36:37]
	s_waitcnt vmcnt(22)
	v_lshlrev_b32_e32 v40, 16, v30
	v_cvt_pk_bf16_f32 v33, v36, v37
	global_store_dword v[6:7], v33, off
	v_mul_f32_e32 v6, 0x4b800000, v34
	v_cndmask_b32_e32 v6, v34, v6, vcc
	v_rsq_f32_e32 v6, v6
	v_mul_f32_e32 v33, 0xbfb8aa3b, v45
	v_exp_f32_e32 v33, v33
	v_lshlrev_b32_e32 v36, 16, v32
	v_mul_f32_e32 v7, 0x45800000, v6
	v_cndmask_b32_e32 v6, v6, v7, vcc
	v_mul_f32_e32 v7, 0xbfb8aa3b, v44
	v_exp_f32_e32 v7, v7
	v_add_f32_e32 v33, 1.0, v33
	v_rcp_f32_e32 v35, v33
	v_and_b32_e32 v37, 0xffff0000, v32
	v_add_f32_e32 v7, 1.0, v7
	v_rcp_f32_e32 v34, v7
	v_pk_mul_f32 v[6:7], v[6:7], v[42:43] op_sel_hi:[0,1]
	v_pk_mul_f32 v[6:7], v[2:3], v[6:7]
	v_and_b32_e32 v41, 0xffff0000, v30
	v_pk_mul_f32 v[34:35], v[34:35], v[44:45]
	s_nop 0
	v_pk_mul_f32 v[6:7], v[34:35], v[6:7]
	v_lshlrev_b32_e32 v34, 16, v31
	v_and_b32_e32 v35, 0xffff0000, v31
	v_mul_f32_e32 v31, 0xbfb8aa3b, v36
	v_exp_f32_e32 v31, v31
	v_cvt_pk_bf16_f32 v33, v6, v7
	v_add_co_u32_e32 v6, vcc, s76, v8
	v_add_f32_e32 v31, 1.0, v31
	v_rcp_f32_e32 v38, v31
	v_mul_f32_e32 v31, 0xbfb8aa3b, v37
	v_exp_f32_e32 v31, v31
	v_addc_co_u32_e32 v7, vcc, 0, v9, vcc
	global_store_dword v[6:7], v33, off offset:-4096
	v_add_f32_e32 v31, 1.0, v31
	v_rcp_f32_e32 v39, v31
	v_pk_mul_f32 v[32:33], v[34:35], v[34:35]
	v_pk_mul_f32 v[36:37], v[38:39], v[36:37]
	v_lshlrev_b32_e32 v38, 16, v29
	v_and_b32_e32 v39, 0xffff0000, v29
	v_pk_mul_f32 v[30:31], v[38:39], v[38:39]
	v_mov_b32_e32 v43, v32
	v_mov_b32_e32 v42, v30
	v_mov_b32_e32 v32, v31
	v_pk_add_f32 v[30:31], v[42:43], v[32:33]
	v_mov_b32_e32 v33, v31
	v_mov_b32_e32 v32, v30
	s_nop 0
	v_permlane32_swap_b32_e32 v33, v31
	v_permlane32_swap_b32_e32 v32, v30
	s_waitcnt lgkmcnt(0)
	v_pk_add_f32 v[30:31], v[30:31], v[32:33]
	v_mov_b32_e32 v33, v31
	v_mov_b32_e32 v32, v30
	s_nop 0
	v_permlane16_swap_b32_e32 v33, v31
	v_permlane16_swap_b32_e32 v32, v30
	s_waitcnt lgkmcnt(0)
	v_pk_add_f32 v[30:31], v[30:31], v[32:33]
	s_nop 1
	v_add_f32_dpp v31, v31, v31 row_ror:8 row_mask:0xf bank_mask:0xf
	v_add_f32_dpp v30, v30, v30 row_ror:8 row_mask:0xf bank_mask:0xf
	s_waitcnt lgkmcnt(0)
	s_nop 1
	v_add_f32_dpp v31, v31, v31 row_ror:4 row_mask:0xf bank_mask:0xf
	v_add_f32_dpp v30, v30, v30 row_ror:4 row_mask:0xf bank_mask:0xf
	s_waitcnt lgkmcnt(0)
	s_nop 1
	v_add_f32_dpp v31, v31, v31 quad_perm:[2,3,0,1] row_mask:0xf bank_mask:0xf
	v_add_f32_dpp v30, v30, v30 quad_perm:[2,3,0,1] row_mask:0xf bank_mask:0xf
	s_waitcnt lgkmcnt(0)
	s_nop 1
	v_add_f32_dpp v31, v31, v31 quad_perm:[1,0,3,2] row_mask:0xf bank_mask:0xf
	v_add_f32_dpp v30, v30, v30 quad_perm:[1,0,3,2] row_mask:0xf bank_mask:0xf
	s_waitcnt lgkmcnt(0)
	s_nop 0
	v_pk_fma_f32 v[30:31], v[30:31], s[96:97], v[4:5] op_sel_hi:[1,0,0]
	s_nop 0
	v_mul_f32_e32 v29, 0x4b800000, v31
	v_cmp_gt_f32_e64 s[0:1], s77, v31
	v_cmp_gt_f32_e32 vcc, s77, v30
	s_nop 0
	v_cndmask_b32_e64 v29, v31, v29, s[0:1]
	v_rsq_f32_e32 v29, v29
	s_nop 0
	v_mul_f32_e32 v31, 0x45800000, v29
	v_cndmask_b32_e64 v32, v29, v31, s[0:1]
	v_pk_mul_f32 v[32:33], v[32:33], v[34:35] op_sel_hi:[0,1]
	v_pk_mul_f32 v[32:33], v[2:3], v[32:33]
	s_movk_i32 s0, 0x6000
	v_pk_mul_f32 v[32:33], v[36:37], v[32:33]
	s_waitcnt vmcnt(20)
	v_lshlrev_b32_e32 v36, 16, v26
	v_cvt_pk_bf16_f32 v29, v32, v33
	global_store_dword v[6:7], v29, off
	v_mul_f32_e32 v6, 0x4b800000, v30
	v_cndmask_b32_e32 v6, v30, v6, vcc
	v_rsq_f32_e32 v6, v6
	v_mul_f32_e32 v29, 0xbfb8aa3b, v41
	v_exp_f32_e32 v29, v29
	v_lshlrev_b32_e32 v32, 16, v28
	v_mul_f32_e32 v7, 0x45800000, v6
	v_cndmask_b32_e32 v6, v6, v7, vcc
	v_mul_f32_e32 v7, 0xbfb8aa3b, v40
	v_exp_f32_e32 v7, v7
	v_add_f32_e32 v29, 1.0, v29
	v_rcp_f32_e32 v31, v29
	v_and_b32_e32 v33, 0xffff0000, v28
	v_add_f32_e32 v7, 1.0, v7
	v_rcp_f32_e32 v30, v7
	v_pk_mul_f32 v[6:7], v[6:7], v[38:39] op_sel_hi:[0,1]
	v_pk_mul_f32 v[6:7], v[2:3], v[6:7]
	v_and_b32_e32 v37, 0xffff0000, v26
	v_pk_mul_f32 v[30:31], v[30:31], v[40:41]
	s_nop 0
	v_pk_mul_f32 v[6:7], v[30:31], v[6:7]
	v_lshlrev_b32_e32 v30, 16, v27
	v_and_b32_e32 v31, 0xffff0000, v27
	v_mul_f32_e32 v27, 0xbfb8aa3b, v32
	v_exp_f32_e32 v27, v27
	v_cvt_pk_bf16_f32 v29, v6, v7
	v_add_co_u32_e32 v6, vcc, s0, v8
	v_add_f32_e32 v27, 1.0, v27
	v_rcp_f32_e32 v34, v27
	v_mul_f32_e32 v27, 0xbfb8aa3b, v33
	v_exp_f32_e32 v27, v27
	v_addc_co_u32_e32 v7, vcc, 0, v9, vcc
	global_store_dword v[6:7], v29, off offset:-4096
	v_add_f32_e32 v27, 1.0, v27
	v_rcp_f32_e32 v35, v27
	v_pk_mul_f32 v[28:29], v[30:31], v[30:31]
	v_pk_mul_f32 v[32:33], v[34:35], v[32:33]
	v_lshlrev_b32_e32 v34, 16, v25
	v_and_b32_e32 v35, 0xffff0000, v25
	v_pk_mul_f32 v[26:27], v[34:35], v[34:35]
	v_mov_b32_e32 v39, v28
	v_mov_b32_e32 v38, v26
	v_mov_b32_e32 v28, v27
	v_pk_add_f32 v[26:27], v[38:39], v[28:29]
	v_mov_b32_e32 v29, v27
	v_mov_b32_e32 v28, v26
	s_nop 0
	v_permlane32_swap_b32_e32 v29, v27
	v_permlane32_swap_b32_e32 v28, v26
	s_waitcnt lgkmcnt(0)
	v_pk_add_f32 v[26:27], v[26:27], v[28:29]
	v_mov_b32_e32 v29, v27
	v_mov_b32_e32 v28, v26
	s_nop 0
	v_permlane16_swap_b32_e32 v29, v27
	v_permlane16_swap_b32_e32 v28, v26
	s_waitcnt lgkmcnt(0)
	v_pk_add_f32 v[26:27], v[26:27], v[28:29]
	s_nop 1
	v_add_f32_dpp v27, v27, v27 row_ror:8 row_mask:0xf bank_mask:0xf
	v_add_f32_dpp v26, v26, v26 row_ror:8 row_mask:0xf bank_mask:0xf
	s_waitcnt lgkmcnt(0)
	s_nop 1
	v_add_f32_dpp v27, v27, v27 row_ror:4 row_mask:0xf bank_mask:0xf
	v_add_f32_dpp v26, v26, v26 row_ror:4 row_mask:0xf bank_mask:0xf
	s_waitcnt lgkmcnt(0)
	s_nop 1
	v_add_f32_dpp v27, v27, v27 quad_perm:[2,3,0,1] row_mask:0xf bank_mask:0xf
	v_add_f32_dpp v26, v26, v26 quad_perm:[2,3,0,1] row_mask:0xf bank_mask:0xf
	s_waitcnt lgkmcnt(0)
	s_nop 1
	v_add_f32_dpp v27, v27, v27 quad_perm:[1,0,3,2] row_mask:0xf bank_mask:0xf
	v_add_f32_dpp v26, v26, v26 quad_perm:[1,0,3,2] row_mask:0xf bank_mask:0xf
	s_waitcnt lgkmcnt(0)
	s_nop 0
	v_pk_fma_f32 v[26:27], v[26:27], s[96:97], v[4:5] op_sel_hi:[1,0,0]
	s_nop 0
	v_mul_f32_e32 v25, 0x4b800000, v27
	v_cmp_gt_f32_e64 s[0:1], s77, v27
	v_cmp_gt_f32_e32 vcc, s77, v26
	s_nop 0
	v_cndmask_b32_e64 v25, v27, v25, s[0:1]
	v_rsq_f32_e32 v25, v25
	s_nop 0
	v_mul_f32_e32 v27, 0x45800000, v25
	v_cndmask_b32_e64 v28, v25, v27, s[0:1]
	v_pk_mul_f32 v[28:29], v[28:29], v[30:31] op_sel_hi:[0,1]
	v_pk_mul_f32 v[28:29], v[2:3], v[28:29]
	s_nop 0
	v_pk_mul_f32 v[28:29], v[32:33], v[28:29]
	s_waitcnt vmcnt(18)
	v_lshlrev_b32_e32 v32, 16, v22
	v_cvt_pk_bf16_f32 v25, v28, v29
	global_store_dword v[6:7], v25, off
	v_mul_f32_e32 v6, 0x4b800000, v26
	v_cndmask_b32_e32 v6, v26, v6, vcc
	v_rsq_f32_e32 v6, v6
	v_mul_f32_e32 v25, 0xbfb8aa3b, v37
	v_exp_f32_e32 v25, v25
	v_lshlrev_b32_e32 v28, 16, v24
	v_mul_f32_e32 v7, 0x45800000, v6
	v_cndmask_b32_e32 v6, v6, v7, vcc
	v_mul_f32_e32 v7, 0xbfb8aa3b, v36
	v_exp_f32_e32 v7, v7
	v_add_f32_e32 v25, 1.0, v25
	v_rcp_f32_e32 v27, v25
	v_and_b32_e32 v29, 0xffff0000, v24
	v_add_f32_e32 v7, 1.0, v7
	v_rcp_f32_e32 v26, v7
	v_pk_mul_f32 v[6:7], v[6:7], v[34:35] op_sel_hi:[0,1]
	v_pk_mul_f32 v[6:7], v[2:3], v[6:7]
	v_and_b32_e32 v33, 0xffff0000, v22
	v_pk_mul_f32 v[26:27], v[26:27], v[36:37]
	s_nop 0
	v_pk_mul_f32 v[6:7], v[26:27], v[6:7]
	v_lshlrev_b32_e32 v26, 16, v23
	v_and_b32_e32 v27, 0xffff0000, v23
	v_mul_f32_e32 v23, 0xbfb8aa3b, v28
	v_exp_f32_e32 v23, v23
	v_cvt_pk_bf16_f32 v25, v6, v7
	v_add_co_u32_e32 v6, vcc, s4, v8
	v_add_f32_e32 v23, 1.0, v23
	v_rcp_f32_e32 v30, v23
	v_mul_f32_e32 v23, 0xbfb8aa3b, v29
	v_exp_f32_e32 v23, v23
	v_addc_co_u32_e32 v7, vcc, 0, v9, vcc
	global_store_dword v[6:7], v25, off offset:-4096
	v_add_f32_e32 v23, 1.0, v23
	v_rcp_f32_e32 v31, v23
	v_pk_mul_f32 v[24:25], v[26:27], v[26:27]
	v_pk_mul_f32 v[28:29], v[30:31], v[28:29]
	v_lshlrev_b32_e32 v30, 16, v21
	v_and_b32_e32 v31, 0xffff0000, v21
	v_pk_mul_f32 v[22:23], v[30:31], v[30:31]
	v_mov_b32_e32 v35, v24
	v_mov_b32_e32 v34, v22
	v_mov_b32_e32 v24, v23
	v_pk_add_f32 v[22:23], v[34:35], v[24:25]
	v_mov_b32_e32 v25, v23
	v_mov_b32_e32 v24, v22
	s_nop 0
	v_permlane32_swap_b32_e32 v25, v23
	v_permlane32_swap_b32_e32 v24, v22
	s_waitcnt lgkmcnt(0)
	v_pk_add_f32 v[22:23], v[22:23], v[24:25]
	v_mov_b32_e32 v25, v23
	v_mov_b32_e32 v24, v22
	s_nop 0
	v_permlane16_swap_b32_e32 v25, v23
	v_permlane16_swap_b32_e32 v24, v22
	s_waitcnt lgkmcnt(0)
	v_pk_add_f32 v[22:23], v[22:23], v[24:25]
	s_nop 1
	v_add_f32_dpp v23, v23, v23 row_ror:8 row_mask:0xf bank_mask:0xf
	v_add_f32_dpp v22, v22, v22 row_ror:8 row_mask:0xf bank_mask:0xf
	s_waitcnt lgkmcnt(0)
	s_nop 1
	v_add_f32_dpp v23, v23, v23 row_ror:4 row_mask:0xf bank_mask:0xf
	v_add_f32_dpp v22, v22, v22 row_ror:4 row_mask:0xf bank_mask:0xf
	s_waitcnt lgkmcnt(0)
	s_nop 1
	v_add_f32_dpp v23, v23, v23 quad_perm:[2,3,0,1] row_mask:0xf bank_mask:0xf
	v_add_f32_dpp v22, v22, v22 quad_perm:[2,3,0,1] row_mask:0xf bank_mask:0xf
	s_waitcnt lgkmcnt(0)
	s_nop 1
	v_add_f32_dpp v23, v23, v23 quad_perm:[1,0,3,2] row_mask:0xf bank_mask:0xf
	v_add_f32_dpp v22, v22, v22 quad_perm:[1,0,3,2] row_mask:0xf bank_mask:0xf
	s_waitcnt lgkmcnt(0)
	s_nop 0
	v_pk_fma_f32 v[22:23], v[22:23], s[96:97], v[4:5] op_sel_hi:[1,0,0]
	s_nop 0
	v_mul_f32_e32 v21, 0x4b800000, v23
	v_cmp_gt_f32_e64 s[0:1], s77, v23
	v_cmp_gt_f32_e32 vcc, s77, v22
	s_nop 0
	v_cndmask_b32_e64 v21, v23, v21, s[0:1]
	v_rsq_f32_e32 v21, v21
	s_nop 0
	v_mul_f32_e32 v23, 0x45800000, v21
	v_cndmask_b32_e64 v24, v21, v23, s[0:1]
	v_pk_mul_f32 v[24:25], v[24:25], v[26:27] op_sel_hi:[0,1]
	v_pk_mul_f32 v[24:25], v[2:3], v[24:25]
	s_nop 0
	v_pk_mul_f32 v[24:25], v[28:29], v[24:25]
	s_waitcnt vmcnt(16)
	v_lshlrev_b32_e32 v28, 16, v18
	v_cvt_pk_bf16_f32 v21, v24, v25
	global_store_dword v[6:7], v21, off
	v_mul_f32_e32 v6, 0x4b800000, v22
	v_cndmask_b32_e32 v6, v22, v6, vcc
	v_rsq_f32_e32 v6, v6
	v_mul_f32_e32 v21, 0xbfb8aa3b, v33
	v_exp_f32_e32 v21, v21
	v_lshlrev_b32_e32 v24, 16, v20
	v_mul_f32_e32 v7, 0x45800000, v6
	v_cndmask_b32_e32 v6, v6, v7, vcc
	v_mul_f32_e32 v7, 0xbfb8aa3b, v32
	v_exp_f32_e32 v7, v7
	v_add_f32_e32 v21, 1.0, v21
	v_rcp_f32_e32 v23, v21
	v_and_b32_e32 v25, 0xffff0000, v20
	v_add_f32_e32 v7, 1.0, v7
	v_rcp_f32_e32 v22, v7
	v_pk_mul_f32 v[6:7], v[6:7], v[30:31] op_sel_hi:[0,1]
	v_pk_mul_f32 v[6:7], v[2:3], v[6:7]
	v_and_b32_e32 v29, 0xffff0000, v18
	v_pk_mul_f32 v[22:23], v[22:23], v[32:33]
	s_nop 0
	v_pk_mul_f32 v[6:7], v[22:23], v[6:7]
	v_lshlrev_b32_e32 v22, 16, v19
	v_and_b32_e32 v23, 0xffff0000, v19
	v_mul_f32_e32 v19, 0xbfb8aa3b, v24
	v_exp_f32_e32 v19, v19
	v_cvt_pk_bf16_f32 v21, v6, v7
	v_add_co_u32_e32 v6, vcc, s12, v8
	v_add_f32_e32 v19, 1.0, v19
	v_rcp_f32_e32 v26, v19
	v_mul_f32_e32 v19, 0xbfb8aa3b, v25
	v_exp_f32_e32 v19, v19
	v_addc_co_u32_e32 v7, vcc, 0, v9, vcc
	global_store_dword v[6:7], v21, off offset:-4096
	v_add_f32_e32 v19, 1.0, v19
	v_rcp_f32_e32 v27, v19
	v_pk_mul_f32 v[20:21], v[22:23], v[22:23]
	v_pk_mul_f32 v[24:25], v[26:27], v[24:25]
	v_lshlrev_b32_e32 v26, 16, v17
	v_and_b32_e32 v27, 0xffff0000, v17
	v_pk_mul_f32 v[18:19], v[26:27], v[26:27]
	v_mov_b32_e32 v31, v20
	v_mov_b32_e32 v30, v18
	v_mov_b32_e32 v20, v19
	v_pk_add_f32 v[18:19], v[30:31], v[20:21]
	v_mov_b32_e32 v21, v19
	v_mov_b32_e32 v20, v18
	s_nop 0
	v_permlane32_swap_b32_e32 v21, v19
	v_permlane32_swap_b32_e32 v20, v18
	s_waitcnt lgkmcnt(0)
	v_pk_add_f32 v[18:19], v[18:19], v[20:21]
	v_mov_b32_e32 v21, v19
	v_mov_b32_e32 v20, v18
	s_nop 0
	v_permlane16_swap_b32_e32 v21, v19
	v_permlane16_swap_b32_e32 v20, v18
	s_waitcnt lgkmcnt(0)
	v_pk_add_f32 v[18:19], v[18:19], v[20:21]
	s_nop 1
	v_add_f32_dpp v19, v19, v19 row_ror:8 row_mask:0xf bank_mask:0xf
	v_add_f32_dpp v18, v18, v18 row_ror:8 row_mask:0xf bank_mask:0xf
	s_waitcnt lgkmcnt(0)
	s_nop 1
	v_add_f32_dpp v19, v19, v19 row_ror:4 row_mask:0xf bank_mask:0xf
	v_add_f32_dpp v18, v18, v18 row_ror:4 row_mask:0xf bank_mask:0xf
	s_waitcnt lgkmcnt(0)
	s_nop 1
	v_add_f32_dpp v19, v19, v19 quad_perm:[2,3,0,1] row_mask:0xf bank_mask:0xf
	v_add_f32_dpp v18, v18, v18 quad_perm:[2,3,0,1] row_mask:0xf bank_mask:0xf
	s_waitcnt lgkmcnt(0)
	s_nop 1
	v_add_f32_dpp v19, v19, v19 quad_perm:[1,0,3,2] row_mask:0xf bank_mask:0xf
	v_add_f32_dpp v18, v18, v18 quad_perm:[1,0,3,2] row_mask:0xf bank_mask:0xf
	s_waitcnt lgkmcnt(0)
	s_nop 0
	v_pk_fma_f32 v[18:19], v[18:19], s[96:97], v[4:5] op_sel_hi:[1,0,0]
	s_nop 0
	v_mul_f32_e32 v17, 0x4b800000, v19
	v_cmp_gt_f32_e64 s[0:1], s77, v19
	v_cmp_gt_f32_e32 vcc, s77, v18
	s_nop 0
	v_cndmask_b32_e64 v17, v19, v17, s[0:1]
	v_rsq_f32_e32 v17, v17
	s_nop 0
	v_mul_f32_e32 v19, 0x45800000, v17
	v_cndmask_b32_e64 v20, v17, v19, s[0:1]
	v_pk_mul_f32 v[20:21], v[20:21], v[22:23] op_sel_hi:[0,1]
	v_pk_mul_f32 v[20:21], v[2:3], v[20:21]
	s_mov_b32 s0, 0xc000
	v_pk_mul_f32 v[20:21], v[24:25], v[20:21]
	s_waitcnt vmcnt(14)
	v_lshlrev_b32_e32 v24, 16, v14
	v_cvt_pk_bf16_f32 v17, v20, v21
	global_store_dword v[6:7], v17, off
	v_mul_f32_e32 v6, 0x4b800000, v18
	v_cndmask_b32_e32 v6, v18, v6, vcc
	v_rsq_f32_e32 v6, v6
	v_mul_f32_e32 v17, 0xbfb8aa3b, v29
	v_exp_f32_e32 v17, v17
	v_lshlrev_b32_e32 v20, 16, v16
	v_mul_f32_e32 v7, 0x45800000, v6
	v_cndmask_b32_e32 v6, v6, v7, vcc
	v_mul_f32_e32 v7, 0xbfb8aa3b, v28
	v_exp_f32_e32 v7, v7
	v_add_f32_e32 v17, 1.0, v17
	v_rcp_f32_e32 v19, v17
	v_and_b32_e32 v21, 0xffff0000, v16
	v_add_f32_e32 v7, 1.0, v7
	v_rcp_f32_e32 v18, v7
	v_pk_mul_f32 v[6:7], v[6:7], v[26:27] op_sel_hi:[0,1]
	v_pk_mul_f32 v[6:7], v[2:3], v[6:7]
	v_and_b32_e32 v25, 0xffff0000, v14
	v_pk_mul_f32 v[18:19], v[18:19], v[28:29]
	s_nop 0
	v_pk_mul_f32 v[6:7], v[18:19], v[6:7]
	v_lshlrev_b32_e32 v18, 16, v15
	v_and_b32_e32 v19, 0xffff0000, v15
	v_mul_f32_e32 v15, 0xbfb8aa3b, v20
	v_exp_f32_e32 v15, v15
	v_cvt_pk_bf16_f32 v17, v6, v7
	v_add_co_u32_e32 v6, vcc, s0, v8
	v_add_f32_e32 v15, 1.0, v15
	v_rcp_f32_e32 v22, v15
	v_mul_f32_e32 v15, 0xbfb8aa3b, v21
	v_exp_f32_e32 v15, v15
	v_addc_co_u32_e32 v7, vcc, 0, v9, vcc
	global_store_dword v[6:7], v17, off offset:-4096
	v_add_f32_e32 v15, 1.0, v15
	v_rcp_f32_e32 v23, v15
	v_pk_mul_f32 v[16:17], v[18:19], v[18:19]
	v_pk_mul_f32 v[20:21], v[22:23], v[20:21]
	v_lshlrev_b32_e32 v22, 16, v13
	v_and_b32_e32 v23, 0xffff0000, v13
	v_pk_mul_f32 v[14:15], v[22:23], v[22:23]
	v_mov_b32_e32 v27, v16
	v_mov_b32_e32 v26, v14
	v_mov_b32_e32 v16, v15
	v_pk_add_f32 v[14:15], v[26:27], v[16:17]
	v_mov_b32_e32 v17, v15
	v_mov_b32_e32 v16, v14
	s_nop 0
	v_permlane32_swap_b32_e32 v17, v15
	v_permlane32_swap_b32_e32 v16, v14
	s_waitcnt lgkmcnt(0)
	v_pk_add_f32 v[14:15], v[14:15], v[16:17]
	v_mov_b32_e32 v17, v15
	v_mov_b32_e32 v16, v14
	s_nop 0
	v_permlane16_swap_b32_e32 v17, v15
	v_permlane16_swap_b32_e32 v16, v14
	s_waitcnt lgkmcnt(0)
	v_pk_add_f32 v[14:15], v[14:15], v[16:17]
	s_nop 1
	v_add_f32_dpp v15, v15, v15 row_ror:8 row_mask:0xf bank_mask:0xf
	v_add_f32_dpp v14, v14, v14 row_ror:8 row_mask:0xf bank_mask:0xf
	s_waitcnt lgkmcnt(0)
	s_nop 1
	v_add_f32_dpp v15, v15, v15 row_ror:4 row_mask:0xf bank_mask:0xf
	v_add_f32_dpp v14, v14, v14 row_ror:4 row_mask:0xf bank_mask:0xf
	s_waitcnt lgkmcnt(0)
	s_nop 1
	v_add_f32_dpp v15, v15, v15 quad_perm:[2,3,0,1] row_mask:0xf bank_mask:0xf
	v_add_f32_dpp v14, v14, v14 quad_perm:[2,3,0,1] row_mask:0xf bank_mask:0xf
	s_waitcnt lgkmcnt(0)
	s_nop 1
	v_add_f32_dpp v15, v15, v15 quad_perm:[1,0,3,2] row_mask:0xf bank_mask:0xf
	v_add_f32_dpp v14, v14, v14 quad_perm:[1,0,3,2] row_mask:0xf bank_mask:0xf
	s_waitcnt lgkmcnt(0)
	s_nop 0
	v_pk_fma_f32 v[14:15], v[14:15], s[96:97], v[4:5] op_sel_hi:[1,0,0]
	s_nop 0
	v_mul_f32_e32 v13, 0x4b800000, v15
	v_cmp_gt_f32_e64 s[0:1], s77, v15
	v_cmp_gt_f32_e32 vcc, s77, v14
	s_nop 0
	v_cndmask_b32_e64 v13, v15, v13, s[0:1]
	v_rsq_f32_e32 v13, v13
	s_nop 0
	v_mul_f32_e32 v15, 0x45800000, v13
	v_cndmask_b32_e64 v16, v13, v15, s[0:1]
	v_pk_mul_f32 v[16:17], v[16:17], v[18:19] op_sel_hi:[0,1]
	v_pk_mul_f32 v[16:17], v[2:3], v[16:17]
	s_mov_b32 s0, 0xe000
	v_pk_mul_f32 v[16:17], v[20:21], v[16:17]
	s_waitcnt vmcnt(13)
	v_lshlrev_b32_e32 v20, 16, v10
	v_cvt_pk_bf16_f32 v13, v16, v17
	global_store_dword v[6:7], v13, off
	v_mul_f32_e32 v6, 0x4b800000, v14
	v_cndmask_b32_e32 v6, v14, v6, vcc
	v_rsq_f32_e32 v6, v6
	v_mul_f32_e32 v13, 0xbfb8aa3b, v25
	v_exp_f32_e32 v13, v13
	s_waitcnt vmcnt(13)
	v_lshlrev_b32_e32 v16, 16, v12
	v_mul_f32_e32 v7, 0x45800000, v6
	v_cndmask_b32_e32 v6, v6, v7, vcc
	v_mul_f32_e32 v7, 0xbfb8aa3b, v24
	v_exp_f32_e32 v7, v7
	v_add_f32_e32 v13, 1.0, v13
	v_rcp_f32_e32 v15, v13
	v_and_b32_e32 v17, 0xffff0000, v12
	v_add_f32_e32 v7, 1.0, v7
	v_rcp_f32_e32 v14, v7
	v_pk_mul_f32 v[6:7], v[6:7], v[22:23] op_sel_hi:[0,1]
	v_pk_mul_f32 v[6:7], v[2:3], v[6:7]
	v_and_b32_e32 v21, 0xffff0000, v10
	v_pk_mul_f32 v[14:15], v[14:15], v[24:25]
	s_nop 0
	v_pk_mul_f32 v[6:7], v[14:15], v[6:7]
	v_lshlrev_b32_e32 v14, 16, v11
	v_and_b32_e32 v15, 0xffff0000, v11
	v_mul_f32_e32 v11, 0xbfb8aa3b, v16
	v_exp_f32_e32 v11, v11
	v_cvt_pk_bf16_f32 v13, v6, v7
	v_add_co_u32_e32 v6, vcc, s0, v8
	v_add_f32_e32 v11, 1.0, v11
	v_rcp_f32_e32 v18, v11
	v_mul_f32_e32 v11, 0xbfb8aa3b, v17
	v_exp_f32_e32 v11, v11
	v_addc_co_u32_e32 v7, vcc, 0, v9, vcc
	global_store_dword v[6:7], v13, off offset:-4096
	v_add_f32_e32 v11, 1.0, v11
	v_rcp_f32_e32 v19, v11
	v_pk_mul_f32 v[12:13], v[14:15], v[14:15]
	v_pk_mul_f32 v[16:17], v[18:19], v[16:17]
	v_lshlrev_b32_e32 v18, 16, v0
	v_and_b32_e32 v19, 0xffff0000, v0
	v_pk_mul_f32 v[10:11], v[18:19], v[18:19]
	v_mov_b32_e32 v23, v12
	v_mov_b32_e32 v22, v10
	v_mov_b32_e32 v12, v11
	v_pk_add_f32 v[10:11], v[22:23], v[12:13]
	v_mov_b32_e32 v13, v11
	v_mov_b32_e32 v12, v10
	s_nop 0
	v_permlane32_swap_b32_e32 v13, v11
	v_permlane32_swap_b32_e32 v12, v10
	s_waitcnt lgkmcnt(0)
	v_pk_add_f32 v[10:11], v[10:11], v[12:13]
	v_mov_b32_e32 v13, v11
	v_mov_b32_e32 v12, v10
	s_nop 0
	v_permlane16_swap_b32_e32 v13, v11
	v_permlane16_swap_b32_e32 v12, v10
	s_waitcnt lgkmcnt(0)
	v_pk_add_f32 v[10:11], v[10:11], v[12:13]
	s_nop 1
	v_add_f32_dpp v11, v11, v11 row_ror:8 row_mask:0xf bank_mask:0xf
	v_add_f32_dpp v10, v10, v10 row_ror:8 row_mask:0xf bank_mask:0xf
	s_waitcnt lgkmcnt(0)
	s_nop 1
	v_add_f32_dpp v11, v11, v11 row_ror:4 row_mask:0xf bank_mask:0xf
	v_add_f32_dpp v10, v10, v10 row_ror:4 row_mask:0xf bank_mask:0xf
	s_waitcnt lgkmcnt(0)
	s_nop 1
	v_add_f32_dpp v11, v11, v11 quad_perm:[2,3,0,1] row_mask:0xf bank_mask:0xf
	v_add_f32_dpp v10, v10, v10 quad_perm:[2,3,0,1] row_mask:0xf bank_mask:0xf
	s_waitcnt lgkmcnt(0)
	s_nop 1
	v_add_f32_dpp v11, v11, v11 quad_perm:[1,0,3,2] row_mask:0xf bank_mask:0xf
	v_add_f32_dpp v10, v10, v10 quad_perm:[1,0,3,2] row_mask:0xf bank_mask:0xf
	s_waitcnt lgkmcnt(0)
	s_nop 0
	v_pk_fma_f32 v[4:5], v[10:11], s[96:97], v[4:5] op_sel_hi:[1,0,0]
	s_nop 0
	v_mul_f32_e32 v0, 0x4b800000, v5
	v_cmp_gt_f32_e64 s[0:1], s77, v5
	v_cmp_gt_f32_e32 vcc, s77, v4
	s_nop 0
	v_cndmask_b32_e64 v0, v5, v0, s[0:1]
	v_rsq_f32_e32 v0, v0
	s_nop 0
	v_mul_f32_e32 v5, 0x45800000, v0
	v_cndmask_b32_e64 v0, v0, v5, s[0:1]
	v_pk_mul_f32 v[10:11], v[0:1], v[14:15] op_sel_hi:[0,1]
	v_pk_mul_f32 v[10:11], v[2:3], v[10:11]
	s_nop 0
	v_pk_mul_f32 v[10:11], v[16:17], v[10:11]
	s_nop 0
	v_cvt_pk_bf16_f32 v0, v10, v11
	global_store_dword v[6:7], v0, off
	v_mul_f32_e32 v0, 0x4b800000, v4
	v_cndmask_b32_e32 v0, v4, v0, vcc
	v_rsq_f32_e32 v0, v0
	s_nop 0
	v_mul_f32_e32 v4, 0x45800000, v0
	v_cndmask_b32_e32 v0, v0, v4, vcc
	v_mul_f32_e32 v4, 0xbfb8aa3b, v20
	v_pk_mul_f32 v[6:7], v[0:1], v[18:19] op_sel_hi:[0,1]
	v_mul_f32_e32 v0, 0xbfb8aa3b, v21
	v_exp_f32_e32 v4, v4
	v_exp_f32_e32 v0, v0
	v_pk_mul_f32 v[2:3], v[2:3], v[6:7]
	v_add_f32_e32 v4, 1.0, v4
	v_add_f32_e32 v0, 1.0, v0
	v_rcp_f32_e32 v4, v4
	v_rcp_f32_e32 v5, v0
	s_nop 0
	v_pk_mul_f32 v[4:5], v[4:5], v[20:21]
	s_nop 0
	v_pk_mul_f32 v[2:3], v[4:5], v[2:3]
	s_nop 0
	v_cvt_pk_bf16_f32 v0, v2, v3
	v_add_co_u32_e32 v2, vcc, 0xf000, v8
	s_nop 1
	v_addc_co_u32_e32 v3, vcc, 0, v9, vcc
	global_store_dword v[2:3], v0, off

.LBB0_316:
	s_andn2_b64 vcc, exec, s[0:1]
	s_cbranch_vccnz .LBB0_313
	s_lshl_b64 s[0:1], s[4:5], 6
	v_lshl_add_u64 v[38:39], v[8:9], 0, s[0:1]
	v_mov_b64_e32 v[40:41], s[30:31]
	v_mad_u64_u32 v[40:41], s[0:1], v38, s3, v[40:41]
	v_mad_u32_u24 v41, v39, s3, v41
	s_lshl_b32 s0, s34, 1
	s_mov_b32 s1, s5
	v_lshlrev_b64 v[44:45], 12, v[38:39]
	v_lshl_add_u64 v[38:39], v[40:41], 0, s[0:1]
	v_lshlrev_b32_e32 v0, 1, v6
	v_lshl_add_u64 v[100:101], v[38:39], 0, v[0:1]
	v_lshl_add_u64 v[70:71], v[4:5], 0, v[44:45]
	global_load_dword v102, v[100:101], off offset:3072
	global_load_dword v99, v[70:71], off
	v_or_b32_e32 v38, 0x1000, v44
	v_mov_b32_e32 v39, v45
	v_lshl_add_u64 v[68:69], v[4:5], 0, v[38:39]
	global_load_dword v107, v[68:69], off
	s_movk_i32 s0, 0x3000
	v_add_co_u32_e32 v38, vcc, s0, v100
	s_movk_i32 s0, 0x5000
	s_nop 0
	v_addc_co_u32_e32 v39, vcc, 0, v101, vcc
	global_load_dword v109, v[38:39], off offset:896
	v_or_b32_e32 v38, 0x2000, v44
	v_mov_b32_e32 v39, v45
	v_lshl_add_u64 v[66:67], v[4:5], 0, v[38:39]
	v_add_co_u32_e32 v38, vcc, s0, v100
	global_load_dword v97, v[66:67], off
	s_nop 0
	v_addc_co_u32_e32 v39, vcc, 0, v101, vcc
	global_load_dword v98, v[38:39], off offset:2816
	v_or_b32_e32 v38, 0x3000, v44
	v_mov_b32_e32 v39, v45
	s_mov_b32 s0, 0x8000
	v_lshl_add_u64 v[64:65], v[4:5], 0, v[38:39]
	v_add_co_u32_e32 v38, vcc, s0, v100
	global_load_dword v95, v[64:65], off
	s_nop 0
	v_addc_co_u32_e32 v39, vcc, 0, v101, vcc
	global_load_dword v96, v[38:39], off offset:640
	v_or_b32_e32 v38, 0x4000, v44
	v_mov_b32_e32 v39, v45
	s_mov_b32 s0, 0xa000
	v_lshl_add_u64 v[62:63], v[4:5], 0, v[38:39]
	v_add_co_u32_e32 v38, vcc, s0, v100
	global_load_dword v93, v[62:63], off
	s_nop 0
	v_addc_co_u32_e32 v39, vcc, 0, v101, vcc
	global_load_dword v94, v[38:39], off offset:2560
	v_or_b32_e32 v38, 0x5000, v44
	v_mov_b32_e32 v39, v45
	s_mov_b32 s0, 0xd000
	v_lshl_add_u64 v[60:61], v[4:5], 0, v[38:39]
	v_add_co_u32_e32 v38, vcc, s0, v100
	s_mov_b32 s0, 0xf000
	s_nop 0
	v_addc_co_u32_e32 v39, vcc, 0, v101, vcc
	global_load_dword v92, v[38:39], off offset:384
	v_or_b32_e32 v38, 0x6000, v44
	v_mov_b32_e32 v39, v45
	v_lshl_add_u64 v[58:59], v[4:5], 0, v[38:39]
	v_add_co_u32_e32 v38, vcc, s0, v100
	s_mov_b32 s0, 0x12000
	s_nop 0
	v_addc_co_u32_e32 v39, vcc, 0, v101, vcc
	global_load_dword v90, v[38:39], off offset:2304
	v_or_b32_e32 v38, 0x7000, v44
	v_mov_b32_e32 v39, v45
	v_lshl_add_u64 v[56:57], v[4:5], 0, v[38:39]
	v_add_co_u32_e32 v38, vcc, s0, v100
	s_mov_b32 s0, 0x14000
	s_nop 0
	v_addc_co_u32_e32 v39, vcc, 0, v101, vcc
	global_load_dword v88, v[38:39], off offset:128
	v_or_b32_e32 v38, 0x8000, v44
	v_mov_b32_e32 v39, v45
	v_lshl_add_u64 v[54:55], v[4:5], 0, v[38:39]
	v_add_co_u32_e32 v38, vcc, s0, v100
	s_mov_b32 s0, 0x16000
	s_nop 0
	v_addc_co_u32_e32 v39, vcc, 0, v101, vcc
	global_load_dword v86, v[38:39], off offset:2048
	v_or_b32_e32 v38, 0x9000, v44
	v_mov_b32_e32 v39, v45
	v_lshl_add_u64 v[52:53], v[4:5], 0, v[38:39]
	v_add_co_u32_e32 v38, vcc, s0, v100
	s_mov_b32 s0, 0x19000
	s_nop 0
	v_addc_co_u32_e32 v39, vcc, 0, v101, vcc
	global_load_dword v84, v[38:39], off offset:3968
	v_or_b32_e32 v38, 0xa000, v44
	v_mov_b32_e32 v39, v45
	v_lshl_add_u64 v[50:51], v[4:5], 0, v[38:39]
	v_add_co_u32_e32 v38, vcc, s0, v100
	s_mov_b32 s0, 0x1b000
	s_nop 0
	v_addc_co_u32_e32 v39, vcc, 0, v101, vcc
	global_load_dword v82, v[38:39], off offset:1792
	v_or_b32_e32 v38, 0xb000, v44
	v_mov_b32_e32 v39, v45
	v_lshl_add_u64 v[48:49], v[4:5], 0, v[38:39]
	v_add_co_u32_e32 v38, vcc, s0, v100
	s_mov_b32 s0, 0x1e000
	s_nop 0
	v_addc_co_u32_e32 v39, vcc, 0, v101, vcc
	global_load_dword v80, v[38:39], off offset:3712
	v_or_b32_e32 v38, 0xc000, v44
	v_mov_b32_e32 v39, v45
	v_lshl_add_u64 v[46:47], v[4:5], 0, v[38:39]
	v_add_co_u32_e32 v38, vcc, s0, v100
	s_mov_b32 s0, 0x20000
	s_nop 0
	v_addc_co_u32_e32 v39, vcc, 0, v101, vcc
	global_load_dword v78, v[38:39], off offset:1536
	v_or_b32_e32 v38, 0xd000, v44
	v_mov_b32_e32 v39, v45
	v_lshl_add_u64 v[42:43], v[4:5], 0, v[38:39]
	v_add_co_u32_e32 v38, vcc, s0, v100
	s_mov_b32 s0, 0x23000
	s_nop 0
	v_addc_co_u32_e32 v39, vcc, 0, v101, vcc
	global_load_dword v76, v[38:39], off offset:3456
	v_or_b32_e32 v38, 0xe000, v44
	v_mov_b32_e32 v39, v45
	v_lshl_add_u64 v[40:41], v[4:5], 0, v[38:39]
	v_add_co_u32_e32 v38, vcc, s0, v100
	v_or_b32_e32 v44, 0xf000, v44
	s_nop 0
	v_addc_co_u32_e32 v39, vcc, 0, v101, vcc
	s_mov_b32 s0, 0x25000
	global_load_dword v74, v[38:39], off offset:1280
	v_lshl_add_u64 v[38:39], v[4:5], 0, v[44:45]
	v_add_co_u32_e32 v44, vcc, s0, v100
	s_waitcnt vmcnt(18)
	v_lshlrev_b32_e32 v100, 16, v99
	v_addc_co_u32_e32 v45, vcc, 0, v101, vcc
	global_load_dword v72, v[44:45], off offset:3200
	v_lshlrev_b32_e32 v44, 16, v102
	v_and_b32_e32 v101, 0xffff0000, v99
	v_mul_f32_e32 v99, 0xbfb8aa3b, v44
	v_exp_f32_e32 v99, v99
	v_and_b32_e32 v45, 0xffff0000, v102
	s_waitcnt vmcnt(18)
	v_lshlrev_b32_e32 v106, 16, v107
	v_and_b32_e32 v107, 0xffff0000, v107
	v_add_f32_e32 v99, 1.0, v99
	v_rcp_f32_e32 v104, v99
	v_mul_f32_e32 v99, 0xbfb8aa3b, v45
	v_exp_f32_e32 v99, v99
	v_pk_mul_f32 v[102:103], v[100:101], v[100:101]
	s_waitcnt vmcnt(17)
	v_lshlrev_b32_e32 v108, 16, v109
	v_mov_b32_e32 v111, v102
	v_add_f32_e32 v99, 1.0, v99
	v_rcp_f32_e32 v105, v99
	v_and_b32_e32 v109, 0xffff0000, v109
	global_load_dword v91, v[60:61], off
	global_load_dword v89, v[58:59], off
	global_load_dword v87, v[56:57], off
	global_load_dword v85, v[54:55], off
	global_load_dword v83, v[52:53], off
	global_load_dword v81, v[50:51], off
	global_load_dword v79, v[48:49], off
	global_load_dword v77, v[46:47], off
	v_pk_mul_f32 v[104:105], v[104:105], v[44:45]
	v_pk_mul_f32 v[44:45], v[106:107], v[106:107]
	global_load_dword v75, v[42:43], off
	global_load_dword v73, v[40:41], off
	global_load_dword v0, v[38:39], off
	v_mov_b32_e32 v110, v44
	v_mov_b32_e32 v102, v45
	v_pk_add_f32 v[44:45], v[110:111], v[102:103]
	v_mov_b32_e32 v103, v45
	v_mov_b32_e32 v102, v44
	s_nop 0
	v_permlane32_swap_b32_e32 v103, v45
	v_permlane32_swap_b32_e32 v102, v44
	s_waitcnt lgkmcnt(0)
	v_pk_add_f32 v[44:45], v[44:45], v[102:103]
	v_mov_b32_e32 v103, v45
	v_mov_b32_e32 v102, v44
	s_nop 0
	v_permlane16_swap_b32_e32 v103, v45
	v_permlane16_swap_b32_e32 v102, v44
	s_waitcnt lgkmcnt(0)
	v_pk_add_f32 v[44:45], v[44:45], v[102:103]
	s_nop 1
	v_add_f32_dpp v45, v45, v45 row_ror:8 row_mask:0xf bank_mask:0xf
	v_add_f32_dpp v44, v44, v44 row_ror:8 row_mask:0xf bank_mask:0xf
	s_waitcnt lgkmcnt(0)
	s_nop 1
	v_add_f32_dpp v45, v45, v45 row_ror:4 row_mask:0xf bank_mask:0xf
	v_add_f32_dpp v44, v44, v44 row_ror:4 row_mask:0xf bank_mask:0xf
	s_waitcnt lgkmcnt(0)
	s_nop 1
	v_add_f32_dpp v45, v45, v45 quad_perm:[2,3,0,1] row_mask:0xf bank_mask:0xf
	v_add_f32_dpp v44, v44, v44 quad_perm:[2,3,0,1] row_mask:0xf bank_mask:0xf
	s_waitcnt lgkmcnt(0)
	s_nop 1
	v_add_f32_dpp v103, v45, v45 quad_perm:[1,0,3,2] row_mask:0xf bank_mask:0xf
	v_add_f32_dpp v102, v44, v44 quad_perm:[1,0,3,2] row_mask:0xf bank_mask:0xf
	s_waitcnt lgkmcnt(0)
	v_mov_b64_e32 v[44:45], s[72:73]
	v_pk_fma_f32 v[102:103], v[102:103], s[96:97], v[44:45] op_sel_hi:[1,0,0]
	s_nop 0
	v_mul_f32_e32 v99, 0x4b800000, v103
	v_cmp_gt_f32_e64 s[0:1], s77, v103
	v_cmp_gt_f32_e32 vcc, s77, v102
	s_nop 0
	v_cndmask_b32_e64 v99, v103, v99, s[0:1]
	v_rsq_f32_e32 v99, v99
	s_nop 0
	v_mul_f32_e32 v103, 0x45800000, v99
	v_cndmask_b32_e64 v110, v99, v103, s[0:1]
	v_pk_mul_f32 v[100:101], v[110:111], v[100:101] op_sel_hi:[0,1]
	v_pk_mul_f32 v[100:101], v[2:3], v[100:101]
	s_waitcnt vmcnt(24)
	v_and_b32_e32 v103, 0xffff0000, v96
	v_pk_mul_f32 v[100:101], v[104:105], v[100:101]
	s_nop 0
	v_cvt_pk_bf16_f32 v99, v100, v101
	global_store_dword v[70:71], v99, off
	v_mul_f32_e32 v70, 0x4b800000, v102
	v_cndmask_b32_e32 v70, v102, v70, vcc
	v_rsq_f32_e32 v70, v70
	v_mul_f32_e32 v99, 0xbfb8aa3b, v109
	v_exp_f32_e32 v99, v99
	v_lshlrev_b32_e32 v102, 16, v96
	v_mul_f32_e32 v71, 0x45800000, v70
	v_cndmask_b32_e32 v70, v70, v71, vcc
	v_mul_f32_e32 v71, 0xbfb8aa3b, v108
	v_exp_f32_e32 v71, v71
	v_add_f32_e32 v99, 1.0, v99
	v_rcp_f32_e32 v101, v99
	v_add_f32_e32 v71, 1.0, v71
	v_rcp_f32_e32 v100, v71
	v_pk_mul_f32 v[70:71], v[70:71], v[106:107] op_sel_hi:[0,1]
	v_pk_mul_f32 v[70:71], v[2:3], v[70:71]
	v_pk_mul_f32 v[100:101], v[100:101], v[108:109]
	s_nop 0
	v_pk_mul_f32 v[70:71], v[100:101], v[70:71]
	s_nop 0
	v_cvt_pk_bf16_f32 v70, v70, v71
	global_store_dword v[68:69], v70, off
	v_lshlrev_b32_e32 v70, 16, v98
	v_lshlrev_b32_e32 v68, 16, v97
	v_and_b32_e32 v69, 0xffff0000, v97
	v_mul_f32_e32 v97, 0xbfb8aa3b, v70
	v_exp_f32_e32 v97, v97
	v_and_b32_e32 v71, 0xffff0000, v98
	v_pk_mul_f32 v[98:99], v[68:69], v[68:69]
	v_add_f32_e32 v97, 1.0, v97
	v_rcp_f32_e32 v100, v97
	v_mul_f32_e32 v97, 0xbfb8aa3b, v71
	v_exp_f32_e32 v97, v97
	v_mov_b32_e32 v105, v98
	v_add_f32_e32 v97, 1.0, v97
	v_rcp_f32_e32 v101, v97
	s_nop 0
	v_pk_mul_f32 v[70:71], v[100:101], v[70:71]
	v_lshlrev_b32_e32 v100, 16, v95
	v_and_b32_e32 v101, 0xffff0000, v95
	v_pk_mul_f32 v[96:97], v[100:101], v[100:101]
	s_nop 0
	v_mov_b32_e32 v104, v96
	v_mov_b32_e32 v98, v97
	v_pk_add_f32 v[96:97], v[104:105], v[98:99]
	v_mov_b32_e32 v99, v97
	v_mov_b32_e32 v98, v96
	s_nop 0
	v_permlane32_swap_b32_e32 v99, v97
	v_permlane32_swap_b32_e32 v98, v96
	s_waitcnt lgkmcnt(0)
	v_pk_add_f32 v[96:97], v[96:97], v[98:99]
	v_mov_b32_e32 v99, v97
	v_mov_b32_e32 v98, v96
	s_nop 0
	v_permlane16_swap_b32_e32 v99, v97
	v_permlane16_swap_b32_e32 v98, v96
	s_waitcnt lgkmcnt(0)
	v_pk_add_f32 v[96:97], v[96:97], v[98:99]
	s_nop 1
	v_add_f32_dpp v97, v97, v97 row_ror:8 row_mask:0xf bank_mask:0xf
	v_add_f32_dpp v96, v96, v96 row_ror:8 row_mask:0xf bank_mask:0xf
	s_waitcnt lgkmcnt(0)
	s_nop 1
	v_add_f32_dpp v97, v97, v97 row_ror:4 row_mask:0xf bank_mask:0xf
	v_add_f32_dpp v96, v96, v96 row_ror:4 row_mask:0xf bank_mask:0xf
	s_waitcnt lgkmcnt(0)
	s_nop 1
	v_add_f32_dpp v97, v97, v97 quad_perm:[2,3,0,1] row_mask:0xf bank_mask:0xf
	v_add_f32_dpp v96, v96, v96 quad_perm:[2,3,0,1] row_mask:0xf bank_mask:0xf
	s_waitcnt lgkmcnt(0)
	s_nop 1
	v_add_f32_dpp v97, v97, v97 quad_perm:[1,0,3,2] row_mask:0xf bank_mask:0xf
	v_add_f32_dpp v96, v96, v96 quad_perm:[1,0,3,2] row_mask:0xf bank_mask:0xf
	s_waitcnt lgkmcnt(0)
	s_nop 0
	v_pk_fma_f32 v[96:97], v[96:97], s[96:97], v[44:45] op_sel_hi:[1,0,0]
	s_nop 0
	v_mul_f32_e32 v95, 0x4b800000, v97
	v_cmp_gt_f32_e64 s[0:1], s77, v97
	v_cmp_gt_f32_e32 vcc, s77, v96
	s_nop 0
	v_cndmask_b32_e64 v95, v97, v95, s[0:1]
	v_rsq_f32_e32 v95, v95
	s_nop 0
	v_mul_f32_e32 v97, 0x45800000, v95
	v_cndmask_b32_e64 v98, v95, v97, s[0:1]
	v_pk_mul_f32 v[68:69], v[98:99], v[68:69] op_sel_hi:[0,1]
	v_pk_mul_f32 v[68:69], v[2:3], v[68:69]
	s_waitcnt vmcnt(23)
	v_and_b32_e32 v95, 0xffff0000, v92
	v_pk_mul_f32 v[68:69], v[70:71], v[68:69]
	s_nop 0
	v_cvt_pk_bf16_f32 v68, v68, v69
	global_store_dword v[66:67], v68, off
	v_mul_f32_e32 v66, 0x4b800000, v96
	v_cndmask_b32_e32 v66, v96, v66, vcc
	v_rsq_f32_e32 v66, v66
	v_mul_f32_e32 v69, 0xbfb8aa3b, v103
	v_exp_f32_e32 v69, v69
	v_mul_f32_e32 v67, 0x45800000, v66
	v_cndmask_b32_e32 v66, v66, v67, vcc
	v_mul_f32_e32 v67, 0xbfb8aa3b, v102
	v_exp_f32_e32 v67, v67
	v_add_f32_e32 v69, 1.0, v69
	v_rcp_f32_e32 v69, v69
	v_add_f32_e32 v67, 1.0, v67
	v_rcp_f32_e32 v68, v67
	v_pk_mul_f32 v[66:67], v[66:67], v[100:101] op_sel_hi:[0,1]
	v_pk_mul_f32 v[66:67], v[2:3], v[66:67]
	v_pk_mul_f32 v[68:69], v[68:69], v[102:103]
	s_nop 0
	v_pk_mul_f32 v[66:67], v[68:69], v[66:67]
	s_nop 0
	v_cvt_pk_bf16_f32 v66, v66, v67
	global_store_dword v[64:65], v66, off
	v_lshlrev_b32_e32 v66, 16, v94
	v_and_b32_e32 v67, 0xffff0000, v94
	v_mul_f32_e32 v70, 0xbfb8aa3b, v66
	v_mul_f32_e32 v71, 0xbfb8aa3b, v67
	v_exp_f32_e32 v70, v70
	v_exp_f32_e32 v71, v71
	v_lshlrev_b32_e32 v64, 16, v93
	v_and_b32_e32 v65, 0xffff0000, v93
	v_add_f32_e32 v70, 1.0, v70
	v_add_f32_e32 v71, 1.0, v71
	v_rcp_f32_e32 v70, v70
	v_rcp_f32_e32 v71, v71
	v_pk_mul_f32 v[68:69], v[64:65], v[64:65]
	v_lshlrev_b32_e32 v94, 16, v92
	v_mov_b32_e32 v97, v68
	v_pk_mul_f32 v[66:67], v[70:71], v[66:67]
	s_waitcnt vmcnt(14)
	v_lshlrev_b32_e32 v70, 16, v91
	v_and_b32_e32 v71, 0xffff0000, v91
	v_pk_mul_f32 v[92:93], v[70:71], v[70:71]
	s_nop 0
	v_mov_b32_e32 v96, v92
	v_mov_b32_e32 v68, v93
	v_pk_add_f32 v[68:69], v[96:97], v[68:69]
	v_mov_b32_e32 v93, v69
	v_mov_b32_e32 v92, v68
	s_nop 0
	v_permlane32_swap_b32_e32 v93, v69
	v_permlane32_swap_b32_e32 v92, v68
	s_waitcnt lgkmcnt(0)
	v_pk_add_f32 v[68:69], v[68:69], v[92:93]
	v_mov_b32_e32 v93, v69
	v_mov_b32_e32 v92, v68
	s_nop 0
	v_permlane16_swap_b32_e32 v93, v69
	v_permlane16_swap_b32_e32 v92, v68
	s_waitcnt lgkmcnt(0)
	v_pk_add_f32 v[68:69], v[68:69], v[92:93]
	s_nop 1
	v_add_f32_dpp v69, v69, v69 row_ror:8 row_mask:0xf bank_mask:0xf
	v_add_f32_dpp v68, v68, v68 row_ror:8 row_mask:0xf bank_mask:0xf
	s_waitcnt lgkmcnt(0)
	s_nop 1
	v_add_f32_dpp v69, v69, v69 row_ror:4 row_mask:0xf bank_mask:0xf
	v_add_f32_dpp v68, v68, v68 row_ror:4 row_mask:0xf bank_mask:0xf
	s_waitcnt lgkmcnt(0)
	s_nop 1
	v_add_f32_dpp v69, v69, v69 quad_perm:[2,3,0,1] row_mask:0xf bank_mask:0xf
	v_add_f32_dpp v68, v68, v68 quad_perm:[2,3,0,1] row_mask:0xf bank_mask:0xf
	s_waitcnt lgkmcnt(0)
	s_nop 1
	v_add_f32_dpp v69, v69, v69 quad_perm:[1,0,3,2] row_mask:0xf bank_mask:0xf
	v_add_f32_dpp v68, v68, v68 quad_perm:[1,0,3,2] row_mask:0xf bank_mask:0xf
	s_waitcnt lgkmcnt(0)
	s_nop 0
	v_pk_fma_f32 v[68:69], v[68:69], s[96:97], v[44:45] op_sel_hi:[1,0,0]
	s_nop 0
	v_mul_f32_e32 v91, 0x4b800000, v69
	v_cmp_gt_f32_e64 s[0:1], s77, v69
	v_cmp_gt_f32_e32 vcc, s77, v68
	s_nop 0
	v_cndmask_b32_e64 v69, v69, v91, s[0:1]
	v_rsq_f32_e32 v69, v69
	s_nop 0
	v_mul_f32_e32 v91, 0x45800000, v69
	v_cndmask_b32_e64 v92, v69, v91, s[0:1]
	v_pk_mul_f32 v[64:65], v[92:93], v[64:65] op_sel_hi:[0,1]
	v_pk_mul_f32 v[64:65], v[2:3], v[64:65]
	v_and_b32_e32 v69, 0xffff0000, v88
	v_pk_mul_f32 v[64:65], v[66:67], v[64:65]
	s_nop 0
	v_cvt_pk_bf16_f32 v64, v64, v65
	global_store_dword v[62:63], v64, off
	v_mul_f32_e32 v62, 0x4b800000, v68
	v_cndmask_b32_e32 v62, v68, v62, vcc
	v_rsq_f32_e32 v62, v62
	v_mul_f32_e32 v65, 0xbfb8aa3b, v95
	v_exp_f32_e32 v65, v65
	v_lshlrev_b32_e32 v68, 16, v88
	v_mul_f32_e32 v63, 0x45800000, v62
	v_cndmask_b32_e32 v62, v62, v63, vcc
	v_mul_f32_e32 v63, 0xbfb8aa3b, v94
	v_exp_f32_e32 v63, v63
	v_add_f32_e32 v65, 1.0, v65
	v_rcp_f32_e32 v65, v65
	v_add_f32_e32 v63, 1.0, v63
	v_rcp_f32_e32 v64, v63
	v_pk_mul_f32 v[62:63], v[62:63], v[70:71] op_sel_hi:[0,1]
	v_pk_mul_f32 v[62:63], v[2:3], v[62:63]
	v_pk_mul_f32 v[64:65], v[64:65], v[94:95]
	s_nop 0
	v_pk_mul_f32 v[62:63], v[64:65], v[62:63]
	s_nop 0
	v_cvt_pk_bf16_f32 v62, v62, v63
	global_store_dword v[60:61], v62, off
	v_lshlrev_b32_e32 v62, 16, v90
	v_and_b32_e32 v63, 0xffff0000, v90
	v_mul_f32_e32 v66, 0xbfb8aa3b, v62
	v_mul_f32_e32 v67, 0xbfb8aa3b, v63
	v_exp_f32_e32 v66, v66
	v_exp_f32_e32 v67, v67
	s_waitcnt vmcnt(15)
	v_lshlrev_b32_e32 v60, 16, v89
	v_and_b32_e32 v61, 0xffff0000, v89
	v_add_f32_e32 v66, 1.0, v66
	v_add_f32_e32 v67, 1.0, v67
	v_rcp_f32_e32 v66, v66
	v_rcp_f32_e32 v67, v67
	v_pk_mul_f32 v[64:65], v[60:61], v[60:61]
	v_pk_mul_f32 v[62:63], v[66:67], v[62:63]
	s_waitcnt vmcnt(14)
	v_lshlrev_b32_e32 v66, 16, v87
	v_and_b32_e32 v67, 0xffff0000, v87
	v_pk_mul_f32 v[70:71], v[66:67], v[66:67]
	v_mov_b32_e32 v89, v64
	v_mov_b32_e32 v88, v70
	v_mov_b32_e32 v64, v71
	v_pk_add_f32 v[64:65], v[88:89], v[64:65]
	v_mov_b32_e32 v71, v65
	v_mov_b32_e32 v70, v64
	s_nop 0
	v_permlane32_swap_b32_e32 v71, v65
	v_permlane32_swap_b32_e32 v70, v64
	s_waitcnt lgkmcnt(0)
	v_pk_add_f32 v[64:65], v[64:65], v[70:71]
	v_mov_b32_e32 v71, v65
	v_mov_b32_e32 v70, v64
	s_nop 0
	v_permlane16_swap_b32_e32 v71, v65
	v_permlane16_swap_b32_e32 v70, v64
	s_waitcnt lgkmcnt(0)
	v_pk_add_f32 v[64:65], v[64:65], v[70:71]
	s_nop 1
	v_add_f32_dpp v65, v65, v65 row_ror:8 row_mask:0xf bank_mask:0xf
	v_add_f32_dpp v64, v64, v64 row_ror:8 row_mask:0xf bank_mask:0xf
	s_waitcnt lgkmcnt(0)
	s_nop 1
	v_add_f32_dpp v65, v65, v65 row_ror:4 row_mask:0xf bank_mask:0xf
	v_add_f32_dpp v64, v64, v64 row_ror:4 row_mask:0xf bank_mask:0xf
	s_waitcnt lgkmcnt(0)
	s_nop 1
	v_add_f32_dpp v65, v65, v65 quad_perm:[2,3,0,1] row_mask:0xf bank_mask:0xf
	v_add_f32_dpp v64, v64, v64 quad_perm:[2,3,0,1] row_mask:0xf bank_mask:0xf
	s_waitcnt lgkmcnt(0)
	s_nop 1
	v_add_f32_dpp v65, v65, v65 quad_perm:[1,0,3,2] row_mask:0xf bank_mask:0xf
	v_add_f32_dpp v64, v64, v64 quad_perm:[1,0,3,2] row_mask:0xf bank_mask:0xf
	s_waitcnt lgkmcnt(0)
	s_nop 0
	v_pk_fma_f32 v[64:65], v[64:65], s[96:97], v[44:45] op_sel_hi:[1,0,0]
	s_nop 0
	v_mul_f32_e32 v70, 0x4b800000, v65
	v_cmp_gt_f32_e64 s[0:1], s77, v65
	v_cmp_gt_f32_e32 vcc, s77, v64
	s_nop 0
	v_cndmask_b32_e64 v65, v65, v70, s[0:1]
	v_rsq_f32_e32 v65, v65
	s_nop 0
	v_mul_f32_e32 v70, 0x45800000, v65
	v_cndmask_b32_e64 v70, v65, v70, s[0:1]
	v_pk_mul_f32 v[60:61], v[70:71], v[60:61] op_sel_hi:[0,1]
	v_pk_mul_f32 v[60:61], v[2:3], v[60:61]
	v_and_b32_e32 v65, 0xffff0000, v84
	v_pk_mul_f32 v[60:61], v[62:63], v[60:61]
	s_nop 0
	v_cvt_pk_bf16_f32 v60, v60, v61
	global_store_dword v[58:59], v60, off
	v_mul_f32_e32 v58, 0x4b800000, v64
	v_cndmask_b32_e32 v58, v64, v58, vcc
	v_rsq_f32_e32 v58, v58
	v_mul_f32_e32 v61, 0xbfb8aa3b, v69
	v_exp_f32_e32 v61, v61
	v_lshlrev_b32_e32 v64, 16, v84
	v_mul_f32_e32 v59, 0x45800000, v58
	v_cndmask_b32_e32 v58, v58, v59, vcc
	v_mul_f32_e32 v59, 0xbfb8aa3b, v68
	v_exp_f32_e32 v59, v59
	v_add_f32_e32 v61, 1.0, v61
	v_rcp_f32_e32 v61, v61
	v_add_f32_e32 v59, 1.0, v59
	v_rcp_f32_e32 v60, v59
	v_pk_mul_f32 v[58:59], v[58:59], v[66:67] op_sel_hi:[0,1]
	v_pk_mul_f32 v[58:59], v[2:3], v[58:59]
	v_pk_mul_f32 v[60:61], v[60:61], v[68:69]
	s_nop 0
	v_pk_mul_f32 v[58:59], v[60:61], v[58:59]
	s_nop 0
	v_cvt_pk_bf16_f32 v58, v58, v59
	global_store_dword v[56:57], v58, off
	v_lshlrev_b32_e32 v58, 16, v86
	v_and_b32_e32 v59, 0xffff0000, v86
	v_mul_f32_e32 v62, 0xbfb8aa3b, v58
	v_mul_f32_e32 v63, 0xbfb8aa3b, v59
	v_exp_f32_e32 v62, v62
	v_exp_f32_e32 v63, v63
	s_waitcnt vmcnt(15)
	v_lshlrev_b32_e32 v56, 16, v85
	v_and_b32_e32 v57, 0xffff0000, v85
	v_add_f32_e32 v62, 1.0, v62
	v_add_f32_e32 v63, 1.0, v63
	v_rcp_f32_e32 v62, v62
	v_rcp_f32_e32 v63, v63
	v_pk_mul_f32 v[60:61], v[56:57], v[56:57]
	v_pk_mul_f32 v[58:59], v[62:63], v[58:59]
	s_waitcnt vmcnt(14)
	v_lshlrev_b32_e32 v62, 16, v83
	v_and_b32_e32 v63, 0xffff0000, v83
	v_pk_mul_f32 v[66:67], v[62:63], v[62:63]
	v_mov_b32_e32 v69, v60
	v_mov_b32_e32 v68, v66
	v_mov_b32_e32 v60, v67
	v_pk_add_f32 v[60:61], v[68:69], v[60:61]
	v_mov_b32_e32 v67, v61
	v_mov_b32_e32 v66, v60
	s_nop 0
	v_permlane32_swap_b32_e32 v67, v61
	v_permlane32_swap_b32_e32 v66, v60
	s_waitcnt lgkmcnt(0)
	v_pk_add_f32 v[60:61], v[60:61], v[66:67]
	v_mov_b32_e32 v67, v61
	v_mov_b32_e32 v66, v60
	s_nop 0
	v_permlane16_swap_b32_e32 v67, v61
	v_permlane16_swap_b32_e32 v66, v60
	s_waitcnt lgkmcnt(0)
	v_pk_add_f32 v[60:61], v[60:61], v[66:67]
	s_nop 1
	v_add_f32_dpp v61, v61, v61 row_ror:8 row_mask:0xf bank_mask:0xf
	v_add_f32_dpp v60, v60, v60 row_ror:8 row_mask:0xf bank_mask:0xf
	s_waitcnt lgkmcnt(0)
	s_nop 1
	v_add_f32_dpp v61, v61, v61 row_ror:4 row_mask:0xf bank_mask:0xf
	v_add_f32_dpp v60, v60, v60 row_ror:4 row_mask:0xf bank_mask:0xf
	s_waitcnt lgkmcnt(0)
	s_nop 1
	v_add_f32_dpp v61, v61, v61 quad_perm:[2,3,0,1] row_mask:0xf bank_mask:0xf
	v_add_f32_dpp v60, v60, v60 quad_perm:[2,3,0,1] row_mask:0xf bank_mask:0xf
	s_waitcnt lgkmcnt(0)
	s_nop 1
	v_add_f32_dpp v61, v61, v61 quad_perm:[1,0,3,2] row_mask:0xf bank_mask:0xf
	v_add_f32_dpp v60, v60, v60 quad_perm:[1,0,3,2] row_mask:0xf bank_mask:0xf
	s_waitcnt lgkmcnt(0)
	s_nop 0
	v_pk_fma_f32 v[60:61], v[60:61], s[96:97], v[44:45] op_sel_hi:[1,0,0]
	s_nop 0
	v_mul_f32_e32 v66, 0x4b800000, v61
	v_cmp_gt_f32_e64 s[0:1], s77, v61
	v_cmp_gt_f32_e32 vcc, s77, v60
	s_nop 0
	v_cndmask_b32_e64 v61, v61, v66, s[0:1]
	v_rsq_f32_e32 v61, v61
	s_nop 0
	v_mul_f32_e32 v66, 0x45800000, v61
	v_cndmask_b32_e64 v66, v61, v66, s[0:1]
	v_pk_mul_f32 v[56:57], v[66:67], v[56:57] op_sel_hi:[0,1]
	v_pk_mul_f32 v[56:57], v[2:3], v[56:57]
	v_and_b32_e32 v61, 0xffff0000, v80
	v_pk_mul_f32 v[56:57], v[58:59], v[56:57]
	s_nop 0
	v_cvt_pk_bf16_f32 v56, v56, v57
	global_store_dword v[54:55], v56, off
	v_mul_f32_e32 v54, 0x4b800000, v60
	v_cndmask_b32_e32 v54, v60, v54, vcc
	v_rsq_f32_e32 v54, v54
	v_mul_f32_e32 v57, 0xbfb8aa3b, v65
	v_exp_f32_e32 v57, v57
	v_lshlrev_b32_e32 v60, 16, v80
	v_mul_f32_e32 v55, 0x45800000, v54
	v_cndmask_b32_e32 v54, v54, v55, vcc
	v_mul_f32_e32 v55, 0xbfb8aa3b, v64
	v_exp_f32_e32 v55, v55
	v_add_f32_e32 v57, 1.0, v57
	v_rcp_f32_e32 v57, v57
	v_add_f32_e32 v55, 1.0, v55
	v_rcp_f32_e32 v56, v55
	v_pk_mul_f32 v[54:55], v[54:55], v[62:63] op_sel_hi:[0,1]
	v_pk_mul_f32 v[54:55], v[2:3], v[54:55]
	v_pk_mul_f32 v[56:57], v[56:57], v[64:65]
	s_nop 0
	v_pk_mul_f32 v[54:55], v[56:57], v[54:55]
	s_nop 0
	v_cvt_pk_bf16_f32 v54, v54, v55
	global_store_dword v[52:53], v54, off
	v_lshlrev_b32_e32 v54, 16, v82
	v_and_b32_e32 v55, 0xffff0000, v82
	v_mul_f32_e32 v58, 0xbfb8aa3b, v54
	v_mul_f32_e32 v59, 0xbfb8aa3b, v55
	v_exp_f32_e32 v58, v58
	v_exp_f32_e32 v59, v59
	s_waitcnt vmcnt(15)
	v_lshlrev_b32_e32 v52, 16, v81
	v_and_b32_e32 v53, 0xffff0000, v81
	v_add_f32_e32 v58, 1.0, v58
	v_add_f32_e32 v59, 1.0, v59
	v_rcp_f32_e32 v58, v58
	v_rcp_f32_e32 v59, v59
	v_pk_mul_f32 v[56:57], v[52:53], v[52:53]
	v_pk_mul_f32 v[54:55], v[58:59], v[54:55]
	s_waitcnt vmcnt(14)
	v_lshlrev_b32_e32 v58, 16, v79
	v_and_b32_e32 v59, 0xffff0000, v79
	v_pk_mul_f32 v[62:63], v[58:59], v[58:59]
	v_mov_b32_e32 v65, v56
	v_mov_b32_e32 v64, v62
	v_mov_b32_e32 v56, v63
	v_pk_add_f32 v[56:57], v[64:65], v[56:57]
	v_mov_b32_e32 v63, v57
	v_mov_b32_e32 v62, v56
	s_nop 0
	v_permlane32_swap_b32_e32 v63, v57
	v_permlane32_swap_b32_e32 v62, v56
	s_waitcnt lgkmcnt(0)
	v_pk_add_f32 v[56:57], v[56:57], v[62:63]
	v_mov_b32_e32 v63, v57
	v_mov_b32_e32 v62, v56
	s_nop 0
	v_permlane16_swap_b32_e32 v63, v57
	v_permlane16_swap_b32_e32 v62, v56
	s_waitcnt lgkmcnt(0)
	v_pk_add_f32 v[56:57], v[56:57], v[62:63]
	s_nop 1
	v_add_f32_dpp v57, v57, v57 row_ror:8 row_mask:0xf bank_mask:0xf
	v_add_f32_dpp v56, v56, v56 row_ror:8 row_mask:0xf bank_mask:0xf
	s_waitcnt lgkmcnt(0)
	s_nop 1
	v_add_f32_dpp v57, v57, v57 row_ror:4 row_mask:0xf bank_mask:0xf
	v_add_f32_dpp v56, v56, v56 row_ror:4 row_mask:0xf bank_mask:0xf
	s_waitcnt lgkmcnt(0)
	s_nop 1
	v_add_f32_dpp v57, v57, v57 quad_perm:[2,3,0,1] row_mask:0xf bank_mask:0xf
	v_add_f32_dpp v56, v56, v56 quad_perm:[2,3,0,1] row_mask:0xf bank_mask:0xf
	s_waitcnt lgkmcnt(0)
	s_nop 1
	v_add_f32_dpp v57, v57, v57 quad_perm:[1,0,3,2] row_mask:0xf bank_mask:0xf
	v_add_f32_dpp v56, v56, v56 quad_perm:[1,0,3,2] row_mask:0xf bank_mask:0xf
	s_waitcnt lgkmcnt(0)
	s_nop 0
	v_pk_fma_f32 v[56:57], v[56:57], s[96:97], v[44:45] op_sel_hi:[1,0,0]
	s_nop 0
	v_mul_f32_e32 v62, 0x4b800000, v57
	v_cmp_gt_f32_e64 s[0:1], s77, v57
	v_cmp_gt_f32_e32 vcc, s77, v56
	s_nop 0
	v_cndmask_b32_e64 v57, v57, v62, s[0:1]
	v_rsq_f32_e32 v57, v57
	s_nop 0
	v_mul_f32_e32 v62, 0x45800000, v57
	v_cndmask_b32_e64 v62, v57, v62, s[0:1]
	v_pk_mul_f32 v[52:53], v[62:63], v[52:53] op_sel_hi:[0,1]
	v_pk_mul_f32 v[52:53], v[2:3], v[52:53]
	v_and_b32_e32 v57, 0xffff0000, v76
	v_pk_mul_f32 v[52:53], v[54:55], v[52:53]
	s_nop 0
	v_cvt_pk_bf16_f32 v52, v52, v53
	global_store_dword v[50:51], v52, off
	v_mul_f32_e32 v50, 0x4b800000, v56
	v_cndmask_b32_e32 v50, v56, v50, vcc
	v_rsq_f32_e32 v50, v50
	v_mul_f32_e32 v53, 0xbfb8aa3b, v61
	v_exp_f32_e32 v53, v53
	v_lshlrev_b32_e32 v56, 16, v76
	v_mul_f32_e32 v51, 0x45800000, v50
	v_cndmask_b32_e32 v50, v50, v51, vcc
	v_mul_f32_e32 v51, 0xbfb8aa3b, v60
	v_exp_f32_e32 v51, v51
	v_add_f32_e32 v53, 1.0, v53
	v_rcp_f32_e32 v53, v53
	v_add_f32_e32 v51, 1.0, v51
	v_rcp_f32_e32 v52, v51
	v_pk_mul_f32 v[50:51], v[50:51], v[58:59] op_sel_hi:[0,1]
	v_pk_mul_f32 v[50:51], v[2:3], v[50:51]
	v_pk_mul_f32 v[52:53], v[52:53], v[60:61]
	s_nop 0
	v_pk_mul_f32 v[50:51], v[52:53], v[50:51]
	s_nop 0
	v_cvt_pk_bf16_f32 v50, v50, v51
	global_store_dword v[48:49], v50, off
	v_lshlrev_b32_e32 v50, 16, v78
	v_and_b32_e32 v51, 0xffff0000, v78
	v_mul_f32_e32 v54, 0xbfb8aa3b, v50
	v_mul_f32_e32 v55, 0xbfb8aa3b, v51
	v_exp_f32_e32 v54, v54
	v_exp_f32_e32 v55, v55
	s_waitcnt vmcnt(15)
	v_lshlrev_b32_e32 v48, 16, v77
	v_and_b32_e32 v49, 0xffff0000, v77
	v_add_f32_e32 v54, 1.0, v54
	v_add_f32_e32 v55, 1.0, v55
	v_rcp_f32_e32 v54, v54
	v_rcp_f32_e32 v55, v55
	v_pk_mul_f32 v[52:53], v[48:49], v[48:49]
	v_pk_mul_f32 v[50:51], v[54:55], v[50:51]
	s_waitcnt vmcnt(14)
	v_lshlrev_b32_e32 v54, 16, v75
	v_and_b32_e32 v55, 0xffff0000, v75
	v_pk_mul_f32 v[58:59], v[54:55], v[54:55]
	v_mov_b32_e32 v61, v52
	v_mov_b32_e32 v60, v58
	v_mov_b32_e32 v52, v59
	v_pk_add_f32 v[52:53], v[60:61], v[52:53]
	v_mov_b32_e32 v59, v53
	v_mov_b32_e32 v58, v52
	s_nop 0
	v_permlane32_swap_b32_e32 v59, v53
	v_permlane32_swap_b32_e32 v58, v52
	s_waitcnt lgkmcnt(0)
	v_pk_add_f32 v[52:53], v[52:53], v[58:59]
	v_mov_b32_e32 v59, v53
	v_mov_b32_e32 v58, v52
	s_nop 0
	v_permlane16_swap_b32_e32 v59, v53
	v_permlane16_swap_b32_e32 v58, v52
	s_waitcnt lgkmcnt(0)
	v_pk_add_f32 v[52:53], v[52:53], v[58:59]
	s_nop 1
	v_add_f32_dpp v53, v53, v53 row_ror:8 row_mask:0xf bank_mask:0xf
	v_add_f32_dpp v52, v52, v52 row_ror:8 row_mask:0xf bank_mask:0xf
	s_waitcnt lgkmcnt(0)
	s_nop 1
	v_add_f32_dpp v53, v53, v53 row_ror:4 row_mask:0xf bank_mask:0xf
	v_add_f32_dpp v52, v52, v52 row_ror:4 row_mask:0xf bank_mask:0xf
	s_waitcnt lgkmcnt(0)
	s_nop 1
	v_add_f32_dpp v53, v53, v53 quad_perm:[2,3,0,1] row_mask:0xf bank_mask:0xf
	v_add_f32_dpp v52, v52, v52 quad_perm:[2,3,0,1] row_mask:0xf bank_mask:0xf
	s_waitcnt lgkmcnt(0)
	s_nop 1
	v_add_f32_dpp v53, v53, v53 quad_perm:[1,0,3,2] row_mask:0xf bank_mask:0xf
	v_add_f32_dpp v52, v52, v52 quad_perm:[1,0,3,2] row_mask:0xf bank_mask:0xf
	s_waitcnt lgkmcnt(0)
	s_nop 0
	v_pk_fma_f32 v[52:53], v[52:53], s[96:97], v[44:45] op_sel_hi:[1,0,0]
	s_nop 0
	v_mul_f32_e32 v58, 0x4b800000, v53
	v_cmp_gt_f32_e64 s[0:1], s77, v53
	v_cmp_gt_f32_e32 vcc, s77, v52
	s_nop 0
	v_cndmask_b32_e64 v53, v53, v58, s[0:1]
	v_rsq_f32_e32 v53, v53
	s_nop 0
	v_mul_f32_e32 v58, 0x45800000, v53
	v_cndmask_b32_e64 v58, v53, v58, s[0:1]
	v_pk_mul_f32 v[48:49], v[58:59], v[48:49] op_sel_hi:[0,1]
	v_pk_mul_f32 v[48:49], v[2:3], v[48:49]
	v_and_b32_e32 v53, 0xffff0000, v72
	v_pk_mul_f32 v[48:49], v[50:51], v[48:49]
	s_nop 0
	v_cvt_pk_bf16_f32 v48, v48, v49
	global_store_dword v[46:47], v48, off
	v_mul_f32_e32 v46, 0x4b800000, v52
	v_cndmask_b32_e32 v46, v52, v46, vcc
	v_rsq_f32_e32 v46, v46
	v_mul_f32_e32 v49, 0xbfb8aa3b, v57
	v_exp_f32_e32 v49, v49
	v_lshlrev_b32_e32 v52, 16, v72
	v_mul_f32_e32 v47, 0x45800000, v46
	v_cndmask_b32_e32 v46, v46, v47, vcc
	v_mul_f32_e32 v47, 0xbfb8aa3b, v56
	v_exp_f32_e32 v47, v47
	v_add_f32_e32 v49, 1.0, v49
	v_rcp_f32_e32 v49, v49
	v_add_f32_e32 v47, 1.0, v47
	v_rcp_f32_e32 v48, v47
	v_pk_mul_f32 v[46:47], v[46:47], v[54:55] op_sel_hi:[0,1]
	v_pk_mul_f32 v[46:47], v[2:3], v[46:47]
	v_pk_mul_f32 v[48:49], v[48:49], v[56:57]
	s_nop 0
	v_pk_mul_f32 v[46:47], v[48:49], v[46:47]
	s_nop 0
	v_cvt_pk_bf16_f32 v46, v46, v47
	global_store_dword v[42:43], v46, off
	v_lshlrev_b32_e32 v46, 16, v74
	v_and_b32_e32 v47, 0xffff0000, v74
	v_mul_f32_e32 v50, 0xbfb8aa3b, v46
	v_mul_f32_e32 v51, 0xbfb8aa3b, v47
	v_exp_f32_e32 v50, v50
	v_exp_f32_e32 v51, v51
	s_waitcnt vmcnt(15)
	v_lshlrev_b32_e32 v42, 16, v73
	v_and_b32_e32 v43, 0xffff0000, v73
	v_add_f32_e32 v50, 1.0, v50
	v_add_f32_e32 v51, 1.0, v51
	v_rcp_f32_e32 v50, v50
	v_rcp_f32_e32 v51, v51
	v_pk_mul_f32 v[48:49], v[42:43], v[42:43]
	v_pk_mul_f32 v[46:47], v[50:51], v[46:47]
	s_waitcnt vmcnt(14)
	v_lshlrev_b32_e32 v50, 16, v0
	v_and_b32_e32 v51, 0xffff0000, v0
	v_pk_mul_f32 v[54:55], v[50:51], v[50:51]
	v_mov_b32_e32 v57, v48
	v_mov_b32_e32 v56, v54
	v_mov_b32_e32 v48, v55
	v_pk_add_f32 v[48:49], v[56:57], v[48:49]
	v_mov_b32_e32 v55, v49
	v_mov_b32_e32 v54, v48
	s_nop 0
	v_permlane32_swap_b32_e32 v55, v49
	v_permlane32_swap_b32_e32 v54, v48
	s_waitcnt lgkmcnt(0)
	v_pk_add_f32 v[48:49], v[48:49], v[54:55]
	v_mov_b32_e32 v55, v49
	v_mov_b32_e32 v54, v48
	s_nop 0
	v_permlane16_swap_b32_e32 v55, v49
	v_permlane16_swap_b32_e32 v54, v48
	s_waitcnt lgkmcnt(0)
	v_pk_add_f32 v[48:49], v[48:49], v[54:55]
	s_nop 1
	v_add_f32_dpp v49, v49, v49 row_ror:8 row_mask:0xf bank_mask:0xf
	v_add_f32_dpp v48, v48, v48 row_ror:8 row_mask:0xf bank_mask:0xf
	s_waitcnt lgkmcnt(0)
	s_nop 1
	v_add_f32_dpp v49, v49, v49 row_ror:4 row_mask:0xf bank_mask:0xf
	v_add_f32_dpp v48, v48, v48 row_ror:4 row_mask:0xf bank_mask:0xf
	s_waitcnt lgkmcnt(0)
	s_nop 1
	v_add_f32_dpp v49, v49, v49 quad_perm:[2,3,0,1] row_mask:0xf bank_mask:0xf
	v_add_f32_dpp v48, v48, v48 quad_perm:[2,3,0,1] row_mask:0xf bank_mask:0xf
	s_waitcnt lgkmcnt(0)
	s_nop 1
	v_add_f32_dpp v49, v49, v49 quad_perm:[1,0,3,2] row_mask:0xf bank_mask:0xf
	v_add_f32_dpp v48, v48, v48 quad_perm:[1,0,3,2] row_mask:0xf bank_mask:0xf
	s_waitcnt lgkmcnt(0)
	s_nop 0
	v_pk_fma_f32 v[44:45], v[48:49], s[96:97], v[44:45] op_sel_hi:[1,0,0]
	s_nop 0
	v_mul_f32_e32 v0, 0x4b800000, v45
	v_cmp_gt_f32_e64 s[0:1], s77, v45
	v_cmp_gt_f32_e32 vcc, s77, v44
	s_nop 0
	v_cndmask_b32_e64 v0, v45, v0, s[0:1]
	v_rsq_f32_e32 v0, v0
	s_nop 0
	v_mul_f32_e32 v45, 0x45800000, v0
	v_cndmask_b32_e64 v0, v0, v45, s[0:1]
	v_pk_mul_f32 v[42:43], v[0:1], v[42:43] op_sel_hi:[0,1]
	v_pk_mul_f32 v[42:43], v[2:3], v[42:43]
	s_nop 0
	v_pk_mul_f32 v[42:43], v[46:47], v[42:43]
	s_nop 0
	v_cvt_pk_bf16_f32 v0, v42, v43
	global_store_dword v[40:41], v0, off
	v_mul_f32_e32 v0, 0x4b800000, v44
	v_cndmask_b32_e32 v0, v44, v0, vcc
	v_rsq_f32_e32 v0, v0
	s_nop 0
	v_mul_f32_e32 v40, 0x45800000, v0
	v_cndmask_b32_e32 v0, v0, v40, vcc
	v_mul_f32_e32 v40, 0xbfb8aa3b, v52
	v_pk_mul_f32 v[42:43], v[0:1], v[50:51] op_sel_hi:[0,1]
	v_mul_f32_e32 v0, 0xbfb8aa3b, v53
	v_exp_f32_e32 v40, v40
	v_exp_f32_e32 v0, v0
	v_pk_mul_f32 v[42:43], v[2:3], v[42:43]
	v_add_f32_e32 v40, 1.0, v40
	v_add_f32_e32 v0, 1.0, v0
	v_rcp_f32_e32 v40, v40
	v_rcp_f32_e32 v41, v0
	s_nop 0
	v_pk_mul_f32 v[40:41], v[40:41], v[52:53]
	s_nop 0
	v_pk_mul_f32 v[40:41], v[40:41], v[42:43]
	s_nop 0
	v_cvt_pk_bf16_f32 v0, v40, v41
	global_store_dword v[38:39], v0, off
	s_branch .LBB0_313

; DI bf16_t f2bf(float f) { unsigned u = __float_as_uint(f); u += 0x7fffu + ((u >> 16) & 1u); return (bf16_t)(u >> 16); }
; DI float wave_sum(float v) { for (int o = 32; o; o >>= 1) v += __shfl_xor(v, o); return v; }
; DI void run_phase(const Params& p, int ph, unsigned char* smem, const int tid, const int rep) {
;     ...
;             for (int u = 0; u < 2; ++u) { const int t = t0 + u;
;                 const float ang = (float)ps[u] * invf; float sn, cs; sincosf(ang, &sn, &cs);
;                 const float kr = krv[u];
; #pragma unroll
;                 for (int h = 0; h < 4; ++h) {
;                     { const float a0 = qa[u][h][0], a1 = qa[u][h][1], a2 = qa[u][h][2];
;                       const float rs = rsqrtf(wave_sum(a0 * a0 + a1 * a1 + a2 * a2) * (1.f / 192.f) + NEPS) * (0.07216878364870322f * LOG2E);
;                       const float y2 = a2 * rs * gq2; const float oth = __shfl_xor(y2, 32);
;                       const float rot = (lane < 32) ? (y2 * cs - oth * sn) : (y2 * cs + oth * sn);
;                       bf16_t* qo = mlaq + (size_t)t * 768 + h * 192; qo[lane] = f2bf(a0 * rs * gq0); qo[lane + 64] = f2bf(a1 * rs * gq1); qo[lane + 128] = f2bf(rot); }
;                     { const float a0 = ka[u][h][0], a1 = ka[u][h][1];
;                       const float rs = rsqrtf(wave_sum(a0 * a0 + a1 * a1 + kr * kr) * (1.f / 192.f) + NEPS);
;                       const float y2 = kr * rs * gk2; const float oth = __shfl_xor(y2, 32);
;                       const float rot = (lane < 32) ? (y2 * cs - oth * sn) : (y2 * cs + oth * sn);
;                       bf16_t* ko = mlak + (size_t)t * 768 + h * 192; ko[lane] = f2bf(a0 * rs * gk0); ko[lane + 64] = f2bf(a1 * rs * gk1); ko[lane + 128] = f2bf(rot); }
.LBB0_331:
	s_or_b64 exec, exec, s[0:1]
	v_mul_f32_e32 v26, v24, v24
	v_fmamk_f32 v27, v26, 0xb94c1982, v249
	v_fmaak_f32 v27, v26, v27, 0xbe2aaa9d
	v_mul_f32_e32 v27, v26, v27
	v_fmac_f32_e32 v24, v24, v27
	v_fmamk_f32 v27, v26, 0x37d75334, v223
	v_fmaak_f32 v27, v26, v27, 0x3d2aabf7
	v_fmaak_f32 v27, v26, v27, 0xbf000004
	v_fma_f32 v26, v26, v27, 1.0
	v_lshlrev_b32_e32 v27, 30, v25
	v_and_b32_e32 v25, 1, v25
	v_cmp_eq_u32_e32 vcc, 0, v25
	s_brev_b32 s0, 1
	s_waitcnt vmcnt(41)
	v_lshlrev_b32_e32 v19, 16, v58
	v_cndmask_b32_e32 v25, v26, v24, vcc
	v_xor_b32_e32 v24, 0x80000000, v24
	v_cndmask_b32_e32 v24, v24, v26, vcc
	v_lshlrev_b32_e32 v18, 16, v51
	s_waitcnt vmcnt(39)
	v_lshlrev_b32_e32 v33, 16, v53
	v_lshlrev_b32_e32 v32, 16, v50
	v_xor_b32_e32 v17, v17, v16
	v_bitop3_b32 v24, v24, v27, s0 bitop3:0x78
	s_movk_i32 s0, 0x1f8
	v_lshlrev_b32_e32 v70, 16, v57
	s_waitcnt vmcnt(38)
	v_lshlrev_b32_e32 v30, 16, v55
	s_waitcnt vmcnt(35)
	v_lshlrev_b32_e32 v28, 16, v54
	s_waitcnt vmcnt(25)
	v_lshlrev_b32_e32 v13, 16, v61
	v_lshlrev_b32_e32 v12, 16, v49
	v_and_b32_e32 v34, 0x80000000, v27
	v_xor_b32_e32 v17, v17, v25
	v_cmp_class_f32_e64 vcc, v16, s0
	v_pk_mul_f32 v[26:27], v[18:19], v[18:19]
	v_pk_mul_f32 v[54:55], v[32:33], v[32:33]
	v_lshlrev_b32_e32 v11, 16, v52
	s_waitcnt vmcnt(24)
	v_lshlrev_b32_e32 v10, 16, v56
	v_xor_b32_e32 v17, v17, v34
	v_cndmask_b32_e32 v34, v224, v24, vcc
	v_pk_mul_f32 v[24:25], v[12:13], v[12:13]
	v_mul_f32_e32 v53, v70, v70
	v_mov_b32_e32 v56, v54
	v_mov_b32_e32 v57, v26
	v_mov_b32_e32 v52, v55
	v_pk_add_f32 v[52:53], v[56:57], v[52:53]
	v_mov_b32_e32 v26, v24
	v_pk_add_f32 v[26:27], v[26:27], v[52:53]
	v_mov_b32_e32 v53, v27
	v_mov_b32_e32 v52, v26
	s_nop 0
	v_permlane32_swap_b32_e32 v53, v27
	v_permlane32_swap_b32_e32 v52, v26
	s_mov_b32 s4, 0x3baaaaab
	v_cndmask_b32_e32 v35, v224, v17, vcc
	v_mad_i64_i32 v[16:17], s[0:1], v3, s7, v[6:7]
	s_waitcnt lgkmcnt(0)
	v_pk_add_f32 v[26:27], v[26:27], v[52:53]
	v_mov_b32_e32 v53, v27
	v_mov_b32_e32 v52, v26
	s_nop 0
	v_permlane16_swap_b32_e32 v53, v27
	v_permlane16_swap_b32_e32 v52, v26
	v_lshlrev_b32_e32 v31, 16, v63
	v_lshlrev_b32_e32 v29, 16, v59
	v_lshlrev_b32_e32 v51, 16, v62
	v_pk_mul_f32 v[54:55], v[28:29], v[28:29]
	s_waitcnt lgkmcnt(0)
	v_pk_add_f32 v[26:27], v[26:27], v[52:53]
	s_nop 1
	v_mov_b32_dpp v53, v27 row_ror:8 row_mask:0xf bank_mask:0xf
	v_mov_b32_dpp v52, v26 row_ror:8 row_mask:0xf bank_mask:0xf
	v_mov_b32_e32 v56, v54
	v_lshlrev_b32_e32 v23, 16, v66
	v_lshlrev_b32_e32 v22, 16, v60
	v_lshlrev_b32_e32 v21, 16, v67
	s_waitcnt lgkmcnt(0)
	v_pk_add_f32 v[26:27], v[26:27], v[52:53]
	s_nop 1
	v_mov_b32_dpp v53, v27 row_shl:4 row_mask:0xf bank_mask:0x5
	v_mov_b32_dpp v53, v27 row_shr:4 row_mask:0xf bank_mask:0xa
	v_mov_b32_dpp v52, v26 row_shl:4 row_mask:0xf bank_mask:0x5
	v_mov_b32_dpp v52, v26 row_shr:4 row_mask:0xf bank_mask:0xa
	v_lshlrev_b32_e32 v20, 16, v64
	v_lshlrev_b32_e32 v50, 16, v65
	v_lshlrev_b32_e32 v15, 16, v69
	v_lshlrev_b32_e32 v14, 16, v68
	s_waitcnt lgkmcnt(0)
	v_pk_add_f32 v[26:27], v[26:27], v[52:53]
	s_nop 1
	v_mov_b32_dpp v53, v27 quad_perm:[2,3,0,1] row_mask:0xf bank_mask:0xf
	v_mov_b32_dpp v52, v26 quad_perm:[2,3,0,1] row_mask:0xf bank_mask:0xf
	v_add_u32_e32 v2, s17, v2
	s_waitcnt lgkmcnt(0)
	v_pk_add_f32 v[26:27], v[26:27], v[52:53]
	s_nop 1
	v_add_f32_dpp v53, v27, v27 quad_perm:[1,0,3,2] row_mask:0xf bank_mask:0xf
	v_add_f32_dpp v52, v26, v26 quad_perm:[1,0,3,2] row_mask:0xf bank_mask:0xf
	s_waitcnt lgkmcnt(0)
	v_mov_b64_e32 v[26:27], s[72:73]
	v_pk_fma_f32 v[52:53], v[52:53], s[4:5], v[26:27] op_sel_hi:[1,0,0]
	s_nop 0
	v_mul_f32_e32 v49, 0x4b800000, v53
	v_cmp_gt_f32_e64 s[0:1], s77, v53
	v_cmp_gt_f32_e32 vcc, s77, v52
	s_nop 0
	v_cndmask_b32_e64 v49, v53, v49, s[0:1]
	v_rsq_f32_e32 v49, v49
	s_nop 0
	v_mul_f32_e32 v53, 0x45800000, v49
	v_cndmask_b32_e64 v49, v49, v53, s[0:1]
	v_mul_f32_e32 v49, 0x3dd53b94, v49
	v_mul_f32_e32 v19, v49, v19
	v_mul_f32_e32 v19, v41, v19
	ds_bpermute_b32 v53, v43, v19
	v_mul_f32_e32 v18, v49, v18
	v_mul_f32_e32 v18, v36, v18
	s_waitcnt lgkmcnt(0)
	v_mul_f32_e32 v53, v35, v53
	v_cndmask_b32_e64 v53, v53, -v53, s[38:39]
	v_fmac_f32_e32 v53, v34, v19
	v_bfe_u32 v19, v18, 16, 1
	v_add3_u32 v18, v18, v19, s11
	global_store_short_d16_hi v[16:17], v18, off
	v_mul_f32_e32 v18, v49, v70
	v_mul_f32_e32 v18, v37, v18
	v_bfe_u32 v19, v18, 16, 1
	v_add3_u32 v18, v18, v19, s11
	global_store_short_d16_hi v[16:17], v18, off offset:128
	v_bfe_u32 v18, v53, 16, 1
	v_add3_u32 v18, v53, v18, s11
	global_store_short_d16_hi v[16:17], v18, off offset:256
	v_mul_f32_e32 v18, 0x4b800000, v52
	v_cndmask_b32_e32 v18, v52, v18, vcc
	v_rsq_f32_e32 v18, v18
	v_mul_f32_e32 v53, v51, v51
	v_mul_f32_e32 v19, 0x45800000, v18
	v_cndmask_b32_e32 v49, v18, v19, vcc
	v_mul_f32_e32 v18, v49, v12
	v_mul_f32_e32 v18, v40, v18
	ds_bpermute_b32 v19, v43, v18
	s_waitcnt lgkmcnt(0)
	v_mul_f32_e32 v19, v35, v19
	v_cndmask_b32_e64 v52, v19, -v19, s[38:39]
	v_fmac_f32_e32 v52, v34, v18
	v_mul_f32_e32 v18, v49, v32
	v_mul_f32_e32 v18, v38, v18
	v_bfe_u32 v19, v18, 16, 1
	v_add3_u32 v32, v18, v19, s11
	v_mad_i64_i32 v[18:19], s[0:1], v3, s7, v[8:9]
	v_mul_f32_e32 v3, v49, v33
	v_mul_f32_e32 v3, v39, v3
	global_store_short_d16_hi v[18:19], v32, off
	v_bfe_u32 v32, v3, 16, 1
	v_add3_u32 v3, v3, v32, s11
	global_store_short_d16_hi v[18:19], v3, off offset:128
	v_bfe_u32 v3, v52, 16, 1
	v_pk_mul_f32 v[32:33], v[30:31], v[30:31]
	v_add3_u32 v3, v52, v3, s11
	v_mov_b32_e32 v57, v32
	v_mov_b32_e32 v52, v55
	v_pk_add_f32 v[52:53], v[56:57], v[52:53]
	v_mov_b32_e32 v32, v24
	v_pk_add_f32 v[32:33], v[32:33], v[52:53]
	v_mov_b32_e32 v53, v33
	v_mov_b32_e32 v52, v32
	s_nop 0
	v_permlane32_swap_b32_e32 v53, v33
	v_permlane32_swap_b32_e32 v52, v32
	global_store_short_d16_hi v[18:19], v3, off offset:256
	s_waitcnt lgkmcnt(0)
; DI bf16_t f2bf(float f) { unsigned u = __float_as_uint(f); u += 0x7fffu + ((u >> 16) & 1u); return (bf16_t)(u >> 16); }
; DI float wave_sum(float v) { for (int o = 32; o; o >>= 1) v += __shfl_xor(v, o); return v; }
; DI void run_phase(const Params& p, int ph, unsigned char* smem, const int tid, const int rep) {
;     ...
;                 for (int h = 0; h < 4; ++h) {
;                     { const float a0 = qa[u][h][0], a1 = qa[u][h][1], a2 = qa[u][h][2];
;                       const float rs = rsqrtf(wave_sum(a0 * a0 + a1 * a1 + a2 * a2) * (1.f / 192.f) + NEPS) * (0.07216878364870322f * LOG2E);
;                       const float y2 = a2 * rs * gq2; const float oth = __shfl_xor(y2, 32);
;                       const float rot = (lane < 32) ? (y2 * cs - oth * sn) : (y2 * cs + oth * sn);
;                       bf16_t* qo = mlaq + (size_t)t * 768 + h * 192; qo[lane] = f2bf(a0 * rs * gq0); qo[lane + 64] = f2bf(a1 * rs * gq1); qo[lane + 128] = f2bf(rot); }
;                     { const float a0 = ka[u][h][0], a1 = ka[u][h][1];
;                       const float rs = rsqrtf(wave_sum(a0 * a0 + a1 * a1 + kr * kr) * (1.f / 192.f) + NEPS);
;                       const float y2 = kr * rs * gk2; const float oth = __shfl_xor(y2, 32);
;                       const float rot = (lane < 32) ? (y2 * cs - oth * sn) : (y2 * cs + oth * sn);
;                       bf16_t* ko = mlak + (size_t)t * 768 + h * 192; ko[lane] = f2bf(a0 * rs * gk0); ko[lane + 64] = f2bf(a1 * rs * gk1); ko[lane + 128] = f2bf(rot); }
	v_pk_add_f32 v[32:33], v[32:33], v[52:53]
	v_mov_b32_e32 v53, v33
	v_mov_b32_e32 v52, v32
	s_nop 0
	v_permlane16_swap_b32_e32 v53, v33
	v_permlane16_swap_b32_e32 v52, v32
	s_waitcnt lgkmcnt(0)
	v_pk_add_f32 v[32:33], v[32:33], v[52:53]
	s_nop 1
	v_add_f32_dpp v33, v33, v33 row_ror:8 row_mask:0xf bank_mask:0xf
	v_add_f32_dpp v32, v32, v32 row_ror:8 row_mask:0xf bank_mask:0xf
	s_waitcnt lgkmcnt(0)
	s_nop 1
	v_add_f32_dpp v33, v33, v33 row_ror:4 row_mask:0xf bank_mask:0xf
	v_add_f32_dpp v32, v32, v32 row_ror:4 row_mask:0xf bank_mask:0xf
	s_waitcnt lgkmcnt(0)
	s_nop 1
	v_add_f32_dpp v33, v33, v33 quad_perm:[2,3,0,1] row_mask:0xf bank_mask:0xf
	v_add_f32_dpp v32, v32, v32 quad_perm:[2,3,0,1] row_mask:0xf bank_mask:0xf
	s_waitcnt lgkmcnt(0)
	s_nop 1
	v_add_f32_dpp v33, v33, v33 quad_perm:[1,0,3,2] row_mask:0xf bank_mask:0xf
	v_add_f32_dpp v32, v32, v32 quad_perm:[1,0,3,2] row_mask:0xf bank_mask:0xf
	s_waitcnt lgkmcnt(0)
	s_nop 0
	v_pk_fma_f32 v[32:33], v[32:33], s[4:5], v[26:27] op_sel_hi:[1,0,0]
	s_nop 0
	v_mul_f32_e32 v3, 0x4b800000, v33
	v_cmp_gt_f32_e64 s[0:1], s77, v33
	v_cmp_gt_f32_e32 vcc, s77, v32
	s_nop 0
	v_cndmask_b32_e64 v3, v33, v3, s[0:1]
	v_rsq_f32_e32 v3, v3
	s_nop 0
	v_mul_f32_e32 v33, 0x45800000, v3
	v_cndmask_b32_e64 v3, v3, v33, s[0:1]
	v_mul_f32_e32 v3, 0x3dd53b94, v3
	v_mul_f32_e32 v31, v3, v31
	v_mul_f32_e32 v31, v41, v31
	ds_bpermute_b32 v33, v43, v31
	v_mul_f32_e32 v30, v3, v30
	v_mul_f32_e32 v30, v36, v30
	v_mul_f32_e32 v3, v3, v51
	v_mul_f32_e32 v3, v37, v3
	s_waitcnt lgkmcnt(0)
	v_mul_f32_e32 v33, v35, v33
	v_cndmask_b32_e64 v33, v33, -v33, s[38:39]
	v_fmac_f32_e32 v33, v34, v31
	v_bfe_u32 v31, v30, 16, 1
	v_add3_u32 v30, v30, v31, s11
	global_store_short_d16_hi v[16:17], v30, off offset:384
	v_bfe_u32 v30, v3, 16, 1
	v_add3_u32 v3, v3, v30, s11
	global_store_short_d16_hi v[16:17], v3, off offset:512
	v_bfe_u32 v3, v33, 16, 1
	v_add3_u32 v3, v33, v3, s11
	global_store_short_d16_hi v[16:17], v3, off offset:640
	v_mul_f32_e32 v3, 0x4b800000, v32
	v_cndmask_b32_e32 v3, v32, v3, vcc
	v_rsq_f32_e32 v3, v3
	v_pk_mul_f32 v[32:33], v[20:21], v[20:21]
	v_mul_f32_e32 v30, 0x45800000, v3
	v_cndmask_b32_e32 v3, v3, v30, vcc
	v_mul_f32_e32 v30, v3, v12
	v_mul_f32_e32 v30, v40, v30
	ds_bpermute_b32 v31, v43, v30
	v_mul_f32_e32 v28, v3, v28
	v_mul_f32_e32 v28, v38, v28
	v_mul_f32_e32 v3, v3, v29
	v_mul_f32_e32 v3, v39, v3
	s_waitcnt lgkmcnt(0)
	v_mul_f32_e32 v31, v35, v31
	v_cndmask_b32_e64 v31, v31, -v31, s[38:39]
	v_fmac_f32_e32 v31, v34, v30
	v_bfe_u32 v30, v28, 16, 1
	v_add3_u32 v28, v28, v30, s11
	global_store_short_d16_hi v[18:19], v28, off offset:384
	v_bfe_u32 v28, v3, 16, 1
	v_add3_u32 v3, v3, v28, s11
	global_store_short_d16_hi v[18:19], v3, off offset:512
	v_bfe_u32 v3, v31, 16, 1
	v_pk_mul_f32 v[28:29], v[22:23], v[22:23]
	v_add3_u32 v3, v31, v3, s11
	v_mul_f32_e32 v31, v50, v50
	v_mov_b32_e32 v52, v32
	v_mov_b32_e32 v53, v28
	v_mov_b32_e32 v30, v33
	v_pk_add_f32 v[30:31], v[52:53], v[30:31]
	v_mov_b32_e32 v28, v24
	v_pk_add_f32 v[28:29], v[28:29], v[30:31]
	v_mov_b32_e32 v31, v29
	v_mov_b32_e32 v30, v28
	s_nop 0
	v_permlane32_swap_b32_e32 v31, v29
	v_permlane32_swap_b32_e32 v30, v28
	global_store_short_d16_hi v[18:19], v3, off offset:640
	s_waitcnt lgkmcnt(0)
	v_pk_add_f32 v[28:29], v[28:29], v[30:31]
	v_mov_b32_e32 v31, v29
	v_mov_b32_e32 v30, v28
	s_nop 0
	v_permlane16_swap_b32_e32 v31, v29
	v_permlane16_swap_b32_e32 v30, v28
	s_waitcnt lgkmcnt(0)
	v_pk_add_f32 v[28:29], v[28:29], v[30:31]
	s_nop 1
	v_add_f32_dpp v29, v29, v29 row_ror:8 row_mask:0xf bank_mask:0xf
	v_add_f32_dpp v28, v28, v28 row_ror:8 row_mask:0xf bank_mask:0xf
	s_waitcnt lgkmcnt(0)
	s_nop 1
	v_add_f32_dpp v29, v29, v29 row_ror:4 row_mask:0xf bank_mask:0xf
	v_add_f32_dpp v28, v28, v28 row_ror:4 row_mask:0xf bank_mask:0xf
	s_waitcnt lgkmcnt(0)
	s_nop 1
	v_add_f32_dpp v29, v29, v29 quad_perm:[2,3,0,1] row_mask:0xf bank_mask:0xf
	v_add_f32_dpp v28, v28, v28 quad_perm:[2,3,0,1] row_mask:0xf bank_mask:0xf
	s_waitcnt lgkmcnt(0)
	s_nop 1
	v_add_f32_dpp v29, v29, v29 quad_perm:[1,0,3,2] row_mask:0xf bank_mask:0xf
	v_add_f32_dpp v28, v28, v28 quad_perm:[1,0,3,2] row_mask:0xf bank_mask:0xf
	s_waitcnt lgkmcnt(0)
	s_nop 0
	v_pk_fma_f32 v[28:29], v[28:29], s[4:5], v[26:27] op_sel_hi:[1,0,0]
	s_nop 0
	v_mul_f32_e32 v3, 0x4b800000, v29
	v_cmp_gt_f32_e64 s[0:1], s77, v29
	v_cmp_gt_f32_e32 vcc, s77, v28
	s_nop 0
	v_cndmask_b32_e64 v3, v29, v3, s[0:1]
	v_rsq_f32_e32 v3, v3
	s_nop 0
	v_mul_f32_e32 v29, 0x45800000, v3
	v_cndmask_b32_e64 v3, v3, v29, s[0:1]
	v_mul_f32_e32 v3, 0x3dd53b94, v3
	v_mul_f32_e32 v23, v3, v23
	v_mul_f32_e32 v23, v41, v23
	ds_bpermute_b32 v29, v43, v23
	v_mul_f32_e32 v22, v3, v22
	v_mul_f32_e32 v22, v36, v22
	v_mul_f32_e32 v3, v3, v50
	v_mul_f32_e32 v3, v37, v3
	s_waitcnt lgkmcnt(0)
; DI bf16_t f2bf(float f) { unsigned u = __float_as_uint(f); u += 0x7fffu + ((u >> 16) & 1u); return (bf16_t)(u >> 16); }
; DI float wave_sum(float v) { for (int o = 32; o; o >>= 1) v += __shfl_xor(v, o); return v; }
; DI void run_phase(const Params& p, int ph, unsigned char* smem, const int tid, const int rep) {
;     ...
;         for (int t0 = (blockIdx.x * 8 + wv) * 2; t0 < TS; t0 += gridDim.x * 16) {
;     ...
;                 for (int h = 0; h < 4; ++h) {
;                     { const float a0 = qa[u][h][0], a1 = qa[u][h][1], a2 = qa[u][h][2];
;                       const float rs = rsqrtf(wave_sum(a0 * a0 + a1 * a1 + a2 * a2) * (1.f / 192.f) + NEPS) * (0.07216878364870322f * LOG2E);
;                       const float y2 = a2 * rs * gq2; const float oth = __shfl_xor(y2, 32);
;                       const float rot = (lane < 32) ? (y2 * cs - oth * sn) : (y2 * cs + oth * sn);
;                       bf16_t* qo = mlaq + (size_t)t * 768 + h * 192; qo[lane] = f2bf(a0 * rs * gq0); qo[lane + 64] = f2bf(a1 * rs * gq1); qo[lane + 128] = f2bf(rot); }
;                     { const float a0 = ka[u][h][0], a1 = ka[u][h][1];
;                       const float rs = rsqrtf(wave_sum(a0 * a0 + a1 * a1 + kr * kr) * (1.f / 192.f) + NEPS);
;                       const float y2 = kr * rs * gk2; const float oth = __shfl_xor(y2, 32);
;                       const float rot = (lane < 32) ? (y2 * cs - oth * sn) : (y2 * cs + oth * sn);
;                       bf16_t* ko = mlak + (size_t)t * 768 + h * 192; ko[lane] = f2bf(a0 * rs * gk0); ko[lane + 64] = f2bf(a1 * rs * gk1); ko[lane + 128] = f2bf(rot); }
	v_mul_f32_e32 v29, v35, v29
	v_cndmask_b32_e64 v29, v29, -v29, s[38:39]
	v_fmac_f32_e32 v29, v34, v23
	v_bfe_u32 v23, v22, 16, 1
	v_add3_u32 v22, v22, v23, s11
	global_store_short_d16_hi v[16:17], v22, off offset:768
	v_bfe_u32 v22, v3, 16, 1
	v_add3_u32 v3, v3, v22, s11
	global_store_short_d16_hi v[16:17], v3, off offset:896
	v_bfe_u32 v3, v29, 16, 1
	v_add3_u32 v3, v29, v3, s11
	global_store_short_d16_hi v[16:17], v3, off offset:1024
	v_mul_f32_e32 v3, 0x4b800000, v28
	v_cndmask_b32_e32 v3, v28, v3, vcc
	v_rsq_f32_e32 v3, v3
	s_nop 0
	v_mul_f32_e32 v22, 0x45800000, v3
	v_cndmask_b32_e32 v3, v3, v22, vcc
	v_mul_f32_e32 v22, v3, v12
	v_mul_f32_e32 v22, v40, v22
	ds_bpermute_b32 v23, v43, v22
	v_mul_f32_e32 v20, v3, v20
	v_mul_f32_e32 v20, v38, v20
	v_mul_f32_e32 v3, v3, v21
	v_mul_f32_e32 v3, v39, v3
	s_waitcnt lgkmcnt(0)
	v_mul_f32_e32 v23, v35, v23
	v_cndmask_b32_e64 v23, v23, -v23, s[38:39]
	v_fmac_f32_e32 v23, v34, v22
	v_bfe_u32 v22, v20, 16, 1
	v_add3_u32 v20, v20, v22, s11
	global_store_short_d16_hi v[18:19], v20, off offset:768
	v_bfe_u32 v20, v3, 16, 1
	v_add3_u32 v3, v3, v20, s11
	global_store_short_d16_hi v[18:19], v3, off offset:896
	v_bfe_u32 v3, v23, 16, 1
	v_pk_mul_f32 v[20:21], v[14:15], v[14:15]
	v_add3_u32 v3, v23, v3, s11
	v_pk_mov_b32 v[22:23], v[24:25], v[20:21] op_sel:[1,0]
	v_mov_b32_e32 v25, v21
	v_pk_fma_f32 v[22:23], v[10:11], v[10:11], v[22:23]
	global_store_short_d16_hi v[18:19], v3, off offset:1024
	v_pk_add_f32 v[20:21], v[24:25], v[22:23]
	v_mov_b32_e32 v23, v21
	v_mov_b32_e32 v22, v20
	s_nop 0
	v_permlane32_swap_b32_e32 v23, v21
	v_permlane32_swap_b32_e32 v22, v20
	s_waitcnt lgkmcnt(0)
	v_pk_add_f32 v[20:21], v[20:21], v[22:23]
	v_mov_b32_e32 v23, v21
	v_mov_b32_e32 v22, v20
	s_nop 0
	v_permlane16_swap_b32_e32 v23, v21
	v_permlane16_swap_b32_e32 v22, v20
	s_waitcnt lgkmcnt(0)
	v_pk_add_f32 v[20:21], v[20:21], v[22:23]
	s_nop 1
	v_add_f32_dpp v21, v21, v21 row_ror:8 row_mask:0xf bank_mask:0xf
	v_add_f32_dpp v20, v20, v20 row_ror:8 row_mask:0xf bank_mask:0xf
	s_waitcnt lgkmcnt(0)
	s_nop 1
	v_add_f32_dpp v21, v21, v21 row_ror:4 row_mask:0xf bank_mask:0xf
	v_add_f32_dpp v20, v20, v20 row_ror:4 row_mask:0xf bank_mask:0xf
	s_waitcnt lgkmcnt(0)
	s_nop 1
	v_add_f32_dpp v21, v21, v21 quad_perm:[2,3,0,1] row_mask:0xf bank_mask:0xf
	v_add_f32_dpp v20, v20, v20 quad_perm:[2,3,0,1] row_mask:0xf bank_mask:0xf
	s_waitcnt lgkmcnt(0)
	s_nop 1
	v_add_f32_dpp v21, v21, v21 quad_perm:[1,0,3,2] row_mask:0xf bank_mask:0xf
	v_add_f32_dpp v20, v20, v20 quad_perm:[1,0,3,2] row_mask:0xf bank_mask:0xf
	s_waitcnt lgkmcnt(0)
	s_nop 0
	v_pk_fma_f32 v[20:21], v[20:21], s[4:5], v[26:27] op_sel_hi:[1,0,0]
	s_nop 0
	v_mul_f32_e32 v3, 0x4b800000, v21
	v_cmp_gt_f32_e64 s[0:1], s77, v21
	v_cmp_gt_f32_e32 vcc, s77, v20
	s_nop 0
	v_cndmask_b32_e64 v3, v21, v3, s[0:1]
	v_rsq_f32_e32 v3, v3
	s_nop 0
	v_mul_f32_e32 v21, 0x45800000, v3
	v_cndmask_b32_e64 v3, v3, v21, s[0:1]
	v_mul_f32_e32 v3, 0x3dd53b94, v3
	v_mul_f32_e32 v15, v3, v15
	v_mul_f32_e32 v15, v41, v15
	ds_bpermute_b32 v21, v43, v15
	v_mul_f32_e32 v14, v3, v14
	v_mul_f32_e32 v3, v3, v11
	v_mul_f32_e32 v3, v37, v3
	v_bfe_u32 v11, v3, 16, 1
	s_waitcnt lgkmcnt(0)
	v_mul_f32_e32 v21, v35, v21
	v_cndmask_b32_e64 v21, v21, -v21, s[38:39]
	v_fmac_f32_e32 v21, v34, v15
	v_add3_u32 v3, v3, v11, s11
	global_store_short_d16_hi v[16:17], v3, off offset:1280
	v_bfe_u32 v3, v21, 16, 1
	v_add3_u32 v3, v21, v3, s11
	global_store_short_d16_hi v[16:17], v3, off offset:1408
	v_mul_f32_e32 v3, 0x4b800000, v20
	v_cndmask_b32_e32 v3, v20, v3, vcc
	v_rsq_f32_e32 v3, v3
	v_mul_f32_e32 v14, v36, v14
	v_bfe_u32 v15, v14, 16, 1
	v_add3_u32 v14, v14, v15, s11
	v_mul_f32_e32 v11, 0x45800000, v3
	v_cndmask_b32_e32 v3, v3, v11, vcc
	v_mul_f32_e32 v11, v3, v12
	v_mul_f32_e32 v11, v40, v11
	ds_bpermute_b32 v12, v43, v11
	v_cmp_lt_i32_e32 vcc, s11, v2
	s_or_b64 s[34:35], vcc, s[34:35]
	global_store_short_d16_hi v[16:17], v14, off offset:1152
	s_waitcnt lgkmcnt(0)
	v_mul_f32_e32 v12, v35, v12
	v_cndmask_b32_e64 v12, v12, -v12, s[38:39]
	v_fmac_f32_e32 v12, v34, v11
	v_mul_f32_e32 v11, v3, v13
	v_mul_f32_e32 v3, v3, v10
	v_mul_f32_e32 v3, v39, v3
	v_bfe_u32 v10, v3, 16, 1
	v_mul_f32_e32 v11, v38, v11
	v_add3_u32 v3, v3, v10, s11
	v_bfe_u32 v13, v11, 16, 1
	global_store_short_d16_hi v[18:19], v3, off offset:1280
	v_bfe_u32 v3, v12, 16, 1
	v_add3_u32 v11, v11, v13, s11
	v_add3_u32 v3, v12, v3, s11
	global_store_short_d16_hi v[18:19], v11, off offset:1152
	global_store_short_d16_hi v[18:19], v3, off offset:1408
	s_andn2_b64 exec, exec, s[34:35]
	s_cbranch_execz .LBB0_340

; DI bf16_t f2bf(float f) { unsigned u = __float_as_uint(f); u += 0x7fffu + ((u >> 16) & 1u); return (bf16_t)(u >> 16); }
; DI float wave_sum(float v) { for (int o = 32; o; o >>= 1) v += __shfl_xor(v, o); return v; }
; DI void run_phase(const Params& p, int ph, unsigned char* smem, const int tid, const int rep) {
;     ...
;             for (int u = 0; u < 2; ++u) { const int t = t0 + u;
;                 const float ang = (float)ps[u] * invf; float sn, cs; sincosf(ang, &sn, &cs);
;                 const float kr = krv[u];
; #pragma unroll
;                 for (int h = 0; h < 4; ++h) {
;                     { const float a0 = qa[u][h][0], a1 = qa[u][h][1], a2 = qa[u][h][2];
;                       const float rs = rsqrtf(wave_sum(a0 * a0 + a1 * a1 + a2 * a2) * (1.f / 192.f) + NEPS) * (0.07216878364870322f * LOG2E);
;                       const float y2 = a2 * rs * gq2; const float oth = __shfl_xor(y2, 32);
;                       const float rot = (lane < 32) ? (y2 * cs - oth * sn) : (y2 * cs + oth * sn);
;                       bf16_t* qo = mlaq + (size_t)t * 768 + h * 192; qo[lane] = f2bf(a0 * rs * gq0); qo[lane + 64] = f2bf(a1 * rs * gq1); qo[lane + 128] = f2bf(rot); }
;                     { const float a0 = ka[u][h][0], a1 = ka[u][h][1];
;                       const float rs = rsqrtf(wave_sum(a0 * a0 + a1 * a1 + kr * kr) * (1.f / 192.f) + NEPS);
;                       const float y2 = kr * rs * gk2; const float oth = __shfl_xor(y2, 32);
;                       const float rot = (lane < 32) ? (y2 * cs - oth * sn) : (y2 * cs + oth * sn);
;                       bf16_t* ko = mlak + (size_t)t * 768 + h * 192; ko[lane] = f2bf(a0 * rs * gk0); ko[lane + 64] = f2bf(a1 * rs * gk1); ko[lane + 128] = f2bf(rot); }
.LBB0_336:
	s_or_b64 exec, exec, s[0:1]
	s_waitcnt vmcnt(40)
	v_lshlrev_b32_e32 v20, 16, v15
	s_waitcnt vmcnt(22)
	v_lshlrev_b32_e32 v15, 16, v14
	v_lshlrev_b32_e32 v14, 16, v12
	s_waitcnt vmcnt(21)
	v_lshlrev_b32_e32 v12, 16, v18
	v_mul_f32_e32 v18, v78, v78
	v_lshlrev_b32_e32 v32, 16, v19
	v_fmamk_f32 v19, v18, 0xb94c1982, v249
	v_fmaak_f32 v19, v18, v19, 0xbe2aaa9d
	v_mul_f32_e32 v19, v18, v19
	v_fmac_f32_e32 v78, v78, v19
	v_fmamk_f32 v19, v18, 0x37d75334, v223
	v_fmaak_f32 v19, v18, v19, 0x3d2aabf7
	v_lshlrev_b32_e32 v30, 16, v27
	v_fmaak_f32 v19, v18, v19, 0xbf000004
	v_and_b32_e32 v27, 1, v79
	v_fma_f32 v18, v18, v19, 1.0
	v_cmp_eq_u32_e32 vcc, 0, v27
	v_lshlrev_b32_e32 v31, 16, v28
	v_lshlrev_b32_e32 v19, 30, v79
	v_cndmask_b32_e32 v27, v18, v78, vcc
	v_xor_b32_e32 v28, v77, v10
	v_lshlrev_b32_e32 v33, 16, v24
	v_lshlrev_b32_e32 v24, 16, v26
	v_and_b32_e32 v26, 0x80000000, v19
	v_xor_b32_e32 v27, v28, v27
	v_xor_b32_e32 v26, v27, v26
	v_xor_b32_e32 v27, 0x80000000, v78
	v_cndmask_b32_e32 v18, v27, v18, vcc
	s_brev_b32 s0, 1
	v_lshlrev_b32_e32 v21, 16, v17
	v_lshlrev_b32_e32 v35, 16, v25
	v_lshlrev_b32_e32 v34, 16, v22
	v_bitop3_b32 v18, v18, v19, s0 bitop3:0x78
	s_movk_i32 s0, 0x1f8
	v_lshlrev_b32_e32 v80, 16, v16
	v_lshlrev_b32_e32 v22, 16, v29
	v_lshlrev_b32_e32 v17, 16, v76
	v_cmp_class_f32_e64 vcc, v10, s0
	v_pk_mul_f32 v[28:29], v[20:21], v[20:21]
	v_pk_mul_f32 v[76:77], v[34:35], v[34:35]
	v_lshlrev_b32_e32 v72, 16, v23
	v_lshlrev_b32_e32 v71, 16, v70
	v_lshlrev_b32_e32 v23, 16, v74
	v_lshlrev_b32_e32 v16, 16, v75
	v_cndmask_b32_e32 v70, v224, v26, vcc
	v_pk_mul_f32 v[26:27], v[14:15], v[14:15]
	v_mul_f32_e32 v75, v80, v80
	v_mov_b32_e32 v78, v76
	v_mov_b32_e32 v79, v28
	v_mov_b32_e32 v74, v77
	v_pk_add_f32 v[74:75], v[78:79], v[74:75]
	v_mov_b32_e32 v28, v26
	v_pk_add_f32 v[28:29], v[28:29], v[74:75]
	v_mov_b32_e32 v75, v29
	v_mov_b32_e32 v74, v28
	s_nop 0
	v_permlane32_swap_b32_e32 v75, v29
	v_permlane32_swap_b32_e32 v74, v28
	s_mov_b32 s4, 0x3baaaaab
	v_cndmask_b32_e32 v10, v224, v18, vcc
	v_mad_i64_i32 v[18:19], s[0:1], v2, s7, v[6:7]
	s_waitcnt lgkmcnt(0)
	v_pk_add_f32 v[28:29], v[28:29], v[74:75]
	v_mov_b32_e32 v75, v29
	v_mov_b32_e32 v74, v28
	s_nop 0
	v_permlane16_swap_b32_e32 v75, v29
	v_permlane16_swap_b32_e32 v74, v28
	v_lshlrev_b32_e32 v25, 16, v73
	v_pk_mul_f32 v[76:77], v[30:31], v[30:31]
	v_lshlrev_b32_e32 v13, 16, v13
	v_mov_b32_e32 v78, v76
	s_waitcnt lgkmcnt(0)
	v_pk_add_f32 v[28:29], v[28:29], v[74:75]
	s_nop 1
	v_add_f32_dpp v29, v29, v29 row_ror:8 row_mask:0xf bank_mask:0xf
	v_add_f32_dpp v28, v28, v28 row_ror:8 row_mask:0xf bank_mask:0xf
	s_waitcnt lgkmcnt(0)
	s_nop 1
	v_add_f32_dpp v29, v29, v29 row_ror:4 row_mask:0xf bank_mask:0xf
	v_add_f32_dpp v28, v28, v28 row_ror:4 row_mask:0xf bank_mask:0xf
	s_waitcnt lgkmcnt(0)
	s_nop 1
	v_add_f32_dpp v29, v29, v29 quad_perm:[2,3,0,1] row_mask:0xf bank_mask:0xf
	v_add_f32_dpp v28, v28, v28 quad_perm:[2,3,0,1] row_mask:0xf bank_mask:0xf
	s_waitcnt lgkmcnt(0)
	s_nop 1
	v_add_f32_dpp v75, v29, v29 quad_perm:[1,0,3,2] row_mask:0xf bank_mask:0xf
	v_add_f32_dpp v74, v28, v28 quad_perm:[1,0,3,2] row_mask:0xf bank_mask:0xf
	s_waitcnt lgkmcnt(0)
	v_mov_b64_e32 v[28:29], s[72:73]
	v_pk_fma_f32 v[74:75], v[74:75], s[4:5], v[28:29] op_sel_hi:[1,0,0]
	s_nop 0
	v_mul_f32_e32 v73, 0x4b800000, v75
	v_cmp_gt_f32_e64 s[0:1], s77, v75
	v_cmp_gt_f32_e32 vcc, s77, v74
	s_nop 0
	v_cndmask_b32_e64 v73, v75, v73, s[0:1]
	v_rsq_f32_e32 v73, v73
	s_nop 0
	v_mul_f32_e32 v75, 0x45800000, v73
	v_cndmask_b32_e64 v73, v73, v75, s[0:1]
	v_mul_f32_e32 v73, 0x3dd53b94, v73
	v_mul_f32_e32 v21, v73, v21
	v_mul_f32_e32 v21, v41, v21
	ds_bpermute_b32 v75, v43, v21
	v_mul_f32_e32 v20, v73, v20
	v_mul_f32_e32 v20, v36, v20
	s_waitcnt lgkmcnt(0)
	v_mul_f32_e32 v75, v70, v75
	v_cndmask_b32_e64 v75, v75, -v75, s[38:39]
	v_fmac_f32_e32 v75, v10, v21
	v_bfe_u32 v21, v20, 16, 1
	v_add3_u32 v20, v20, v21, s11
	global_store_short_d16_hi v[18:19], v20, off
	v_mul_f32_e32 v20, v73, v80
	v_mul_f32_e32 v20, v37, v20
	v_bfe_u32 v21, v20, 16, 1
	v_add3_u32 v20, v20, v21, s11
	global_store_short_d16_hi v[18:19], v20, off offset:128
	v_bfe_u32 v20, v75, 16, 1
	v_add3_u32 v20, v75, v20, s11
	global_store_short_d16_hi v[18:19], v20, off offset:256
	v_mul_f32_e32 v20, 0x4b800000, v74
	v_cndmask_b32_e32 v20, v74, v20, vcc
	v_rsq_f32_e32 v20, v20
	v_mul_f32_e32 v75, v72, v72
	v_mul_f32_e32 v21, 0x45800000, v20
	v_cndmask_b32_e32 v73, v20, v21, vcc
	v_mul_f32_e32 v20, v73, v14
	v_mul_f32_e32 v20, v40, v20
	ds_bpermute_b32 v21, v43, v20
	s_waitcnt lgkmcnt(0)
	v_mul_f32_e32 v21, v70, v21
	v_cndmask_b32_e64 v74, v21, -v21, s[38:39]
	v_fmac_f32_e32 v74, v10, v20
	v_mul_f32_e32 v20, v73, v34
	v_mul_f32_e32 v20, v38, v20
	v_bfe_u32 v21, v20, 16, 1
	v_add3_u32 v34, v20, v21, s11
	v_mad_i64_i32 v[20:21], s[0:1], v2, s7, v[8:9]
	global_store_short_d16_hi v[20:21], v34, off
	v_mul_f32_e32 v34, v73, v35
	v_mul_f32_e32 v34, v39, v34
	v_bfe_u32 v35, v34, 16, 1
	v_add3_u32 v34, v34, v35, s11
	global_store_short_d16_hi v[20:21], v34, off offset:128
	v_bfe_u32 v34, v74, 16, 1
	v_add3_u32 v34, v74, v34, s11
	global_store_short_d16_hi v[20:21], v34, off offset:256
	v_pk_mul_f32 v[34:35], v[32:33], v[32:33]
	v_mov_b32_e32 v74, v77
	v_mov_b32_e32 v79, v34
	v_pk_add_f32 v[74:75], v[78:79], v[74:75]
	v_mov_b32_e32 v34, v26
	v_pk_add_f32 v[34:35], v[34:35], v[74:75]
	v_mov_b32_e32 v75, v35
	v_mov_b32_e32 v74, v34
	s_nop 0
	v_permlane32_swap_b32_e32 v75, v35
	v_permlane32_swap_b32_e32 v74, v34
	s_waitcnt lgkmcnt(0)
	v_pk_add_f32 v[34:35], v[34:35], v[74:75]
	v_mov_b32_e32 v75, v35
	v_mov_b32_e32 v74, v34
	s_nop 0
	v_permlane16_swap_b32_e32 v75, v35
	v_permlane16_swap_b32_e32 v74, v34
	s_waitcnt lgkmcnt(0)
; DI bf16_t f2bf(float f) { unsigned u = __float_as_uint(f); u += 0x7fffu + ((u >> 16) & 1u); return (bf16_t)(u >> 16); }
; DI float wave_sum(float v) { for (int o = 32; o; o >>= 1) v += __shfl_xor(v, o); return v; }
; DI void run_phase(const Params& p, int ph, unsigned char* smem, const int tid, const int rep) {
;     ...
;                 for (int h = 0; h < 4; ++h) {
;                     { const float a0 = qa[u][h][0], a1 = qa[u][h][1], a2 = qa[u][h][2];
;                       const float rs = rsqrtf(wave_sum(a0 * a0 + a1 * a1 + a2 * a2) * (1.f / 192.f) + NEPS) * (0.07216878364870322f * LOG2E);
;                       const float y2 = a2 * rs * gq2; const float oth = __shfl_xor(y2, 32);
;                       const float rot = (lane < 32) ? (y2 * cs - oth * sn) : (y2 * cs + oth * sn);
;                       bf16_t* qo = mlaq + (size_t)t * 768 + h * 192; qo[lane] = f2bf(a0 * rs * gq0); qo[lane + 64] = f2bf(a1 * rs * gq1); qo[lane + 128] = f2bf(rot); }
;                     { const float a0 = ka[u][h][0], a1 = ka[u][h][1];
;                       const float rs = rsqrtf(wave_sum(a0 * a0 + a1 * a1 + kr * kr) * (1.f / 192.f) + NEPS);
;                       const float y2 = kr * rs * gk2; const float oth = __shfl_xor(y2, 32);
;                       const float rot = (lane < 32) ? (y2 * cs - oth * sn) : (y2 * cs + oth * sn);
;                       bf16_t* ko = mlak + (size_t)t * 768 + h * 192; ko[lane] = f2bf(a0 * rs * gk0); ko[lane + 64] = f2bf(a1 * rs * gk1); ko[lane + 128] = f2bf(rot); }
	v_pk_add_f32 v[34:35], v[34:35], v[74:75]
	s_nop 1
	v_add_f32_dpp v35, v35, v35 row_ror:8 row_mask:0xf bank_mask:0xf
	v_add_f32_dpp v34, v34, v34 row_ror:8 row_mask:0xf bank_mask:0xf
	s_waitcnt lgkmcnt(0)
	s_nop 1
	v_add_f32_dpp v35, v35, v35 row_ror:4 row_mask:0xf bank_mask:0xf
	v_add_f32_dpp v34, v34, v34 row_ror:4 row_mask:0xf bank_mask:0xf
	s_waitcnt lgkmcnt(0)
	s_nop 1
	v_add_f32_dpp v35, v35, v35 quad_perm:[2,3,0,1] row_mask:0xf bank_mask:0xf
	v_add_f32_dpp v34, v34, v34 quad_perm:[2,3,0,1] row_mask:0xf bank_mask:0xf
	s_waitcnt lgkmcnt(0)
	s_nop 1
	v_add_f32_dpp v35, v35, v35 quad_perm:[1,0,3,2] row_mask:0xf bank_mask:0xf
	v_add_f32_dpp v34, v34, v34 quad_perm:[1,0,3,2] row_mask:0xf bank_mask:0xf
	s_waitcnt lgkmcnt(0)
	s_nop 0
	v_pk_fma_f32 v[34:35], v[34:35], s[4:5], v[28:29] op_sel_hi:[1,0,0]
	s_nop 0
	v_mul_f32_e32 v73, 0x4b800000, v35
	v_cmp_gt_f32_e64 s[0:1], s77, v35
	v_cmp_gt_f32_e32 vcc, s77, v34
	s_nop 0
	v_cndmask_b32_e64 v35, v35, v73, s[0:1]
	v_rsq_f32_e32 v35, v35
	s_nop 0
	v_mul_f32_e32 v73, 0x45800000, v35
	v_cndmask_b32_e64 v35, v35, v73, s[0:1]
	v_mul_f32_e32 v35, 0x3dd53b94, v35
	v_mul_f32_e32 v33, v35, v33
	v_mul_f32_e32 v33, v41, v33
	ds_bpermute_b32 v73, v43, v33
	v_mul_f32_e32 v32, v35, v32
	v_mul_f32_e32 v32, v36, v32
	s_waitcnt lgkmcnt(0)
	v_mul_f32_e32 v73, v70, v73
	v_cndmask_b32_e64 v73, v73, -v73, s[38:39]
	v_fmac_f32_e32 v73, v10, v33
	v_bfe_u32 v33, v32, 16, 1
	v_add3_u32 v32, v32, v33, s11
	global_store_short_d16_hi v[18:19], v32, off offset:384
	v_mul_f32_e32 v32, v35, v72
	v_mul_f32_e32 v32, v37, v32
	v_bfe_u32 v33, v32, 16, 1
	v_add3_u32 v32, v32, v33, s11
	global_store_short_d16_hi v[18:19], v32, off offset:512
	v_bfe_u32 v32, v73, 16, 1
	v_add3_u32 v32, v73, v32, s11
	global_store_short_d16_hi v[18:19], v32, off offset:640
	v_mul_f32_e32 v32, 0x4b800000, v34
	v_cndmask_b32_e32 v32, v34, v32, vcc
	v_rsq_f32_e32 v32, v32
	s_nop 0
	v_mul_f32_e32 v33, 0x45800000, v32
	v_cndmask_b32_e32 v32, v32, v33, vcc
	v_mul_f32_e32 v33, v32, v14
	v_mul_f32_e32 v33, v40, v33
	ds_bpermute_b32 v34, v43, v33
	v_mul_f32_e32 v30, v32, v30
	v_mul_f32_e32 v30, v38, v30
	s_waitcnt lgkmcnt(0)
	v_mul_f32_e32 v34, v70, v34
	v_cndmask_b32_e64 v34, v34, -v34, s[38:39]
	v_fmac_f32_e32 v34, v10, v33
	v_bfe_u32 v33, v30, 16, 1
	v_add3_u32 v30, v30, v33, s11
	global_store_short_d16_hi v[20:21], v30, off offset:384
	v_mul_f32_e32 v30, v32, v31
	v_mul_f32_e32 v30, v39, v30
	v_bfe_u32 v31, v30, 16, 1
	v_add3_u32 v30, v30, v31, s11
	global_store_short_d16_hi v[20:21], v30, off offset:512
	v_bfe_u32 v30, v34, 16, 1
	v_add3_u32 v30, v34, v30, s11
	global_store_short_d16_hi v[20:21], v30, off offset:640
	v_pk_mul_f32 v[30:31], v[24:25], v[24:25]
	v_pk_mul_f32 v[34:35], v[22:23], v[22:23]
	v_mul_f32_e32 v33, v71, v71
	v_mov_b32_e32 v72, v34
	v_mov_b32_e32 v73, v30
	v_mov_b32_e32 v32, v35
	v_pk_add_f32 v[32:33], v[72:73], v[32:33]
	v_mov_b32_e32 v30, v26
	v_pk_add_f32 v[30:31], v[30:31], v[32:33]
	v_mov_b32_e32 v33, v31
	v_mov_b32_e32 v32, v30
	s_nop 0
	v_permlane32_swap_b32_e32 v33, v31
	v_permlane32_swap_b32_e32 v32, v30
	s_waitcnt lgkmcnt(0)
	v_pk_add_f32 v[30:31], v[30:31], v[32:33]
	v_mov_b32_e32 v33, v31
	v_mov_b32_e32 v32, v30
	s_nop 0
	v_permlane16_swap_b32_e32 v33, v31
	v_permlane16_swap_b32_e32 v32, v30
	s_waitcnt lgkmcnt(0)
	v_pk_add_f32 v[30:31], v[30:31], v[32:33]
	s_nop 1
	v_add_f32_dpp v31, v31, v31 row_ror:8 row_mask:0xf bank_mask:0xf
	v_add_f32_dpp v30, v30, v30 row_ror:8 row_mask:0xf bank_mask:0xf
	s_waitcnt lgkmcnt(0)
	s_nop 1
	v_add_f32_dpp v31, v31, v31 row_ror:4 row_mask:0xf bank_mask:0xf
	v_add_f32_dpp v30, v30, v30 row_ror:4 row_mask:0xf bank_mask:0xf
	s_waitcnt lgkmcnt(0)
	s_nop 1
	v_add_f32_dpp v31, v31, v31 quad_perm:[2,3,0,1] row_mask:0xf bank_mask:0xf
	v_add_f32_dpp v30, v30, v30 quad_perm:[2,3,0,1] row_mask:0xf bank_mask:0xf
	s_waitcnt lgkmcnt(0)
	s_nop 1
	v_add_f32_dpp v31, v31, v31 quad_perm:[1,0,3,2] row_mask:0xf bank_mask:0xf
	v_add_f32_dpp v30, v30, v30 quad_perm:[1,0,3,2] row_mask:0xf bank_mask:0xf
	s_waitcnt lgkmcnt(0)
	s_nop 0
	v_pk_fma_f32 v[30:31], v[30:31], s[4:5], v[28:29] op_sel_hi:[1,0,0]
	s_nop 0
	v_mul_f32_e32 v32, 0x4b800000, v31
	v_cmp_gt_f32_e64 s[0:1], s77, v31
	v_cmp_gt_f32_e32 vcc, s77, v30
	s_nop 0
	v_cndmask_b32_e64 v31, v31, v32, s[0:1]
	v_rsq_f32_e32 v31, v31
	s_nop 0
	v_mul_f32_e32 v32, 0x45800000, v31
	v_cndmask_b32_e64 v31, v31, v32, s[0:1]
	v_mul_f32_e32 v31, 0x3dd53b94, v31
	v_mul_f32_e32 v25, v31, v25
	v_mul_f32_e32 v25, v41, v25
	ds_bpermute_b32 v32, v43, v25
	v_mul_f32_e32 v24, v31, v24
	v_mul_f32_e32 v24, v36, v24
	s_waitcnt lgkmcnt(0)
	v_mul_f32_e32 v32, v70, v32
	v_cndmask_b32_e64 v32, v32, -v32, s[38:39]
	v_fmac_f32_e32 v32, v10, v25
	v_bfe_u32 v25, v24, 16, 1
	v_add3_u32 v24, v24, v25, s11
	global_store_short_d16_hi v[18:19], v24, off offset:768
	v_mul_f32_e32 v24, v31, v71
	v_mul_f32_e32 v24, v37, v24
	v_bfe_u32 v25, v24, 16, 1
	v_add3_u32 v24, v24, v25, s11
	global_store_short_d16_hi v[18:19], v24, off offset:896
	v_bfe_u32 v24, v32, 16, 1
	v_add3_u32 v24, v32, v24, s11
	global_store_short_d16_hi v[18:19], v24, off offset:1024
	v_mul_f32_e32 v24, 0x4b800000, v30
	v_cndmask_b32_e32 v24, v30, v24, vcc
	v_rsq_f32_e32 v24, v24
	s_nop 0
	v_mul_f32_e32 v25, 0x45800000, v24
	v_cndmask_b32_e32 v24, v24, v25, vcc
	v_mul_f32_e32 v25, v24, v14
	v_mul_f32_e32 v25, v40, v25
	ds_bpermute_b32 v30, v43, v25
	v_mul_f32_e32 v22, v24, v22
	v_mul_f32_e32 v22, v38, v22
	s_waitcnt lgkmcnt(0)
; DI bf16_t f2bf(float f) { unsigned u = __float_as_uint(f); u += 0x7fffu + ((u >> 16) & 1u); return (bf16_t)(u >> 16); }
; DI float wave_sum(float v) { for (int o = 32; o; o >>= 1) v += __shfl_xor(v, o); return v; }
; DI void run_phase(const Params& p, int ph, unsigned char* smem, const int tid, const int rep) {
;     ...
;                 const float ang = (float)ps[u] * invf; float sn, cs; sincosf(ang, &sn, &cs);
;                 const float kr = krv[u];
; #pragma unroll
;                 for (int h = 0; h < 4; ++h) {
;                     { const float a0 = qa[u][h][0], a1 = qa[u][h][1], a2 = qa[u][h][2];
;                       const float rs = rsqrtf(wave_sum(a0 * a0 + a1 * a1 + a2 * a2) * (1.f / 192.f) + NEPS) * (0.07216878364870322f * LOG2E);
;                       const float y2 = a2 * rs * gq2; const float oth = __shfl_xor(y2, 32);
;                       const float rot = (lane < 32) ? (y2 * cs - oth * sn) : (y2 * cs + oth * sn);
;                       bf16_t* qo = mlaq + (size_t)t * 768 + h * 192; qo[lane] = f2bf(a0 * rs * gq0); qo[lane + 64] = f2bf(a1 * rs * gq1); qo[lane + 128] = f2bf(rot); }
;                     { const float a0 = ka[u][h][0], a1 = ka[u][h][1];
;                       const float rs = rsqrtf(wave_sum(a0 * a0 + a1 * a1 + kr * kr) * (1.f / 192.f) + NEPS);
;                       const float y2 = kr * rs * gk2; const float oth = __shfl_xor(y2, 32);
;                       const float rot = (lane < 32) ? (y2 * cs - oth * sn) : (y2 * cs + oth * sn);
;                       bf16_t* ko = mlak + (size_t)t * 768 + h * 192; ko[lane] = f2bf(a0 * rs * gk0); ko[lane + 64] = f2bf(a1 * rs * gk1); ko[lane + 128] = f2bf(rot); }
	v_mul_f32_e32 v30, v70, v30
	v_cndmask_b32_e64 v30, v30, -v30, s[38:39]
	v_fmac_f32_e32 v30, v10, v25
	v_bfe_u32 v25, v22, 16, 1
	v_add3_u32 v22, v22, v25, s11
	global_store_short_d16_hi v[20:21], v22, off offset:768
	v_mul_f32_e32 v22, v24, v23
	v_mul_f32_e32 v22, v39, v22
	v_bfe_u32 v23, v22, 16, 1
	v_add3_u32 v22, v22, v23, s11
	global_store_short_d16_hi v[20:21], v22, off offset:896
	v_bfe_u32 v22, v30, 16, 1
	v_add3_u32 v22, v30, v22, s11
	global_store_short_d16_hi v[20:21], v22, off offset:1024
	v_pk_mul_f32 v[22:23], v[16:17], v[16:17]
	s_nop 0
	v_pk_mov_b32 v[24:25], v[26:27], v[22:23] op_sel:[1,0]
	v_mov_b32_e32 v27, v23
	v_pk_fma_f32 v[24:25], v[12:13], v[12:13], v[24:25]
	s_nop 0
	v_pk_add_f32 v[22:23], v[26:27], v[24:25]
	v_mov_b32_e32 v25, v23
	v_mov_b32_e32 v24, v22
	s_nop 0
	v_permlane32_swap_b32_e32 v25, v23
	v_permlane32_swap_b32_e32 v24, v22
	s_waitcnt lgkmcnt(0)
	v_pk_add_f32 v[22:23], v[22:23], v[24:25]
	v_mov_b32_e32 v25, v23
	v_mov_b32_e32 v24, v22
	s_nop 0
	v_permlane16_swap_b32_e32 v25, v23
	v_permlane16_swap_b32_e32 v24, v22
	s_waitcnt lgkmcnt(0)
	v_pk_add_f32 v[22:23], v[22:23], v[24:25]
	s_nop 1
	v_add_f32_dpp v23, v23, v23 row_ror:8 row_mask:0xf bank_mask:0xf
	v_add_f32_dpp v22, v22, v22 row_ror:8 row_mask:0xf bank_mask:0xf
	s_waitcnt lgkmcnt(0)
	s_nop 1
	v_add_f32_dpp v23, v23, v23 row_ror:4 row_mask:0xf bank_mask:0xf
	v_add_f32_dpp v22, v22, v22 row_ror:4 row_mask:0xf bank_mask:0xf
	s_waitcnt lgkmcnt(0)
	s_nop 1
	v_add_f32_dpp v23, v23, v23 quad_perm:[2,3,0,1] row_mask:0xf bank_mask:0xf
	v_add_f32_dpp v22, v22, v22 quad_perm:[2,3,0,1] row_mask:0xf bank_mask:0xf
	s_waitcnt lgkmcnt(0)
	s_nop 1
	v_add_f32_dpp v23, v23, v23 quad_perm:[1,0,3,2] row_mask:0xf bank_mask:0xf
	v_add_f32_dpp v22, v22, v22 quad_perm:[1,0,3,2] row_mask:0xf bank_mask:0xf
	s_waitcnt lgkmcnt(0)
	s_nop 0
	v_pk_fma_f32 v[22:23], v[22:23], s[4:5], v[28:29] op_sel_hi:[1,0,0]
	s_nop 0
	v_mul_f32_e32 v24, 0x4b800000, v23
	v_cmp_gt_f32_e64 s[0:1], s77, v23
	v_cmp_gt_f32_e32 vcc, s77, v22
	s_nop 0
	v_cndmask_b32_e64 v23, v23, v24, s[0:1]
	v_rsq_f32_e32 v23, v23
	s_nop 0
	v_mul_f32_e32 v24, 0x45800000, v23
	v_cndmask_b32_e64 v23, v23, v24, s[0:1]
	v_mul_f32_e32 v23, 0x3dd53b94, v23
	v_mul_f32_e32 v17, v23, v17
	v_mul_f32_e32 v17, v41, v17
	ds_bpermute_b32 v24, v43, v17
	v_mul_f32_e32 v16, v23, v16
	v_mul_f32_e32 v16, v36, v16
	v_mul_f32_e32 v13, v23, v13
	v_mul_f32_e32 v13, v37, v13
	s_waitcnt lgkmcnt(0)
	v_mul_f32_e32 v24, v70, v24
	v_cndmask_b32_e64 v24, v24, -v24, s[38:39]
	v_fmac_f32_e32 v24, v10, v17
	v_bfe_u32 v17, v16, 16, 1
	v_add3_u32 v16, v16, v17, s11
	global_store_short_d16_hi v[18:19], v16, off offset:1152
	v_bfe_u32 v16, v13, 16, 1
	v_add3_u32 v13, v13, v16, s11
	global_store_short_d16_hi v[18:19], v13, off offset:1280
	v_bfe_u32 v13, v24, 16, 1
	v_add3_u32 v13, v24, v13, s11
	global_store_short_d16_hi v[18:19], v13, off offset:1408
	v_mul_f32_e32 v13, 0x4b800000, v22
	v_cndmask_b32_e32 v13, v22, v13, vcc
	v_rsq_f32_e32 v13, v13
	s_brev_b32 s0, 18
	v_mul_f32_e32 v16, 0x45800000, v13
	v_cndmask_b32_e32 v13, v13, v16, vcc
	v_mul_f32_e32 v14, v13, v14
	v_mul_f32_e32 v14, v40, v14
	ds_bpermute_b32 v16, v43, v14
	s_waitcnt lgkmcnt(0)
	v_mul_f32_e32 v16, v70, v16
	v_cndmask_b32_e64 v16, v16, -v16, s[38:39]
	v_fmac_f32_e32 v16, v10, v14
	v_mul_f32_e32 v10, v13, v15
	v_mul_f32_e32 v10, v38, v10
	v_bfe_u32 v14, v10, 16, 1
	v_add3_u32 v10, v10, v14, s11
	global_store_short_d16_hi v[20:21], v10, off offset:1152
	v_mul_f32_e32 v10, v13, v12
	v_mul_f32_e32 v10, v39, v10
	v_bfe_u32 v12, v10, 16, 1
	v_add3_u32 v10, v10, v12, s11
	global_store_short_d16_hi v[20:21], v10, off offset:1280
	v_bfe_u32 v10, v16, 16, 1
	v_add3_u32 v10, v16, v10, s11
	global_store_short_d16_hi v[20:21], v10, off offset:1408
	v_cvt_f32_i32_e32 v10, v11
	v_mul_f32_e32 v16, v42, v10
	v_and_b32_e32 v17, 0x7fffffff, v16
	v_cmp_nlt_f32_e64 s[0:1], |v16|, s0
	s_and_saveexec_b64 s[40:41], s[0:1]
	s_xor_b64 s[44:45], exec, s[40:41]
	s_cbranch_execz .LBB0_338
; DI void run_phase(const Params& p, int ph, unsigned char* smem, const int tid, const int rep) {
;     ...
;                 const float ang = (float)ps[u] * invf; float sn, cs; sincosf(ang, &sn, &cs);
	v_lshrrev_b32_e32 v10, 23, v17
	v_add_u32_e32 v10, 0xffffff88, v10
	v_cmp_lt_u32_e32 vcc, 63, v10
	s_mov_b32 s4, 0xfe5163ab
	v_mov_b32_e32 v13, v1
	v_cndmask_b32_e32 v11, 0, v195, vcc
	v_add_u32_e32 v10, v11, v10
	v_cmp_lt_u32_e64 s[0:1], 31, v10
	v_mov_b32_e32 v15, v1
	v_mov_b32_e32 v19, v1
	v_cndmask_b32_e64 v11, 0, v184, s[0:1]
	v_add_u32_e32 v10, v11, v10
	v_cmp_lt_u32_e64 s[40:41], 31, v10
	v_mov_b32_e32 v21, v1
	v_mov_b32_e32 v23, v1
	v_cndmask_b32_e64 v11, 0, v184, s[40:41]
	v_add_u32_e32 v26, v11, v10
	v_and_b32_e32 v10, 0x7fffff, v17
	v_or_b32_e32 v27, 0x800000, v10
	v_mad_u64_u32 v[10:11], s[42:43], v27, s4, 0
	v_mov_b32_e32 v12, v11
	s_mov_b32 s4, 0x3c439041
	v_mad_u64_u32 v[12:13], s[42:43], v27, s4, v[12:13]
	v_mov_b32_e32 v14, v13
	s_mov_b32 s4, 0xdb629599
	v_mad_u64_u32 v[14:15], s[42:43], v27, s4, v[14:15]
	v_mov_b32_e32 v18, v15
	s_mov_b32 s4, 0xf534ddc0
	v_mad_u64_u32 v[18:19], s[42:43], v27, s4, v[18:19]
	v_mov_b32_e32 v20, v19
	s_mov_b32 s4, 0xfc2757d1
	v_mad_u64_u32 v[20:21], s[42:43], v27, s4, v[20:21]
	v_mov_b32_e32 v22, v21
	s_mov_b32 s4, 0x4e441529
	v_mad_u64_u32 v[22:23], s[42:43], v27, s4, v[22:23]
	v_mov_b32_e32 v24, v23
	v_mov_b32_e32 v25, v1
	s_mov_b32 s4, 0xa2f9836e
	v_mad_u64_u32 v[24:25], s[42:43], v27, s4, v[24:25]
	v_cndmask_b32_e32 v11, v22, v18, vcc
	v_cndmask_b32_e32 v13, v24, v20, vcc
	v_cndmask_b32_e32 v19, v25, v22, vcc
	v_cndmask_b32_e64 v15, v13, v11, s[0:1]
	v_cndmask_b32_e64 v13, v19, v13, s[0:1]
	v_cndmask_b32_e32 v19, v20, v14, vcc
	v_cndmask_b32_e64 v11, v11, v19, s[0:1]
	v_cndmask_b32_e32 v12, v18, v12, vcc
	v_cndmask_b32_e64 v13, v13, v15, s[40:41]
	v_cndmask_b32_e64 v15, v15, v11, s[40:41]
	v_sub_u32_e32 v20, 32, v26
	v_cndmask_b32_e64 v18, v19, v12, s[0:1]
	v_alignbit_b32 v21, v13, v15, v20
	v_cmp_eq_u32_e64 s[42:43], 0, v26
	v_cndmask_b32_e64 v11, v11, v18, s[40:41]
	v_alignbit_b32 v19, v15, v11, v20
	v_cndmask_b32_e64 v13, v21, v13, s[42:43]
	v_cndmask_b32_e32 v10, v14, v10, vcc
	v_cndmask_b32_e64 v15, v19, v15, s[42:43]
	v_bfe_u32 v22, v13, 29, 1
	v_cndmask_b32_e64 v10, v12, v10, s[0:1]
	v_alignbit_b32 v19, v13, v15, 30
	v_sub_u32_e32 v23, 0, v22
	v_cndmask_b32_e64 v10, v18, v10, s[40:41]
	v_xor_b32_e32 v19, v19, v23
	v_alignbit_b32 v12, v11, v10, v20
	v_cndmask_b32_e64 v11, v12, v11, s[42:43]
	v_ffbh_u32_e32 v14, v19
	v_alignbit_b32 v12, v15, v11, 30
	v_min_u32_e32 v14, 32, v14
	v_alignbit_b32 v10, v11, v10, 30
	v_xor_b32_e32 v12, v12, v23
	v_sub_u32_e32 v15, 31, v14
	v_xor_b32_e32 v10, v10, v23
	v_alignbit_b32 v18, v19, v12, v15
	v_alignbit_b32 v10, v12, v10, v15
	v_alignbit_b32 v11, v18, v10, 9
	v_ffbh_u32_e32 v12, v11
	v_min_u32_e32 v12, 32, v12
	v_lshrrev_b32_e32 v21, 29, v13
	v_not_b32_e32 v15, v12
	v_alignbit_b32 v10, v11, v10, v15
	v_lshlrev_b32_e32 v11, 31, v21
	v_or_b32_e32 v15, 0x33000000, v11
	v_add_lshl_u32 v12, v12, v14, 23
	v_lshrrev_b32_e32 v10, 9, v10
	v_sub_u32_e32 v12, v15, v12
	v_or_b32_e32 v11, 0.5, v11
	v_lshlrev_b32_e32 v14, 23, v14
	v_or_b32_e32 v10, v12, v10
	v_lshrrev_b32_e32 v12, 9, v18
	v_sub_u32_e32 v11, v11, v14
	v_or_b32_e32 v11, v12, v11
	v_mul_f32_e32 v12, 0x3fc90fda, v11
	s_mov_b32 s0, 0x3fc90fda
	v_fma_f32 v14, v11, s0, -v12
	v_fmac_f32_e32 v14, 0x33a22168, v11
	v_fmac_f32_e32 v14, 0x3fc90fda, v10
	v_lshrrev_b32_e32 v10, 30, v13
	v_add_f32_e32 v24, v12, v14
	v_add_u32_e32 v25, v22, v10

; DI unsigned pk2(float lo, float hi) { const f32x2 v = {lo, hi}; return __builtin_bit_cast(unsigned, __builtin_convertvector(v, bf16v2_t)); }
; DI float wave_sum(float v) { for (int o = 32; o; o >>= 1) v += __shfl_xor(v, o); return v; }
; DI void run_phase(const Params& p, int ph, unsigned char* smem, const int tid, const int rep) {
;     ...
;           for (int t0 = (blockIdx.x * 8 + wv) * 4; t0 < TS; t0 += gridDim.x * 32) {
;               u32x2 vq[4]; unsigned vkv[4], vf[4][8];
; #pragma unroll
;               for (int u = 0; u < 4; ++u) { const bf16_t* pr = proj + (size_t)(t0 + u) * PLD; vq[u] = *(const u32x2*)(pr + 2048 + 4 * lane); vkv[u] = *(const unsigned*)(pr + 2304 + 2 * lane);
; #pragma unroll
;                   for (int hq = 0; hq < 8; ++hq) vf[u][hq] = *(const unsigned*)(pr + 3520 + hq * 128 + 2 * lane); }
; #pragma unroll
;               for (int u = 0; u < 4; ++u) { const int t = t0 + u; bf16_t* pr = proj + (size_t)t * PLD;
;                   { const u32x2 v = vq[u]; const float a0 = __uint_as_float(v[0] << 16), a1 = __uint_as_float(v[0] & 0xffff0000u), a2 = __uint_as_float(v[1] << 16), a3 = __uint_as_float(v[1] & 0xffff0000u);
;                     const float rs = rsqrtf(wave_sum(a0 * a0 + a1 * a1 + a2 * a2 + a3 * a3) * (1.f / 256.f) + NEPS);
;                     u32x2 o; o[0] = pk2(a0 * rs * ggq[0], a1 * rs * ggq[1]); o[1] = pk2(a2 * rs * ggq[2], a3 * rs * ggq[3]); *(u32x2*)(mlaa + (size_t)t * 384 + 4 * lane) = o; }
;                   { const unsigned v = vkv[u]; const float a0 = __uint_as_float(v << 16), a1 = __uint_as_float(v & 0xffff0000u);
;                     const float rs = rsqrtf(wave_sum(a0 * a0 + a1 * a1) * (1.f / 128.f) + NEPS);
;                     *(unsigned*)(mlaa + (size_t)t * 384 + 256 + 2 * lane) = pk2(a0 * rs * gkv0, a1 * rs * gkv1); }
; #pragma unroll
;                   for (int hq = 0; hq < 8; ++hq) { const unsigned v = vf[u][hq]; const float a0 = __uint_as_float(v << 16), a1 = __uint_as_float(v & 0xffff0000u);
;                     const float rs = rsqrtf(wave_sum(a0 * a0 + a1 * a1) * (1.f / 128.f) + NEPS) * ((hq < 4) ? 0.08838834764831845f * LOG2E : 1.f);
;                     *(unsigned*)(pr + 3520 + hq * 128 + 2 * lane) = pk2(a0 * rs * ((hq < 4) ? fq0 : fk0), a1 * rs * ((hq < 4) ? fq1 : fk1)); } } } }
.LBB0_372:
	v_mov_b64_e32 v[14:15], s[30:31]
	v_mad_i64_i32 v[16:17], s[0:1], v44, s3, v[14:15]
	v_lshl_add_u64 v[18:19], v[16:17], 0, v[0:1]
	v_add_co_u32_e32 v18, vcc, 0x1000, v18
	v_mov_b32_e32 v13, v1
	s_nop 0
	v_addc_co_u32_e32 v19, vcc, 0, v19, vcc
	v_lshl_add_u64 v[16:17], v[16:17], 0, v[12:13]
	global_load_dwordx2 v[18:19], v[18:19], off
	v_add_co_u32_e32 v36, vcc, 0x1000, v16
	v_add_u32_e32 v79, 1, v44
	s_nop 0
	v_addc_co_u32_e32 v37, vcc, 0, v17, vcc
	global_load_dword v89, v[36:37], off offset:512
	v_lshl_add_u64 v[34:35], v[16:17], 0, s[34:35]
	global_load_dword v88, v[36:37], off offset:2944
	global_load_dword v87, v[34:35], off offset:256
	global_load_dword v86, v[34:35], off offset:512
	global_load_dword v85, v[34:35], off offset:768
	global_load_dword v84, v[34:35], off offset:1024
	global_load_dword v83, v[34:35], off offset:1280
	global_load_dword v82, v[34:35], off offset:1536
	global_load_dword v81, v[34:35], off offset:1792
	v_mad_i64_i32 v[16:17], s[0:1], v79, s3, v[14:15]
	v_lshl_add_u64 v[20:21], v[16:17], 0, v[0:1]
	v_add_co_u32_e32 v20, vcc, s87, v20
	v_lshl_add_u64 v[16:17], v[16:17], 0, v[12:13]
	s_nop 0
	v_addc_co_u32_e32 v21, vcc, 0, v21, vcc
	v_add_co_u32_e32 v32, vcc, s87, v16
	v_add_u32_e32 v69, 2, v44
	s_nop 0
	v_addc_co_u32_e32 v33, vcc, 0, v17, vcc
	v_lshl_add_u64 v[28:29], v[16:17], 0, s[34:35]
	v_mad_i64_i32 v[16:17], s[0:1], v69, s3, v[14:15]
	global_load_dwordx2 v[40:41], v[20:21], off
	global_load_dword v80, v[32:33], off offset:512
	v_lshl_add_u64 v[20:21], v[16:17], 0, v[0:1]
	v_add_co_u32_e32 v20, vcc, s87, v20
	v_lshl_add_u64 v[16:17], v[16:17], 0, v[12:13]
	s_nop 0
	v_addc_co_u32_e32 v21, vcc, 0, v21, vcc
	v_add_co_u32_e32 v26, vcc, s87, v16
	v_add_u32_e32 v59, 3, v44
	s_nop 0
	v_addc_co_u32_e32 v27, vcc, 0, v17, vcc
	v_mad_i64_i32 v[14:15], s[0:1], v59, s3, v[14:15]
	global_load_dword v78, v[32:33], off offset:2944
	global_load_dword v77, v[28:29], off offset:256
	global_load_dword v76, v[28:29], off offset:512
	global_load_dword v75, v[28:29], off offset:768
	global_load_dword v74, v[28:29], off offset:1024
	global_load_dword v73, v[28:29], off offset:1280
	global_load_dword v72, v[28:29], off offset:1536
	global_load_dword v71, v[28:29], off offset:1792
	global_load_dwordx2 v[30:31], v[20:21], off
	global_load_dword v70, v[26:27], off offset:512
	v_lshl_add_u64 v[22:23], v[16:17], 0, s[34:35]
	v_lshl_add_u64 v[16:17], v[14:15], 0, v[0:1]
	v_add_co_u32_e32 v16, vcc, s87, v16
	v_lshl_add_u64 v[14:15], v[14:15], 0, v[12:13]
	s_nop 0
	v_addc_co_u32_e32 v17, vcc, 0, v17, vcc
	global_load_dword v68, v[26:27], off offset:2944
	global_load_dword v67, v[22:23], off offset:256
	global_load_dword v66, v[22:23], off offset:512
	global_load_dword v65, v[22:23], off offset:768
	global_load_dword v64, v[22:23], off offset:1024
	global_load_dword v63, v[22:23], off offset:1280
	global_load_dword v62, v[22:23], off offset:1536
	global_load_dword v61, v[22:23], off offset:1792
	global_load_dwordx2 v[24:25], v[16:17], off
	v_add_co_u32_e32 v16, vcc, s87, v14
	s_waitcnt vmcnt(0)
	v_and_b32_e32 v43, 0xffff0000, v18
	v_and_b32_e32 v21, 0xffff0000, v19
	v_and_b32_e32 v20, s0, v18
	v_lshlrev_b32_e32 v42, 16, v18
	v_mul_f32_e32 v18, v43, v43
	v_lshlrev_b32_e32 v38, 16, v19
	v_mov_b32_e32 v39, v21
	v_pk_fma_f32 v[18:19], v[42:43], v[42:43], v[18:19] op_sel_hi:[1,1,0]
	v_lshlrev_b32_e32 v96, 16, v89
	v_and_b32_e32 v97, 0xffff0000, v89
	v_pk_mul_f32 v[90:91], v[20:21], v[20:21]
	v_pk_fma_f32 v[18:19], v[38:39], v[38:39], v[18:19]
	v_pk_mul_f32 v[98:99], v[96:97], v[96:97]
	v_mov_b64_e32 v[20:21], s[12:13]
	v_mov_b32_e32 v90, v98
	v_pk_mov_b32 v[18:19], v[98:99], v[18:19] op_sel:[1,0]
	v_mad_i64_i32 v[92:93], s[0:1], v44, s22, v[20:21]
	v_pk_add_f32 v[18:19], v[90:91], v[18:19]
	v_mov_b32_e32 v91, v19
	v_mov_b32_e32 v90, v18
	s_nop 0
	v_permlane32_swap_b32_e32 v91, v19
	v_permlane32_swap_b32_e32 v90, v18
	v_addc_co_u32_e32 v17, vcc, 0, v15, vcc
	v_lshl_add_u64 v[94:95], v[92:93], 0, v[0:1]
	global_load_dword v60, v[16:17], off offset:512
	s_waitcnt lgkmcnt(0)
	v_pk_add_f32 v[18:19], v[18:19], v[90:91]
	v_mov_b32_e32 v91, v19
	v_mov_b32_e32 v90, v18
	s_nop 0
	v_permlane16_swap_b32_e32 v91, v19
	v_permlane16_swap_b32_e32 v90, v18
	v_lshl_add_u64 v[14:15], v[14:15], 0, s[34:35]
	global_load_dword v58, v[16:17], off offset:2944
	global_load_dword v57, v[14:15], off offset:256
	global_load_dword v56, v[14:15], off offset:512
	global_load_dword v55, v[14:15], off offset:768
	global_load_dword v54, v[14:15], off offset:1024
	global_load_dword v53, v[14:15], off offset:1280
	global_load_dword v52, v[14:15], off offset:1536
	global_load_dword v51, v[14:15], off offset:1792
	v_add_u32_e32 v44, s4, v44
	s_waitcnt lgkmcnt(0)
	v_pk_add_f32 v[18:19], v[18:19], v[90:91]
	s_nop 1
	v_add_f32_dpp v19, v19, v19 row_ror:8 row_mask:0xf bank_mask:0xf
	v_add_f32_dpp v18, v18, v18 row_ror:8 row_mask:0xf bank_mask:0xf
	s_waitcnt lgkmcnt(0)
	s_nop 1
	v_add_f32_dpp v19, v19, v19 row_ror:4 row_mask:0xf bank_mask:0xf
	v_add_f32_dpp v18, v18, v18 row_ror:4 row_mask:0xf bank_mask:0xf
	s_waitcnt lgkmcnt(0)
	s_nop 1
	v_add_f32_dpp v19, v19, v19 quad_perm:[2,3,0,1] row_mask:0xf bank_mask:0xf
	v_add_f32_dpp v18, v18, v18 quad_perm:[2,3,0,1] row_mask:0xf bank_mask:0xf
	s_waitcnt lgkmcnt(0)
	s_nop 1
	v_add_f32_dpp v91, v19, v19 quad_perm:[1,0,3,2] row_mask:0xf bank_mask:0xf
	v_add_f32_dpp v90, v18, v18 quad_perm:[1,0,3,2] row_mask:0xf bank_mask:0xf
	s_waitcnt lgkmcnt(0)
; DI unsigned pk2(float lo, float hi) { const f32x2 v = {lo, hi}; return __builtin_bit_cast(unsigned, __builtin_convertvector(v, bf16v2_t)); }
; DI float wave_sum(float v) { for (int o = 32; o; o >>= 1) v += __shfl_xor(v, o); return v; }
; DI void run_phase(const Params& p, int ph, unsigned char* smem, const int tid, const int rep) {
;     ...
;               for (int u = 0; u < 4; ++u) { const bf16_t* pr = proj + (size_t)(t0 + u) * PLD; vq[u] = *(const u32x2*)(pr + 2048 + 4 * lane); vkv[u] = *(const unsigned*)(pr + 2304 + 2 * lane);
; #pragma unroll
;                   for (int hq = 0; hq < 8; ++hq) vf[u][hq] = *(const unsigned*)(pr + 3520 + hq * 128 + 2 * lane); }
; #pragma unroll
;               for (int u = 0; u < 4; ++u) { const int t = t0 + u; bf16_t* pr = proj + (size_t)t * PLD;
;                   { const u32x2 v = vq[u]; const float a0 = __uint_as_float(v[0] << 16), a1 = __uint_as_float(v[0] & 0xffff0000u), a2 = __uint_as_float(v[1] << 16), a3 = __uint_as_float(v[1] & 0xffff0000u);
;                     const float rs = rsqrtf(wave_sum(a0 * a0 + a1 * a1 + a2 * a2 + a3 * a3) * (1.f / 256.f) + NEPS);
;                     u32x2 o; o[0] = pk2(a0 * rs * ggq[0], a1 * rs * ggq[1]); o[1] = pk2(a2 * rs * ggq[2], a3 * rs * ggq[3]); *(u32x2*)(mlaa + (size_t)t * 384 + 4 * lane) = o; }
;                   { const unsigned v = vkv[u]; const float a0 = __uint_as_float(v << 16), a1 = __uint_as_float(v & 0xffff0000u);
;                     const float rs = rsqrtf(wave_sum(a0 * a0 + a1 * a1) * (1.f / 128.f) + NEPS);
;                     *(unsigned*)(mlaa + (size_t)t * 384 + 256 + 2 * lane) = pk2(a0 * rs * gkv0, a1 * rs * gkv1); }
; #pragma unroll
;                   for (int hq = 0; hq < 8; ++hq) { const unsigned v = vf[u][hq]; const float a0 = __uint_as_float(v << 16), a1 = __uint_as_float(v & 0xffff0000u);
;                     const float rs = rsqrtf(wave_sum(a0 * a0 + a1 * a1) * (1.f / 128.f) + NEPS) * ((hq < 4) ? 0.08838834764831845f * LOG2E : 1.f);
;                     *(unsigned*)(pr + 3520 + hq * 128 + 2 * lane) = pk2(a0 * rs * ((hq < 4) ? fq0 : fk0), a1 * rs * ((hq < 4) ? fq1 : fk1)); } } } }
	v_mov_b64_e32 v[18:19], s[72:73]
	v_pk_fma_f32 v[90:91], v[90:91], s[96:97], v[18:19] op_sel_hi:[1,1,0]
	s_nop 0
	v_mul_f32_e32 v89, 0x4b800000, v91
	v_cmp_gt_f32_e64 s[0:1], s77, v91
	v_cmp_gt_f32_e32 vcc, s77, v90
	s_nop 0
	v_cndmask_b32_e64 v89, v91, v89, s[0:1]
	v_rsq_f32_e32 v89, v89
	s_nop 0
	v_mul_f32_e32 v91, 0x45800000, v89
	v_cndmask_b32_e64 v98, v89, v91, s[0:1]
	v_pk_mul_f32 v[42:43], v[98:99], v[42:43] op_sel_hi:[0,1]
	v_pk_mul_f32 v[38:39], v[98:99], v[38:39] op_sel_hi:[0,1]
	v_pk_mul_f32 v[42:43], v[2:3], v[42:43]
	v_pk_mul_f32 v[38:39], v[4:5], v[38:39]
	v_cvt_pk_bf16_f32 v42, v42, v43
	v_cvt_pk_bf16_f32 v43, v38, v39
	v_mul_f32_e32 v38, 0x4b800000, v90
	v_cndmask_b32_e32 v38, v90, v38, vcc
	v_rsq_f32_e32 v38, v38
	global_store_dwordx2 v[94:95], v[42:43], off
	v_and_b32_e32 v89, 0xffff0000, v87
	v_mul_f32_e32 v39, 0x45800000, v38
	v_cndmask_b32_e32 v38, v38, v39, vcc
	v_pk_mul_f32 v[38:39], v[38:39], v[96:97] op_sel_hi:[0,1]
	v_pk_mul_f32 v[38:39], v[6:7], v[38:39]
	s_nop 0
	v_cvt_pk_bf16_f32 v42, v38, v39
	v_lshl_add_u64 v[38:39], v[92:93], 0, v[12:13]
	global_store_dword v[38:39], v42, off offset:512
	v_lshlrev_b32_e32 v38, 16, v88
	v_and_b32_e32 v39, 0xffff0000, v88
	v_lshlrev_b32_e32 v88, 16, v87
	v_pk_mul_f32 v[42:43], v[38:39], v[38:39]
	v_pk_mul_f32 v[90:91], v[88:89], v[88:89]
	v_mov_b32_e32 v93, v42
	v_mov_b32_e32 v92, v90
	v_mov_b32_e32 v42, v91
	v_pk_add_f32 v[42:43], v[92:93], v[42:43]
	v_mov_b32_e32 v91, v43
	v_mov_b32_e32 v90, v42
	s_nop 0
	v_permlane32_swap_b32_e32 v91, v43
	v_permlane32_swap_b32_e32 v90, v42
	s_waitcnt lgkmcnt(0)
	v_pk_add_f32 v[42:43], v[42:43], v[90:91]
	v_mov_b32_e32 v91, v43
	v_mov_b32_e32 v90, v42
	s_nop 0
	v_permlane16_swap_b32_e32 v91, v43
	v_permlane16_swap_b32_e32 v90, v42
	s_waitcnt lgkmcnt(0)
	v_pk_add_f32 v[42:43], v[42:43], v[90:91]
	s_nop 1
	v_add_f32_dpp v43, v43, v43 row_ror:8 row_mask:0xf bank_mask:0xf
	v_add_f32_dpp v42, v42, v42 row_ror:8 row_mask:0xf bank_mask:0xf
	s_waitcnt lgkmcnt(0)
	s_nop 1
	v_add_f32_dpp v43, v43, v43 row_ror:4 row_mask:0xf bank_mask:0xf
	v_add_f32_dpp v42, v42, v42 row_ror:4 row_mask:0xf bank_mask:0xf
	s_waitcnt lgkmcnt(0)
	s_nop 1
	v_add_f32_dpp v43, v43, v43 quad_perm:[2,3,0,1] row_mask:0xf bank_mask:0xf
	v_add_f32_dpp v42, v42, v42 quad_perm:[2,3,0,1] row_mask:0xf bank_mask:0xf
	s_waitcnt lgkmcnt(0)
	s_nop 1
	v_add_f32_dpp v43, v43, v43 quad_perm:[1,0,3,2] row_mask:0xf bank_mask:0xf
	v_add_f32_dpp v42, v42, v42 quad_perm:[1,0,3,2] row_mask:0xf bank_mask:0xf
	s_waitcnt lgkmcnt(0)
	s_nop 0
	v_pk_fma_f32 v[42:43], v[42:43], s[96:97], v[18:19] op_sel_hi:[1,0,0]
	s_nop 0
	v_mul_f32_e32 v87, 0x4b800000, v43
	v_cmp_gt_f32_e64 s[0:1], s77, v43
	v_cmp_gt_f32_e32 vcc, s77, v42
	s_nop 0
	v_cndmask_b32_e64 v43, v43, v87, s[0:1]
	v_rsq_f32_e32 v43, v43
	s_nop 0
	v_mul_f32_e32 v87, 0x45800000, v43
	v_cndmask_b32_e64 v43, v43, v87, s[0:1]
	v_mul_f32_e32 v90, 0x3e0293ee, v43
	v_pk_mul_f32 v[38:39], v[90:91], v[38:39] op_sel_hi:[0,1]
	v_pk_mul_f32 v[38:39], v[8:9], v[38:39]
	v_and_b32_e32 v43, 0xffff0000, v85
	v_cvt_pk_bf16_f32 v38, v38, v39
	global_store_dword v[36:37], v38, off offset:2944
	v_mul_f32_e32 v36, 0x4b800000, v42
	v_cndmask_b32_e32 v36, v42, v36, vcc
	v_rsq_f32_e32 v36, v36
	v_lshlrev_b32_e32 v42, 16, v85
	v_mul_f32_e32 v37, 0x45800000, v36
	v_cndmask_b32_e32 v36, v36, v37, vcc
	v_mul_f32_e32 v36, 0x3e0293ee, v36
	v_pk_mul_f32 v[36:37], v[36:37], v[88:89] op_sel_hi:[0,1]
	v_pk_mul_f32 v[36:37], v[8:9], v[36:37]
	s_nop 0
	v_cvt_pk_bf16_f32 v36, v36, v37
	global_store_dword v[34:35], v36, off offset:256
	v_lshlrev_b32_e32 v36, 16, v86
	v_and_b32_e32 v37, 0xffff0000, v86
	v_pk_mul_f32 v[38:39], v[36:37], v[36:37]
	v_pk_mul_f32 v[86:87], v[42:43], v[42:43]
	v_mov_b32_e32 v89, v38
	v_mov_b32_e32 v88, v86
	v_mov_b32_e32 v38, v87
	v_pk_add_f32 v[38:39], v[88:89], v[38:39]
	v_mov_b32_e32 v87, v39
	v_mov_b32_e32 v86, v38
	s_nop 0
	v_permlane32_swap_b32_e32 v87, v39
	v_permlane32_swap_b32_e32 v86, v38
	s_waitcnt lgkmcnt(0)
	v_pk_add_f32 v[38:39], v[38:39], v[86:87]
	v_mov_b32_e32 v87, v39
	v_mov_b32_e32 v86, v38
	s_nop 0
	v_permlane16_swap_b32_e32 v87, v39
	v_permlane16_swap_b32_e32 v86, v38
	s_waitcnt lgkmcnt(0)
	v_pk_add_f32 v[38:39], v[38:39], v[86:87]
	s_nop 1
	v_add_f32_dpp v39, v39, v39 row_ror:8 row_mask:0xf bank_mask:0xf
	v_add_f32_dpp v38, v38, v38 row_ror:8 row_mask:0xf bank_mask:0xf
	s_waitcnt lgkmcnt(0)
	s_nop 1
	v_add_f32_dpp v39, v39, v39 row_ror:4 row_mask:0xf bank_mask:0xf
	v_add_f32_dpp v38, v38, v38 row_ror:4 row_mask:0xf bank_mask:0xf
	s_waitcnt lgkmcnt(0)
	s_nop 1
	v_add_f32_dpp v39, v39, v39 quad_perm:[2,3,0,1] row_mask:0xf bank_mask:0xf
	v_add_f32_dpp v38, v38, v38 quad_perm:[2,3,0,1] row_mask:0xf bank_mask:0xf
	s_waitcnt lgkmcnt(0)
	s_nop 1
	v_add_f32_dpp v39, v39, v39 quad_perm:[1,0,3,2] row_mask:0xf bank_mask:0xf
	v_add_f32_dpp v38, v38, v38 quad_perm:[1,0,3,2] row_mask:0xf bank_mask:0xf
	s_waitcnt lgkmcnt(0)
; DI unsigned pk2(float lo, float hi) { const f32x2 v = {lo, hi}; return __builtin_bit_cast(unsigned, __builtin_convertvector(v, bf16v2_t)); }
; DI float wave_sum(float v) { for (int o = 32; o; o >>= 1) v += __shfl_xor(v, o); return v; }
; DI void run_phase(const Params& p, int ph, unsigned char* smem, const int tid, const int rep) {
;     ...
;                   for (int hq = 0; hq < 8; ++hq) { const unsigned v = vf[u][hq]; const float a0 = __uint_as_float(v << 16), a1 = __uint_as_float(v & 0xffff0000u);
;                     const float rs = rsqrtf(wave_sum(a0 * a0 + a1 * a1) * (1.f / 128.f) + NEPS) * ((hq < 4) ? 0.08838834764831845f * LOG2E : 1.f);
;                     *(unsigned*)(pr + 3520 + hq * 128 + 2 * lane) = pk2(a0 * rs * ((hq < 4) ? fq0 : fk0), a1 * rs * ((hq < 4) ? fq1 : fk1)); } } } }
	s_nop 0
	v_pk_fma_f32 v[38:39], v[38:39], s[96:97], v[18:19] op_sel_hi:[1,0,0]
	s_nop 0
	v_mul_f32_e32 v85, 0x4b800000, v39
	v_cmp_gt_f32_e64 s[0:1], s77, v39
	v_cmp_gt_f32_e32 vcc, s77, v38
	s_nop 0
	v_cndmask_b32_e64 v39, v39, v85, s[0:1]
	v_rsq_f32_e32 v39, v39
	s_nop 0
	v_mul_f32_e32 v85, 0x45800000, v39
	v_cndmask_b32_e64 v39, v39, v85, s[0:1]
	v_mul_f32_e32 v86, 0x3e0293ee, v39
	v_pk_mul_f32 v[36:37], v[86:87], v[36:37] op_sel_hi:[0,1]
	v_pk_mul_f32 v[36:37], v[8:9], v[36:37]
	s_nop 0
	v_cvt_pk_bf16_f32 v36, v36, v37
	global_store_dword v[34:35], v36, off offset:512
	v_mul_f32_e32 v36, 0x4b800000, v38
	v_cndmask_b32_e32 v36, v38, v36, vcc
	v_rsq_f32_e32 v36, v36
	s_nop 0
	v_mul_f32_e32 v37, 0x45800000, v36
	v_cndmask_b32_e32 v36, v36, v37, vcc
	v_mul_f32_e32 v36, 0x3e0293ee, v36
	v_pk_mul_f32 v[36:37], v[36:37], v[42:43] op_sel_hi:[0,1]
	v_pk_mul_f32 v[36:37], v[8:9], v[36:37]
	v_lshlrev_b32_e32 v42, 16, v83
	v_cvt_pk_bf16_f32 v36, v36, v37
	global_store_dword v[34:35], v36, off offset:768
	v_lshlrev_b32_e32 v36, 16, v84
	v_and_b32_e32 v37, 0xffff0000, v84
	v_and_b32_e32 v43, 0xffff0000, v83
	v_pk_mul_f32 v[38:39], v[36:37], v[36:37]
	v_pk_mul_f32 v[84:85], v[42:43], v[42:43]
	v_mov_b32_e32 v87, v38
	v_mov_b32_e32 v86, v84
	v_mov_b32_e32 v38, v85
	v_pk_add_f32 v[38:39], v[86:87], v[38:39]
	v_mov_b32_e32 v85, v39
	v_mov_b32_e32 v84, v38
	s_nop 0
	v_permlane32_swap_b32_e32 v85, v39
	v_permlane32_swap_b32_e32 v84, v38
	s_waitcnt lgkmcnt(0)
	v_pk_add_f32 v[38:39], v[38:39], v[84:85]
	v_mov_b32_e32 v85, v39
	v_mov_b32_e32 v84, v38
	s_nop 0
	v_permlane16_swap_b32_e32 v85, v39
	v_permlane16_swap_b32_e32 v84, v38
	s_waitcnt lgkmcnt(0)
	v_pk_add_f32 v[38:39], v[38:39], v[84:85]
	s_nop 1
	v_add_f32_dpp v39, v39, v39 row_ror:8 row_mask:0xf bank_mask:0xf
	v_add_f32_dpp v38, v38, v38 row_ror:8 row_mask:0xf bank_mask:0xf
	s_waitcnt lgkmcnt(0)
	s_nop 1
	v_add_f32_dpp v39, v39, v39 row_ror:4 row_mask:0xf bank_mask:0xf
	v_add_f32_dpp v38, v38, v38 row_ror:4 row_mask:0xf bank_mask:0xf
	s_waitcnt lgkmcnt(0)
	s_nop 1
	v_add_f32_dpp v39, v39, v39 quad_perm:[2,3,0,1] row_mask:0xf bank_mask:0xf
	v_add_f32_dpp v38, v38, v38 quad_perm:[2,3,0,1] row_mask:0xf bank_mask:0xf
	s_waitcnt lgkmcnt(0)
	s_nop 1
	v_add_f32_dpp v39, v39, v39 quad_perm:[1,0,3,2] row_mask:0xf bank_mask:0xf
	v_add_f32_dpp v38, v38, v38 quad_perm:[1,0,3,2] row_mask:0xf bank_mask:0xf
	s_waitcnt lgkmcnt(0)
	s_nop 0
	v_pk_fma_f32 v[38:39], v[38:39], s[96:97], v[18:19] op_sel_hi:[1,0,0]
	s_nop 0
	v_mul_f32_e32 v83, 0x4b800000, v39
	v_cmp_gt_f32_e64 s[0:1], s77, v39
	v_cmp_gt_f32_e32 vcc, s77, v38
	s_nop 0
	v_cndmask_b32_e64 v39, v39, v83, s[0:1]
	v_rsq_f32_e32 v39, v39
	s_nop 0
	v_mul_f32_e32 v83, 0x45800000, v39
	v_cndmask_b32_e64 v84, v39, v83, s[0:1]
	v_pk_mul_f32 v[36:37], v[84:85], v[36:37] op_sel_hi:[0,1]
	v_pk_mul_f32 v[36:37], v[10:11], v[36:37]
	s_nop 0
	v_cvt_pk_bf16_f32 v36, v36, v37
	global_store_dword v[34:35], v36, off offset:1024
	v_mul_f32_e32 v36, 0x4b800000, v38
	v_cndmask_b32_e32 v36, v38, v36, vcc
	v_rsq_f32_e32 v36, v36
	s_nop 0
	v_mul_f32_e32 v37, 0x45800000, v36
	v_cndmask_b32_e32 v36, v36, v37, vcc
	v_pk_mul_f32 v[36:37], v[36:37], v[42:43] op_sel_hi:[0,1]
	v_pk_mul_f32 v[36:37], v[10:11], v[36:37]
	v_lshlrev_b32_e32 v42, 16, v81
	v_cvt_pk_bf16_f32 v36, v36, v37
	global_store_dword v[34:35], v36, off offset:1280
	v_lshlrev_b32_e32 v36, 16, v82
	v_and_b32_e32 v37, 0xffff0000, v82
	v_and_b32_e32 v43, 0xffff0000, v81
	v_pk_mul_f32 v[38:39], v[36:37], v[36:37]
	v_pk_mul_f32 v[82:83], v[42:43], v[42:43]
	v_mov_b32_e32 v85, v38
	v_mov_b32_e32 v84, v82
	v_mov_b32_e32 v38, v83
	v_pk_add_f32 v[38:39], v[84:85], v[38:39]
	v_mov_b32_e32 v83, v39
	v_mov_b32_e32 v82, v38
	s_nop 0
	v_permlane32_swap_b32_e32 v83, v39
	v_permlane32_swap_b32_e32 v82, v38
	v_lshlrev_b32_e32 v84, 16, v80
	v_and_b32_e32 v85, 0xffff0000, v80
	s_waitcnt lgkmcnt(0)
	v_pk_add_f32 v[38:39], v[38:39], v[82:83]
	v_mov_b32_e32 v83, v39
	v_mov_b32_e32 v82, v38
	s_nop 0
	v_permlane16_swap_b32_e32 v83, v39
	v_permlane16_swap_b32_e32 v82, v38
	s_waitcnt lgkmcnt(0)
	v_pk_add_f32 v[38:39], v[38:39], v[82:83]
	s_nop 1
	v_add_f32_dpp v39, v39, v39 row_ror:8 row_mask:0xf bank_mask:0xf
	v_add_f32_dpp v38, v38, v38 row_ror:8 row_mask:0xf bank_mask:0xf
	s_waitcnt lgkmcnt(0)
	s_nop 1
	v_add_f32_dpp v39, v39, v39 row_ror:4 row_mask:0xf bank_mask:0xf
	v_add_f32_dpp v38, v38, v38 row_ror:4 row_mask:0xf bank_mask:0xf
	s_waitcnt lgkmcnt(0)
	s_nop 1
	v_add_f32_dpp v39, v39, v39 quad_perm:[2,3,0,1] row_mask:0xf bank_mask:0xf
	v_add_f32_dpp v38, v38, v38 quad_perm:[2,3,0,1] row_mask:0xf bank_mask:0xf
	s_waitcnt lgkmcnt(0)
	s_nop 1
	v_add_f32_dpp v39, v39, v39 quad_perm:[1,0,3,2] row_mask:0xf bank_mask:0xf
	v_add_f32_dpp v38, v38, v38 quad_perm:[1,0,3,2] row_mask:0xf bank_mask:0xf
	s_waitcnt lgkmcnt(0)
; DI unsigned pk2(float lo, float hi) { const f32x2 v = {lo, hi}; return __builtin_bit_cast(unsigned, __builtin_convertvector(v, bf16v2_t)); }
; DI float wave_sum(float v) { for (int o = 32; o; o >>= 1) v += __shfl_xor(v, o); return v; }
; DI void run_phase(const Params& p, int ph, unsigned char* smem, const int tid, const int rep) {
;     ...
;                   { const u32x2 v = vq[u]; const float a0 = __uint_as_float(v[0] << 16), a1 = __uint_as_float(v[0] & 0xffff0000u), a2 = __uint_as_float(v[1] << 16), a3 = __uint_as_float(v[1] & 0xffff0000u);
;                     const float rs = rsqrtf(wave_sum(a0 * a0 + a1 * a1 + a2 * a2 + a3 * a3) * (1.f / 256.f) + NEPS);
;                     u32x2 o; o[0] = pk2(a0 * rs * ggq[0], a1 * rs * ggq[1]); o[1] = pk2(a2 * rs * ggq[2], a3 * rs * ggq[3]); *(u32x2*)(mlaa + (size_t)t * 384 + 4 * lane) = o; }
;                   { const unsigned v = vkv[u]; const float a0 = __uint_as_float(v << 16), a1 = __uint_as_float(v & 0xffff0000u);
;                     const float rs = rsqrtf(wave_sum(a0 * a0 + a1 * a1) * (1.f / 128.f) + NEPS);
;                     *(unsigned*)(mlaa + (size_t)t * 384 + 256 + 2 * lane) = pk2(a0 * rs * gkv0, a1 * rs * gkv1); }
; #pragma unroll
;                   for (int hq = 0; hq < 8; ++hq) { const unsigned v = vf[u][hq]; const float a0 = __uint_as_float(v << 16), a1 = __uint_as_float(v & 0xffff0000u);
;                     const float rs = rsqrtf(wave_sum(a0 * a0 + a1 * a1) * (1.f / 128.f) + NEPS) * ((hq < 4) ? 0.08838834764831845f * LOG2E : 1.f);
;                     *(unsigned*)(pr + 3520 + hq * 128 + 2 * lane) = pk2(a0 * rs * ((hq < 4) ? fq0 : fk0), a1 * rs * ((hq < 4) ? fq1 : fk1)); } } } }
	s_nop 0
	v_pk_fma_f32 v[38:39], v[38:39], s[96:97], v[18:19] op_sel_hi:[1,0,0]
	s_nop 0
	v_mul_f32_e32 v81, 0x4b800000, v39
	v_cmp_gt_f32_e64 s[0:1], s77, v39
	v_cmp_gt_f32_e32 vcc, s77, v38
	s_nop 0
	v_cndmask_b32_e64 v39, v39, v81, s[0:1]
	v_rsq_f32_e32 v39, v39
	s_nop 0
	v_mul_f32_e32 v81, 0x45800000, v39
	v_cndmask_b32_e64 v82, v39, v81, s[0:1]
	v_pk_mul_f32 v[36:37], v[82:83], v[36:37] op_sel_hi:[0,1]
	v_pk_mul_f32 v[36:37], v[10:11], v[36:37]
	v_pk_mul_f32 v[80:81], v[84:85], v[84:85]
	v_cvt_pk_bf16_f32 v36, v36, v37
	global_store_dword v[34:35], v36, off offset:1536
	v_mul_f32_e32 v36, 0x4b800000, v38
	v_cndmask_b32_e32 v36, v38, v36, vcc
	v_rsq_f32_e32 v36, v36
	s_nop 0
	v_mul_f32_e32 v37, 0x45800000, v36
	v_cndmask_b32_e32 v36, v36, v37, vcc
	v_pk_mul_f32 v[36:37], v[36:37], v[42:43] op_sel_hi:[0,1]
	v_pk_mul_f32 v[36:37], v[10:11], v[36:37]
	s_nop 0
	v_cvt_pk_bf16_f32 v36, v36, v37
	global_store_dword v[34:35], v36, off offset:1792
	v_and_b32_e32 v37, 0xffff0000, v41
	v_and_b32_e32 v36, s0, v40
	v_mov_b32_e32 v35, v37
	v_pk_mul_f32 v[38:39], v[36:37], v[36:37]
	v_and_b32_e32 v37, 0xffff0000, v40
	v_lshlrev_b32_e32 v36, 16, v40
	v_mul_f32_e32 v38, v37, v37
	v_lshlrev_b32_e32 v34, 16, v41
	v_pk_fma_f32 v[40:41], v[36:37], v[36:37], v[38:39] op_sel_hi:[1,1,0]
	v_mov_b32_e32 v38, v80
	v_pk_fma_f32 v[40:41], v[34:35], v[34:35], v[40:41]
	v_mad_i64_i32 v[42:43], s[0:1], v79, s22, v[20:21]
	v_pk_mov_b32 v[40:41], v[80:81], v[40:41] op_sel:[1,0]
	v_lshl_add_u64 v[82:83], v[42:43], 0, v[0:1]
	v_pk_add_f32 v[38:39], v[38:39], v[40:41]
	v_mov_b32_e32 v41, v39
	v_mov_b32_e32 v40, v38
	s_nop 0
	v_permlane32_swap_b32_e32 v41, v39
	v_permlane32_swap_b32_e32 v40, v38
	s_waitcnt lgkmcnt(0)
	v_pk_add_f32 v[38:39], v[38:39], v[40:41]
	v_mov_b32_e32 v41, v39
	v_mov_b32_e32 v40, v38
	s_nop 0
	v_permlane16_swap_b32_e32 v41, v39
	v_permlane16_swap_b32_e32 v40, v38
	s_waitcnt lgkmcnt(0)
	v_pk_add_f32 v[38:39], v[38:39], v[40:41]
	s_nop 1
	v_add_f32_dpp v39, v39, v39 row_ror:8 row_mask:0xf bank_mask:0xf
	v_add_f32_dpp v38, v38, v38 row_ror:8 row_mask:0xf bank_mask:0xf
	s_waitcnt lgkmcnt(0)
	s_nop 1
	v_add_f32_dpp v39, v39, v39 row_ror:4 row_mask:0xf bank_mask:0xf
	v_add_f32_dpp v38, v38, v38 row_ror:4 row_mask:0xf bank_mask:0xf
	s_waitcnt lgkmcnt(0)
	s_nop 1
	v_add_f32_dpp v39, v39, v39 quad_perm:[2,3,0,1] row_mask:0xf bank_mask:0xf
	v_add_f32_dpp v38, v38, v38 quad_perm:[2,3,0,1] row_mask:0xf bank_mask:0xf
	s_waitcnt lgkmcnt(0)
	s_nop 1
	v_add_f32_dpp v39, v39, v39 quad_perm:[1,0,3,2] row_mask:0xf bank_mask:0xf
	v_add_f32_dpp v38, v38, v38 quad_perm:[1,0,3,2] row_mask:0xf bank_mask:0xf
	s_waitcnt lgkmcnt(0)
	s_nop 0
	v_pk_fma_f32 v[38:39], v[38:39], s[96:97], v[18:19] op_sel_hi:[1,1,0]
	s_nop 0
	v_mul_f32_e32 v40, 0x4b800000, v39
	v_cmp_gt_f32_e64 s[0:1], s77, v39
	v_cmp_gt_f32_e32 vcc, s77, v38
	s_nop 0
	v_cndmask_b32_e64 v39, v39, v40, s[0:1]
	v_rsq_f32_e32 v39, v39
	s_nop 0
	v_mul_f32_e32 v40, 0x45800000, v39
	v_cndmask_b32_e64 v40, v39, v40, s[0:1]
	v_pk_mul_f32 v[36:37], v[40:41], v[36:37] op_sel_hi:[0,1]
	v_pk_mul_f32 v[34:35], v[40:41], v[34:35] op_sel_hi:[0,1]
	v_pk_mul_f32 v[36:37], v[2:3], v[36:37]
	v_pk_mul_f32 v[34:35], v[4:5], v[34:35]
	v_cvt_pk_bf16_f32 v36, v36, v37
	v_cvt_pk_bf16_f32 v37, v34, v35
	v_mul_f32_e32 v34, 0x4b800000, v38
	v_cndmask_b32_e32 v34, v38, v34, vcc
	v_rsq_f32_e32 v34, v34
	global_store_dwordx2 v[82:83], v[36:37], off
	v_lshlrev_b32_e32 v38, 16, v77
	v_and_b32_e32 v39, 0xffff0000, v77
	v_mul_f32_e32 v35, 0x45800000, v34
	v_cndmask_b32_e32 v34, v34, v35, vcc
	v_pk_mul_f32 v[34:35], v[34:35], v[84:85] op_sel_hi:[0,1]
	v_pk_mul_f32 v[34:35], v[6:7], v[34:35]
	v_pk_mul_f32 v[40:41], v[38:39], v[38:39]
	v_cvt_pk_bf16_f32 v36, v34, v35
	v_lshl_add_u64 v[34:35], v[42:43], 0, v[12:13]
	global_store_dword v[34:35], v36, off offset:512
	v_lshlrev_b32_e32 v34, 16, v78
	v_and_b32_e32 v35, 0xffff0000, v78
	v_pk_mul_f32 v[36:37], v[34:35], v[34:35]
	v_mov_b32_e32 v42, v40
	v_mov_b32_e32 v43, v36
	v_mov_b32_e32 v36, v41
	v_pk_add_f32 v[36:37], v[42:43], v[36:37]
	v_mov_b32_e32 v41, v37
	v_mov_b32_e32 v40, v36
	s_nop 0
	v_permlane32_swap_b32_e32 v41, v37
	v_permlane32_swap_b32_e32 v40, v36
	s_waitcnt lgkmcnt(0)
	v_pk_add_f32 v[36:37], v[36:37], v[40:41]
	v_mov_b32_e32 v41, v37
	v_mov_b32_e32 v40, v36
	s_nop 0
	v_permlane16_swap_b32_e32 v41, v37
	v_permlane16_swap_b32_e32 v40, v36
	s_waitcnt lgkmcnt(0)
	v_pk_add_f32 v[36:37], v[36:37], v[40:41]
	s_nop 1
	v_add_f32_dpp v37, v37, v37 row_ror:8 row_mask:0xf bank_mask:0xf
	v_add_f32_dpp v36, v36, v36 row_ror:8 row_mask:0xf bank_mask:0xf
	s_waitcnt lgkmcnt(0)
	s_nop 1
	v_add_f32_dpp v37, v37, v37 row_ror:4 row_mask:0xf bank_mask:0xf
	v_add_f32_dpp v36, v36, v36 row_ror:4 row_mask:0xf bank_mask:0xf
	s_waitcnt lgkmcnt(0)
	s_nop 1
	v_add_f32_dpp v37, v37, v37 quad_perm:[2,3,0,1] row_mask:0xf bank_mask:0xf
	v_add_f32_dpp v36, v36, v36 quad_perm:[2,3,0,1] row_mask:0xf bank_mask:0xf
	s_waitcnt lgkmcnt(0)
	s_nop 1
	v_add_f32_dpp v37, v37, v37 quad_perm:[1,0,3,2] row_mask:0xf bank_mask:0xf
	v_add_f32_dpp v36, v36, v36 quad_perm:[1,0,3,2] row_mask:0xf bank_mask:0xf
	s_waitcnt lgkmcnt(0)
; DI unsigned pk2(float lo, float hi) { const f32x2 v = {lo, hi}; return __builtin_bit_cast(unsigned, __builtin_convertvector(v, bf16v2_t)); }
; DI float wave_sum(float v) { for (int o = 32; o; o >>= 1) v += __shfl_xor(v, o); return v; }
; DI void run_phase(const Params& p, int ph, unsigned char* smem, const int tid, const int rep) {
;     ...
;                   for (int hq = 0; hq < 8; ++hq) { const unsigned v = vf[u][hq]; const float a0 = __uint_as_float(v << 16), a1 = __uint_as_float(v & 0xffff0000u);
;                     const float rs = rsqrtf(wave_sum(a0 * a0 + a1 * a1) * (1.f / 128.f) + NEPS) * ((hq < 4) ? 0.08838834764831845f * LOG2E : 1.f);
;                     *(unsigned*)(pr + 3520 + hq * 128 + 2 * lane) = pk2(a0 * rs * ((hq < 4) ? fq0 : fk0), a1 * rs * ((hq < 4) ? fq1 : fk1)); } } } }
	s_nop 0
	v_pk_fma_f32 v[36:37], v[36:37], s[96:97], v[18:19] op_sel_hi:[1,0,0]
	s_nop 0
	v_mul_f32_e32 v40, 0x4b800000, v37
	v_cmp_gt_f32_e64 s[0:1], s77, v37
	v_cmp_gt_f32_e32 vcc, s77, v36
	s_nop 0
	v_cndmask_b32_e64 v37, v37, v40, s[0:1]
	v_rsq_f32_e32 v37, v37
	s_nop 0
	v_mul_f32_e32 v40, 0x45800000, v37
	v_cndmask_b32_e64 v37, v37, v40, s[0:1]
	v_mul_f32_e32 v40, 0x3e0293ee, v37
	v_pk_mul_f32 v[34:35], v[40:41], v[34:35] op_sel_hi:[0,1]
	v_pk_mul_f32 v[34:35], v[8:9], v[34:35]
	v_and_b32_e32 v37, 0xffff0000, v75
	v_cvt_pk_bf16_f32 v34, v34, v35
	global_store_dword v[32:33], v34, off offset:2944
	v_mul_f32_e32 v32, 0x4b800000, v36
	v_cndmask_b32_e32 v32, v36, v32, vcc
	v_rsq_f32_e32 v32, v32
	v_lshlrev_b32_e32 v36, 16, v75
	v_mul_f32_e32 v33, 0x45800000, v32
	v_cndmask_b32_e32 v32, v32, v33, vcc
	v_mul_f32_e32 v32, 0x3e0293ee, v32
	v_pk_mul_f32 v[32:33], v[32:33], v[38:39] op_sel_hi:[0,1]
	v_pk_mul_f32 v[32:33], v[8:9], v[32:33]
	v_pk_mul_f32 v[38:39], v[36:37], v[36:37]
	v_cvt_pk_bf16_f32 v32, v32, v33
	global_store_dword v[28:29], v32, off offset:256
	v_lshlrev_b32_e32 v32, 16, v76
	v_and_b32_e32 v33, 0xffff0000, v76
	v_pk_mul_f32 v[34:35], v[32:33], v[32:33]
	v_mov_b32_e32 v40, v38
	v_mov_b32_e32 v41, v34
	v_mov_b32_e32 v34, v39
	v_pk_add_f32 v[34:35], v[40:41], v[34:35]
	v_mov_b32_e32 v39, v35
	v_mov_b32_e32 v38, v34
	s_nop 0
	v_permlane32_swap_b32_e32 v39, v35
	v_permlane32_swap_b32_e32 v38, v34
	s_waitcnt lgkmcnt(0)
	v_pk_add_f32 v[34:35], v[34:35], v[38:39]
	v_mov_b32_e32 v39, v35
	v_mov_b32_e32 v38, v34
	s_nop 0
	v_permlane16_swap_b32_e32 v39, v35
	v_permlane16_swap_b32_e32 v38, v34
	s_waitcnt lgkmcnt(0)
	v_pk_add_f32 v[34:35], v[34:35], v[38:39]
	s_nop 1
	v_add_f32_dpp v35, v35, v35 row_ror:8 row_mask:0xf bank_mask:0xf
	v_add_f32_dpp v34, v34, v34 row_ror:8 row_mask:0xf bank_mask:0xf
	s_waitcnt lgkmcnt(0)
	s_nop 1
	v_add_f32_dpp v35, v35, v35 row_ror:4 row_mask:0xf bank_mask:0xf
	v_add_f32_dpp v34, v34, v34 row_ror:4 row_mask:0xf bank_mask:0xf
	s_waitcnt lgkmcnt(0)
	s_nop 1
	v_add_f32_dpp v35, v35, v35 quad_perm:[2,3,0,1] row_mask:0xf bank_mask:0xf
	v_add_f32_dpp v34, v34, v34 quad_perm:[2,3,0,1] row_mask:0xf bank_mask:0xf
	s_waitcnt lgkmcnt(0)
	s_nop 1
	v_add_f32_dpp v35, v35, v35 quad_perm:[1,0,3,2] row_mask:0xf bank_mask:0xf
	v_add_f32_dpp v34, v34, v34 quad_perm:[1,0,3,2] row_mask:0xf bank_mask:0xf
	s_waitcnt lgkmcnt(0)
	s_nop 0
	v_pk_fma_f32 v[34:35], v[34:35], s[96:97], v[18:19] op_sel_hi:[1,0,0]
	s_nop 0
	v_mul_f32_e32 v38, 0x4b800000, v35
	v_cmp_gt_f32_e64 s[0:1], s77, v35
	v_cmp_gt_f32_e32 vcc, s77, v34
	s_nop 0
	v_cndmask_b32_e64 v35, v35, v38, s[0:1]
	v_rsq_f32_e32 v35, v35
	s_nop 0
	v_mul_f32_e32 v38, 0x45800000, v35
	v_cndmask_b32_e64 v35, v35, v38, s[0:1]
	v_mul_f32_e32 v38, 0x3e0293ee, v35
	v_pk_mul_f32 v[32:33], v[38:39], v[32:33] op_sel_hi:[0,1]
	v_pk_mul_f32 v[32:33], v[8:9], v[32:33]
	s_nop 0
	v_cvt_pk_bf16_f32 v32, v32, v33
	global_store_dword v[28:29], v32, off offset:512
	v_mul_f32_e32 v32, 0x4b800000, v34
	v_cndmask_b32_e32 v32, v34, v32, vcc
	v_rsq_f32_e32 v32, v32
	s_nop 0
	v_mul_f32_e32 v33, 0x45800000, v32
	v_cndmask_b32_e32 v32, v32, v33, vcc
	v_mul_f32_e32 v32, 0x3e0293ee, v32
	v_pk_mul_f32 v[32:33], v[32:33], v[36:37] op_sel_hi:[0,1]
	v_pk_mul_f32 v[32:33], v[8:9], v[32:33]
	v_lshlrev_b32_e32 v36, 16, v73
	v_cvt_pk_bf16_f32 v32, v32, v33
	global_store_dword v[28:29], v32, off offset:768
	v_lshlrev_b32_e32 v32, 16, v74
	v_and_b32_e32 v33, 0xffff0000, v74
	v_and_b32_e32 v37, 0xffff0000, v73
	v_pk_mul_f32 v[34:35], v[32:33], v[32:33]
	v_pk_mul_f32 v[38:39], v[36:37], v[36:37]
	v_mov_b32_e32 v41, v34
	v_mov_b32_e32 v40, v38
	v_mov_b32_e32 v34, v39
	v_pk_add_f32 v[34:35], v[40:41], v[34:35]
	v_mov_b32_e32 v39, v35
	v_mov_b32_e32 v38, v34
	s_nop 0
	v_permlane32_swap_b32_e32 v39, v35
	v_permlane32_swap_b32_e32 v38, v34
	s_waitcnt lgkmcnt(0)
	v_pk_add_f32 v[34:35], v[34:35], v[38:39]
	v_mov_b32_e32 v39, v35
	v_mov_b32_e32 v38, v34
	s_nop 0
	v_permlane16_swap_b32_e32 v39, v35
	v_permlane16_swap_b32_e32 v38, v34
	s_waitcnt lgkmcnt(0)
	v_pk_add_f32 v[34:35], v[34:35], v[38:39]
	s_nop 1
	v_add_f32_dpp v35, v35, v35 row_ror:8 row_mask:0xf bank_mask:0xf
	v_add_f32_dpp v34, v34, v34 row_ror:8 row_mask:0xf bank_mask:0xf
	s_waitcnt lgkmcnt(0)
	s_nop 1
	v_add_f32_dpp v35, v35, v35 row_ror:4 row_mask:0xf bank_mask:0xf
	v_add_f32_dpp v34, v34, v34 row_ror:4 row_mask:0xf bank_mask:0xf
	s_waitcnt lgkmcnt(0)
	s_nop 1
	v_add_f32_dpp v35, v35, v35 quad_perm:[2,3,0,1] row_mask:0xf bank_mask:0xf
	v_add_f32_dpp v34, v34, v34 quad_perm:[2,3,0,1] row_mask:0xf bank_mask:0xf
	s_waitcnt lgkmcnt(0)
	s_nop 1
	v_add_f32_dpp v35, v35, v35 quad_perm:[1,0,3,2] row_mask:0xf bank_mask:0xf
	v_add_f32_dpp v34, v34, v34 quad_perm:[1,0,3,2] row_mask:0xf bank_mask:0xf
	s_waitcnt lgkmcnt(0)
	s_nop 0
	v_pk_fma_f32 v[34:35], v[34:35], s[96:97], v[18:19] op_sel_hi:[1,0,0]
	s_nop 0
	v_mul_f32_e32 v38, 0x4b800000, v35
	v_cmp_gt_f32_e64 s[0:1], s77, v35
	v_cmp_gt_f32_e32 vcc, s77, v34
	s_nop 0
	v_cndmask_b32_e64 v35, v35, v38, s[0:1]
	v_rsq_f32_e32 v35, v35
	s_nop 0
	v_mul_f32_e32 v38, 0x45800000, v35
	v_cndmask_b32_e64 v38, v35, v38, s[0:1]
	v_pk_mul_f32 v[32:33], v[38:39], v[32:33] op_sel_hi:[0,1]
	v_pk_mul_f32 v[32:33], v[10:11], v[32:33]
	s_nop 0
	v_cvt_pk_bf16_f32 v32, v32, v33
	global_store_dword v[28:29], v32, off offset:1024
	v_mul_f32_e32 v32, 0x4b800000, v34
	v_cndmask_b32_e32 v32, v34, v32, vcc
	v_rsq_f32_e32 v32, v32
	s_nop 0
	v_mul_f32_e32 v33, 0x45800000, v32
	v_cndmask_b32_e32 v32, v32, v33, vcc
	v_pk_mul_f32 v[32:33], v[32:33], v[36:37] op_sel_hi:[0,1]
	v_pk_mul_f32 v[32:33], v[10:11], v[32:33]
	v_lshlrev_b32_e32 v36, 16, v71
	v_cvt_pk_bf16_f32 v32, v32, v33
	global_store_dword v[28:29], v32, off offset:1280
	v_lshlrev_b32_e32 v32, 16, v72
	v_and_b32_e32 v33, 0xffff0000, v72
	v_and_b32_e32 v37, 0xffff0000, v71
	v_pk_mul_f32 v[34:35], v[32:33], v[32:33]
	v_pk_mul_f32 v[38:39], v[36:37], v[36:37]
	v_mov_b32_e32 v41, v34
	v_mov_b32_e32 v40, v38
	v_mov_b32_e32 v34, v39
	v_pk_add_f32 v[34:35], v[40:41], v[34:35]
	v_mov_b32_e32 v39, v35
	v_mov_b32_e32 v38, v34
	s_nop 0
	v_permlane32_swap_b32_e32 v39, v35
	v_permlane32_swap_b32_e32 v38, v34
	v_lshlrev_b32_e32 v40, 16, v70
	v_and_b32_e32 v41, 0xffff0000, v70
	v_pk_mul_f32 v[42:43], v[40:41], v[40:41]
	s_waitcnt lgkmcnt(0)
; DI unsigned pk2(float lo, float hi) { const f32x2 v = {lo, hi}; return __builtin_bit_cast(unsigned, __builtin_convertvector(v, bf16v2_t)); }
; DI float wave_sum(float v) { for (int o = 32; o; o >>= 1) v += __shfl_xor(v, o); return v; }
; DI void run_phase(const Params& p, int ph, unsigned char* smem, const int tid, const int rep) {
;     ...
;                   { const u32x2 v = vq[u]; const float a0 = __uint_as_float(v[0] << 16), a1 = __uint_as_float(v[0] & 0xffff0000u), a2 = __uint_as_float(v[1] << 16), a3 = __uint_as_float(v[1] & 0xffff0000u);
;                     const float rs = rsqrtf(wave_sum(a0 * a0 + a1 * a1 + a2 * a2 + a3 * a3) * (1.f / 256.f) + NEPS);
;                     u32x2 o; o[0] = pk2(a0 * rs * ggq[0], a1 * rs * ggq[1]); o[1] = pk2(a2 * rs * ggq[2], a3 * rs * ggq[3]); *(u32x2*)(mlaa + (size_t)t * 384 + 4 * lane) = o; }
;                   { const unsigned v = vkv[u]; const float a0 = __uint_as_float(v << 16), a1 = __uint_as_float(v & 0xffff0000u);
;                     const float rs = rsqrtf(wave_sum(a0 * a0 + a1 * a1) * (1.f / 128.f) + NEPS);
;                     *(unsigned*)(mlaa + (size_t)t * 384 + 256 + 2 * lane) = pk2(a0 * rs * gkv0, a1 * rs * gkv1); }
; #pragma unroll
;                   for (int hq = 0; hq < 8; ++hq) { const unsigned v = vf[u][hq]; const float a0 = __uint_as_float(v << 16), a1 = __uint_as_float(v & 0xffff0000u);
;                     const float rs = rsqrtf(wave_sum(a0 * a0 + a1 * a1) * (1.f / 128.f) + NEPS) * ((hq < 4) ? 0.08838834764831845f * LOG2E : 1.f);
;                     *(unsigned*)(pr + 3520 + hq * 128 + 2 * lane) = pk2(a0 * rs * ((hq < 4) ? fq0 : fk0), a1 * rs * ((hq < 4) ? fq1 : fk1)); } } } }
	v_pk_add_f32 v[34:35], v[34:35], v[38:39]
	v_mov_b32_e32 v39, v35
	v_mov_b32_e32 v38, v34
	s_nop 0
	v_permlane16_swap_b32_e32 v39, v35
	v_permlane16_swap_b32_e32 v38, v34
	s_waitcnt lgkmcnt(0)
	v_pk_add_f32 v[34:35], v[34:35], v[38:39]
	s_nop 1
	v_add_f32_dpp v35, v35, v35 row_ror:8 row_mask:0xf bank_mask:0xf
	v_add_f32_dpp v34, v34, v34 row_ror:8 row_mask:0xf bank_mask:0xf
	s_waitcnt lgkmcnt(0)
	s_nop 1
	v_add_f32_dpp v35, v35, v35 row_ror:4 row_mask:0xf bank_mask:0xf
	v_add_f32_dpp v34, v34, v34 row_ror:4 row_mask:0xf bank_mask:0xf
	s_waitcnt lgkmcnt(0)
	s_nop 1
	v_add_f32_dpp v35, v35, v35 quad_perm:[2,3,0,1] row_mask:0xf bank_mask:0xf
	v_add_f32_dpp v34, v34, v34 quad_perm:[2,3,0,1] row_mask:0xf bank_mask:0xf
	s_waitcnt lgkmcnt(0)
	s_nop 1
	v_add_f32_dpp v35, v35, v35 quad_perm:[1,0,3,2] row_mask:0xf bank_mask:0xf
	v_add_f32_dpp v34, v34, v34 quad_perm:[1,0,3,2] row_mask:0xf bank_mask:0xf
	s_waitcnt lgkmcnt(0)
	s_nop 0
	v_pk_fma_f32 v[34:35], v[34:35], s[96:97], v[18:19] op_sel_hi:[1,0,0]
	s_nop 0
	v_mul_f32_e32 v38, 0x4b800000, v35
	v_cmp_gt_f32_e64 s[0:1], s77, v35
	v_cmp_gt_f32_e32 vcc, s77, v34
	s_nop 0
	v_cndmask_b32_e64 v35, v35, v38, s[0:1]
	v_rsq_f32_e32 v35, v35
	s_nop 0
	v_mul_f32_e32 v38, 0x45800000, v35
	v_cndmask_b32_e64 v38, v35, v38, s[0:1]
	v_pk_mul_f32 v[32:33], v[38:39], v[32:33] op_sel_hi:[0,1]
	v_pk_mul_f32 v[32:33], v[10:11], v[32:33]
	s_nop 0
	v_cvt_pk_bf16_f32 v32, v32, v33
	global_store_dword v[28:29], v32, off offset:1536
	v_mul_f32_e32 v32, 0x4b800000, v34
	v_cndmask_b32_e32 v32, v34, v32, vcc
	v_rsq_f32_e32 v32, v32
	s_nop 0
	v_mul_f32_e32 v33, 0x45800000, v32
	v_cndmask_b32_e32 v32, v32, v33, vcc
	v_pk_mul_f32 v[32:33], v[32:33], v[36:37] op_sel_hi:[0,1]
	v_pk_mul_f32 v[32:33], v[10:11], v[32:33]
	s_nop 0
	v_cvt_pk_bf16_f32 v32, v32, v33
	global_store_dword v[28:29], v32, off offset:1792
	v_and_b32_e32 v33, 0xffff0000, v31
	v_and_b32_e32 v32, s0, v30
	v_mov_b32_e32 v29, v33
	v_pk_mul_f32 v[34:35], v[32:33], v[32:33]
	v_and_b32_e32 v33, 0xffff0000, v30
	v_lshlrev_b32_e32 v32, 16, v30
	v_mul_f32_e32 v30, v33, v33
	v_lshlrev_b32_e32 v28, 16, v31
	v_pk_fma_f32 v[30:31], v[32:33], v[32:33], v[30:31] op_sel_hi:[1,1,0]
	v_mov_b32_e32 v34, v42
	v_pk_fma_f32 v[30:31], v[28:29], v[28:29], v[30:31]
	v_mad_i64_i32 v[36:37], s[0:1], v69, s22, v[20:21]
	v_pk_mov_b32 v[30:31], v[42:43], v[30:31] op_sel:[1,0]
	v_lshl_add_u64 v[38:39], v[36:37], 0, v[0:1]
	v_pk_add_f32 v[30:31], v[34:35], v[30:31]
	v_mov_b32_e32 v35, v31
	v_mov_b32_e32 v34, v30
	s_nop 0
	v_permlane32_swap_b32_e32 v35, v31
	v_permlane32_swap_b32_e32 v34, v30
	s_waitcnt lgkmcnt(0)
	v_pk_add_f32 v[30:31], v[30:31], v[34:35]
	v_mov_b32_e32 v35, v31
	v_mov_b32_e32 v34, v30
	s_nop 0
	v_permlane16_swap_b32_e32 v35, v31
	v_permlane16_swap_b32_e32 v34, v30
	s_waitcnt lgkmcnt(0)
	v_pk_add_f32 v[30:31], v[30:31], v[34:35]
	s_nop 1
	v_add_f32_dpp v31, v31, v31 row_ror:8 row_mask:0xf bank_mask:0xf
	v_add_f32_dpp v30, v30, v30 row_ror:8 row_mask:0xf bank_mask:0xf
	s_waitcnt lgkmcnt(0)
	s_nop 1
	v_add_f32_dpp v31, v31, v31 row_ror:4 row_mask:0xf bank_mask:0xf
	v_add_f32_dpp v30, v30, v30 row_ror:4 row_mask:0xf bank_mask:0xf
	s_waitcnt lgkmcnt(0)
	s_nop 1
	v_add_f32_dpp v31, v31, v31 quad_perm:[2,3,0,1] row_mask:0xf bank_mask:0xf
	v_add_f32_dpp v30, v30, v30 quad_perm:[2,3,0,1] row_mask:0xf bank_mask:0xf
	s_waitcnt lgkmcnt(0)
	s_nop 1
	v_add_f32_dpp v31, v31, v31 quad_perm:[1,0,3,2] row_mask:0xf bank_mask:0xf
	v_add_f32_dpp v30, v30, v30 quad_perm:[1,0,3,2] row_mask:0xf bank_mask:0xf
	s_waitcnt lgkmcnt(0)
	s_nop 0
	v_pk_fma_f32 v[30:31], v[30:31], s[96:97], v[18:19] op_sel_hi:[1,1,0]
	s_nop 0
	v_mul_f32_e32 v34, 0x4b800000, v31
	v_cmp_gt_f32_e64 s[0:1], s77, v31
	v_cmp_gt_f32_e32 vcc, s77, v30
	s_nop 0
	v_cndmask_b32_e64 v31, v31, v34, s[0:1]
	v_rsq_f32_e32 v31, v31
	s_nop 0
	v_mul_f32_e32 v34, 0x45800000, v31
	v_cndmask_b32_e64 v34, v31, v34, s[0:1]
	v_pk_mul_f32 v[32:33], v[34:35], v[32:33] op_sel_hi:[0,1]
	v_pk_mul_f32 v[28:29], v[34:35], v[28:29] op_sel_hi:[0,1]
	v_pk_mul_f32 v[32:33], v[2:3], v[32:33]
	v_pk_mul_f32 v[28:29], v[4:5], v[28:29]
	v_cvt_pk_bf16_f32 v32, v32, v33
	v_cvt_pk_bf16_f32 v33, v28, v29
	v_mul_f32_e32 v28, 0x4b800000, v30
	v_cndmask_b32_e32 v28, v30, v28, vcc
	v_rsq_f32_e32 v28, v28
	global_store_dwordx2 v[38:39], v[32:33], off
	v_lshlrev_b32_e32 v32, 16, v67
	v_and_b32_e32 v33, 0xffff0000, v67
	v_mul_f32_e32 v29, 0x45800000, v28
	v_cndmask_b32_e32 v28, v28, v29, vcc
	v_pk_mul_f32 v[28:29], v[28:29], v[40:41] op_sel_hi:[0,1]
	v_pk_mul_f32 v[28:29], v[6:7], v[28:29]
	v_pk_mul_f32 v[34:35], v[32:33], v[32:33]
	v_cvt_pk_bf16_f32 v30, v28, v29
	v_lshl_add_u64 v[28:29], v[36:37], 0, v[12:13]
	global_store_dword v[28:29], v30, off offset:512
	v_lshlrev_b32_e32 v28, 16, v68
	v_and_b32_e32 v29, 0xffff0000, v68
	v_pk_mul_f32 v[30:31], v[28:29], v[28:29]
	v_mov_b32_e32 v36, v34
	v_mov_b32_e32 v37, v30
	v_mov_b32_e32 v30, v35
	v_pk_add_f32 v[30:31], v[36:37], v[30:31]
	v_mov_b32_e32 v35, v31
	v_mov_b32_e32 v34, v30
	s_nop 0
	v_permlane32_swap_b32_e32 v35, v31
	v_permlane32_swap_b32_e32 v34, v30
	s_waitcnt lgkmcnt(0)
	v_pk_add_f32 v[30:31], v[30:31], v[34:35]
	v_mov_b32_e32 v35, v31
	v_mov_b32_e32 v34, v30
	s_nop 0
	v_permlane16_swap_b32_e32 v35, v31
	v_permlane16_swap_b32_e32 v34, v30
	s_waitcnt lgkmcnt(0)
	v_pk_add_f32 v[30:31], v[30:31], v[34:35]
	s_nop 1
	v_add_f32_dpp v31, v31, v31 row_ror:8 row_mask:0xf bank_mask:0xf
	v_add_f32_dpp v30, v30, v30 row_ror:8 row_mask:0xf bank_mask:0xf
	s_waitcnt lgkmcnt(0)
	s_nop 1
	v_add_f32_dpp v31, v31, v31 row_ror:4 row_mask:0xf bank_mask:0xf
	v_add_f32_dpp v30, v30, v30 row_ror:4 row_mask:0xf bank_mask:0xf
	s_waitcnt lgkmcnt(0)
; DI unsigned pk2(float lo, float hi) { const f32x2 v = {lo, hi}; return __builtin_bit_cast(unsigned, __builtin_convertvector(v, bf16v2_t)); }
; DI float wave_sum(float v) { for (int o = 32; o; o >>= 1) v += __shfl_xor(v, o); return v; }
; DI void run_phase(const Params& p, int ph, unsigned char* smem, const int tid, const int rep) {
;     ...
;                   for (int hq = 0; hq < 8; ++hq) { const unsigned v = vf[u][hq]; const float a0 = __uint_as_float(v << 16), a1 = __uint_as_float(v & 0xffff0000u);
;                     const float rs = rsqrtf(wave_sum(a0 * a0 + a1 * a1) * (1.f / 128.f) + NEPS) * ((hq < 4) ? 0.08838834764831845f * LOG2E : 1.f);
;                     *(unsigned*)(pr + 3520 + hq * 128 + 2 * lane) = pk2(a0 * rs * ((hq < 4) ? fq0 : fk0), a1 * rs * ((hq < 4) ? fq1 : fk1)); } } } }
	s_nop 1
	v_add_f32_dpp v31, v31, v31 quad_perm:[2,3,0,1] row_mask:0xf bank_mask:0xf
	v_add_f32_dpp v30, v30, v30 quad_perm:[2,3,0,1] row_mask:0xf bank_mask:0xf
	s_waitcnt lgkmcnt(0)
	s_nop 1
	v_add_f32_dpp v31, v31, v31 quad_perm:[1,0,3,2] row_mask:0xf bank_mask:0xf
	v_add_f32_dpp v30, v30, v30 quad_perm:[1,0,3,2] row_mask:0xf bank_mask:0xf
	s_waitcnt lgkmcnt(0)
	s_nop 0
	v_pk_fma_f32 v[30:31], v[30:31], s[96:97], v[18:19] op_sel_hi:[1,0,0]
	s_nop 0
	v_mul_f32_e32 v34, 0x4b800000, v31
	v_cmp_gt_f32_e64 s[0:1], s77, v31
	v_cmp_gt_f32_e32 vcc, s77, v30
	s_nop 0
	v_cndmask_b32_e64 v31, v31, v34, s[0:1]
	v_rsq_f32_e32 v31, v31
	s_nop 0
	v_mul_f32_e32 v34, 0x45800000, v31
	v_cndmask_b32_e64 v31, v31, v34, s[0:1]
	v_mul_f32_e32 v34, 0x3e0293ee, v31
	v_pk_mul_f32 v[28:29], v[34:35], v[28:29] op_sel_hi:[0,1]
	v_pk_mul_f32 v[28:29], v[8:9], v[28:29]
	v_and_b32_e32 v31, 0xffff0000, v65
	v_cvt_pk_bf16_f32 v28, v28, v29
	global_store_dword v[26:27], v28, off offset:2944
	v_mul_f32_e32 v26, 0x4b800000, v30
	v_cndmask_b32_e32 v26, v30, v26, vcc
	v_rsq_f32_e32 v26, v26
	v_lshlrev_b32_e32 v30, 16, v65
	v_mul_f32_e32 v27, 0x45800000, v26
	v_cndmask_b32_e32 v26, v26, v27, vcc
	v_mul_f32_e32 v26, 0x3e0293ee, v26
	v_pk_mul_f32 v[26:27], v[26:27], v[32:33] op_sel_hi:[0,1]
	v_pk_mul_f32 v[26:27], v[8:9], v[26:27]
	v_pk_mul_f32 v[32:33], v[30:31], v[30:31]
	v_cvt_pk_bf16_f32 v26, v26, v27
	global_store_dword v[22:23], v26, off offset:256
	v_lshlrev_b32_e32 v26, 16, v66
	v_and_b32_e32 v27, 0xffff0000, v66
	v_pk_mul_f32 v[28:29], v[26:27], v[26:27]
	v_mov_b32_e32 v34, v32
	v_mov_b32_e32 v35, v28
	v_mov_b32_e32 v28, v33
	v_pk_add_f32 v[28:29], v[34:35], v[28:29]
	v_mov_b32_e32 v33, v29
	v_mov_b32_e32 v32, v28
	s_nop 0
	v_permlane32_swap_b32_e32 v33, v29
	v_permlane32_swap_b32_e32 v32, v28
	s_waitcnt lgkmcnt(0)
	v_pk_add_f32 v[28:29], v[28:29], v[32:33]
	v_mov_b32_e32 v33, v29
	v_mov_b32_e32 v32, v28
	s_nop 0
	v_permlane16_swap_b32_e32 v33, v29
	v_permlane16_swap_b32_e32 v32, v28
	s_waitcnt lgkmcnt(0)
	v_pk_add_f32 v[28:29], v[28:29], v[32:33]
	s_nop 1
	v_add_f32_dpp v29, v29, v29 row_ror:8 row_mask:0xf bank_mask:0xf
	v_add_f32_dpp v28, v28, v28 row_ror:8 row_mask:0xf bank_mask:0xf
	s_waitcnt lgkmcnt(0)
	s_nop 1
	v_add_f32_dpp v29, v29, v29 row_ror:4 row_mask:0xf bank_mask:0xf
	v_add_f32_dpp v28, v28, v28 row_ror:4 row_mask:0xf bank_mask:0xf
	s_waitcnt lgkmcnt(0)
	s_nop 1
	v_add_f32_dpp v29, v29, v29 quad_perm:[2,3,0,1] row_mask:0xf bank_mask:0xf
	v_add_f32_dpp v28, v28, v28 quad_perm:[2,3,0,1] row_mask:0xf bank_mask:0xf
	s_waitcnt lgkmcnt(0)
	s_nop 1
	v_add_f32_dpp v29, v29, v29 quad_perm:[1,0,3,2] row_mask:0xf bank_mask:0xf
	v_add_f32_dpp v28, v28, v28 quad_perm:[1,0,3,2] row_mask:0xf bank_mask:0xf
	s_waitcnt lgkmcnt(0)
	s_nop 0
	v_pk_fma_f32 v[28:29], v[28:29], s[96:97], v[18:19] op_sel_hi:[1,0,0]
	s_nop 0
	v_mul_f32_e32 v32, 0x4b800000, v29
	v_cmp_gt_f32_e64 s[0:1], s77, v29
	v_cmp_gt_f32_e32 vcc, s77, v28
	s_nop 0
	v_cndmask_b32_e64 v29, v29, v32, s[0:1]
	v_rsq_f32_e32 v29, v29
	s_nop 0
	v_mul_f32_e32 v32, 0x45800000, v29
	v_cndmask_b32_e64 v29, v29, v32, s[0:1]
	v_mul_f32_e32 v32, 0x3e0293ee, v29
	v_pk_mul_f32 v[26:27], v[32:33], v[26:27] op_sel_hi:[0,1]
	v_pk_mul_f32 v[26:27], v[8:9], v[26:27]
	s_nop 0
	v_cvt_pk_bf16_f32 v26, v26, v27
	global_store_dword v[22:23], v26, off offset:512
	v_mul_f32_e32 v26, 0x4b800000, v28
	v_cndmask_b32_e32 v26, v28, v26, vcc
	v_rsq_f32_e32 v26, v26
	s_nop 0
	v_mul_f32_e32 v27, 0x45800000, v26
	v_cndmask_b32_e32 v26, v26, v27, vcc
	v_mul_f32_e32 v26, 0x3e0293ee, v26
	v_pk_mul_f32 v[26:27], v[26:27], v[30:31] op_sel_hi:[0,1]
	v_pk_mul_f32 v[26:27], v[8:9], v[26:27]
	v_lshlrev_b32_e32 v30, 16, v63
	v_cvt_pk_bf16_f32 v26, v26, v27
	global_store_dword v[22:23], v26, off offset:768
	v_lshlrev_b32_e32 v26, 16, v64
	v_and_b32_e32 v27, 0xffff0000, v64
	v_and_b32_e32 v31, 0xffff0000, v63
	v_pk_mul_f32 v[28:29], v[26:27], v[26:27]
	v_pk_mul_f32 v[32:33], v[30:31], v[30:31]
	v_mov_b32_e32 v35, v28
	v_mov_b32_e32 v34, v32
	v_mov_b32_e32 v28, v33
	v_pk_add_f32 v[28:29], v[34:35], v[28:29]
	v_mov_b32_e32 v33, v29
	v_mov_b32_e32 v32, v28
	s_nop 0
	v_permlane32_swap_b32_e32 v33, v29
	v_permlane32_swap_b32_e32 v32, v28
	s_waitcnt lgkmcnt(0)
	v_pk_add_f32 v[28:29], v[28:29], v[32:33]
	v_mov_b32_e32 v33, v29
	v_mov_b32_e32 v32, v28
	s_nop 0
	v_permlane16_swap_b32_e32 v33, v29
	v_permlane16_swap_b32_e32 v32, v28
	s_waitcnt lgkmcnt(0)
	v_pk_add_f32 v[28:29], v[28:29], v[32:33]
	s_nop 1
	v_add_f32_dpp v29, v29, v29 row_ror:8 row_mask:0xf bank_mask:0xf
	v_add_f32_dpp v28, v28, v28 row_ror:8 row_mask:0xf bank_mask:0xf
	s_waitcnt lgkmcnt(0)
	s_nop 1
	v_add_f32_dpp v29, v29, v29 row_ror:4 row_mask:0xf bank_mask:0xf
	v_add_f32_dpp v28, v28, v28 row_ror:4 row_mask:0xf bank_mask:0xf
	s_waitcnt lgkmcnt(0)
	s_nop 1
	v_add_f32_dpp v29, v29, v29 quad_perm:[2,3,0,1] row_mask:0xf bank_mask:0xf
	v_add_f32_dpp v28, v28, v28 quad_perm:[2,3,0,1] row_mask:0xf bank_mask:0xf
	s_waitcnt lgkmcnt(0)
	s_nop 1
	v_add_f32_dpp v29, v29, v29 quad_perm:[1,0,3,2] row_mask:0xf bank_mask:0xf
	v_add_f32_dpp v28, v28, v28 quad_perm:[1,0,3,2] row_mask:0xf bank_mask:0xf
	s_waitcnt lgkmcnt(0)
; DI unsigned pk2(float lo, float hi) { const f32x2 v = {lo, hi}; return __builtin_bit_cast(unsigned, __builtin_convertvector(v, bf16v2_t)); }
; DI float wave_sum(float v) { for (int o = 32; o; o >>= 1) v += __shfl_xor(v, o); return v; }
; DI void run_phase(const Params& p, int ph, unsigned char* smem, const int tid, const int rep) {
;     ...
;                   { const u32x2 v = vq[u]; const float a0 = __uint_as_float(v[0] << 16), a1 = __uint_as_float(v[0] & 0xffff0000u), a2 = __uint_as_float(v[1] << 16), a3 = __uint_as_float(v[1] & 0xffff0000u);
;                     const float rs = rsqrtf(wave_sum(a0 * a0 + a1 * a1 + a2 * a2 + a3 * a3) * (1.f / 256.f) + NEPS);
;                     u32x2 o; o[0] = pk2(a0 * rs * ggq[0], a1 * rs * ggq[1]); o[1] = pk2(a2 * rs * ggq[2], a3 * rs * ggq[3]); *(u32x2*)(mlaa + (size_t)t * 384 + 4 * lane) = o; }
;                   { const unsigned v = vkv[u]; const float a0 = __uint_as_float(v << 16), a1 = __uint_as_float(v & 0xffff0000u);
;                     const float rs = rsqrtf(wave_sum(a0 * a0 + a1 * a1) * (1.f / 128.f) + NEPS);
;                     *(unsigned*)(mlaa + (size_t)t * 384 + 256 + 2 * lane) = pk2(a0 * rs * gkv0, a1 * rs * gkv1); }
; #pragma unroll
;                   for (int hq = 0; hq < 8; ++hq) { const unsigned v = vf[u][hq]; const float a0 = __uint_as_float(v << 16), a1 = __uint_as_float(v & 0xffff0000u);
;                     const float rs = rsqrtf(wave_sum(a0 * a0 + a1 * a1) * (1.f / 128.f) + NEPS) * ((hq < 4) ? 0.08838834764831845f * LOG2E : 1.f);
;                     *(unsigned*)(pr + 3520 + hq * 128 + 2 * lane) = pk2(a0 * rs * ((hq < 4) ? fq0 : fk0), a1 * rs * ((hq < 4) ? fq1 : fk1)); } } } }
	s_nop 0
	v_pk_fma_f32 v[28:29], v[28:29], s[96:97], v[18:19] op_sel_hi:[1,0,0]
	s_nop 0
	v_mul_f32_e32 v32, 0x4b800000, v29
	v_cmp_gt_f32_e64 s[0:1], s77, v29
	v_cmp_gt_f32_e32 vcc, s77, v28
	s_nop 0
	v_cndmask_b32_e64 v29, v29, v32, s[0:1]
	v_rsq_f32_e32 v29, v29
	s_nop 0
	v_mul_f32_e32 v32, 0x45800000, v29
	v_cndmask_b32_e64 v32, v29, v32, s[0:1]
	v_pk_mul_f32 v[26:27], v[32:33], v[26:27] op_sel_hi:[0,1]
	v_pk_mul_f32 v[26:27], v[10:11], v[26:27]
	s_nop 0
	v_cvt_pk_bf16_f32 v26, v26, v27
	global_store_dword v[22:23], v26, off offset:1024
	v_mul_f32_e32 v26, 0x4b800000, v28
	v_cndmask_b32_e32 v26, v28, v26, vcc
	v_rsq_f32_e32 v26, v26
	s_nop 0
	v_mul_f32_e32 v27, 0x45800000, v26
	v_cndmask_b32_e32 v26, v26, v27, vcc
	v_pk_mul_f32 v[26:27], v[26:27], v[30:31] op_sel_hi:[0,1]
	v_pk_mul_f32 v[26:27], v[10:11], v[26:27]
	v_lshlrev_b32_e32 v30, 16, v61
	v_cvt_pk_bf16_f32 v26, v26, v27
	global_store_dword v[22:23], v26, off offset:1280
	v_lshlrev_b32_e32 v26, 16, v62
	v_and_b32_e32 v27, 0xffff0000, v62
	v_and_b32_e32 v31, 0xffff0000, v61
	v_pk_mul_f32 v[28:29], v[26:27], v[26:27]
	v_pk_mul_f32 v[32:33], v[30:31], v[30:31]
	v_mov_b32_e32 v35, v28
	v_mov_b32_e32 v34, v32
	v_mov_b32_e32 v28, v33
	v_pk_add_f32 v[28:29], v[34:35], v[28:29]
	v_mov_b32_e32 v33, v29
	v_mov_b32_e32 v32, v28
	s_nop 0
	v_permlane32_swap_b32_e32 v33, v29
	v_permlane32_swap_b32_e32 v32, v28
	s_waitcnt lgkmcnt(0)
	v_pk_add_f32 v[28:29], v[28:29], v[32:33]
	v_mov_b32_e32 v33, v29
	v_mov_b32_e32 v32, v28
	s_nop 0
	v_permlane16_swap_b32_e32 v33, v29
	v_permlane16_swap_b32_e32 v32, v28
	s_waitcnt lgkmcnt(0)
	v_pk_add_f32 v[28:29], v[28:29], v[32:33]
	s_nop 1
	v_add_f32_dpp v29, v29, v29 row_ror:8 row_mask:0xf bank_mask:0xf
	v_add_f32_dpp v28, v28, v28 row_ror:8 row_mask:0xf bank_mask:0xf
	s_waitcnt lgkmcnt(0)
	s_nop 1
	v_add_f32_dpp v29, v29, v29 row_ror:4 row_mask:0xf bank_mask:0xf
	v_add_f32_dpp v28, v28, v28 row_ror:4 row_mask:0xf bank_mask:0xf
	s_waitcnt lgkmcnt(0)
	s_nop 1
	v_add_f32_dpp v29, v29, v29 quad_perm:[2,3,0,1] row_mask:0xf bank_mask:0xf
	v_add_f32_dpp v28, v28, v28 quad_perm:[2,3,0,1] row_mask:0xf bank_mask:0xf
	s_waitcnt lgkmcnt(0)
	s_nop 1
	v_add_f32_dpp v29, v29, v29 quad_perm:[1,0,3,2] row_mask:0xf bank_mask:0xf
	v_add_f32_dpp v28, v28, v28 quad_perm:[1,0,3,2] row_mask:0xf bank_mask:0xf
	s_waitcnt lgkmcnt(0)
	s_nop 0
	v_pk_fma_f32 v[28:29], v[28:29], s[96:97], v[18:19] op_sel_hi:[1,0,0]
	s_nop 0
	v_mul_f32_e32 v32, 0x4b800000, v29
	v_cmp_gt_f32_e64 s[0:1], s77, v29
	v_cmp_gt_f32_e32 vcc, s77, v28
	s_nop 0
	v_cndmask_b32_e64 v29, v29, v32, s[0:1]
	v_rsq_f32_e32 v29, v29
	s_nop 0
	v_mul_f32_e32 v32, 0x45800000, v29
	v_cndmask_b32_e64 v32, v29, v32, s[0:1]
	v_pk_mul_f32 v[26:27], v[32:33], v[26:27] op_sel_hi:[0,1]
	v_pk_mul_f32 v[26:27], v[10:11], v[26:27]
	s_waitcnt vmcnt(36)
	v_lshlrev_b32_e32 v32, 16, v60
	v_cvt_pk_bf16_f32 v26, v26, v27
	global_store_dword v[22:23], v26, off offset:1536
	v_mul_f32_e32 v26, 0x4b800000, v28
	v_cndmask_b32_e32 v26, v28, v26, vcc
	v_rsq_f32_e32 v26, v26
	v_and_b32_e32 v33, 0xffff0000, v60
	v_pk_mul_f32 v[34:35], v[32:33], v[32:33]
	v_mul_f32_e32 v27, 0x45800000, v26
	v_cndmask_b32_e32 v26, v26, v27, vcc
	v_pk_mul_f32 v[26:27], v[26:27], v[30:31] op_sel_hi:[0,1]
	v_pk_mul_f32 v[26:27], v[10:11], v[26:27]
	s_nop 0
	v_cvt_pk_bf16_f32 v26, v26, v27
	global_store_dword v[22:23], v26, off offset:1792
	v_and_b32_e32 v27, 0xffff0000, v25
	v_and_b32_e32 v26, s0, v24
	v_mov_b32_e32 v23, v27
	v_pk_mul_f32 v[28:29], v[26:27], v[26:27]
	v_and_b32_e32 v27, 0xffff0000, v24
	v_lshlrev_b32_e32 v26, 16, v24
	v_mul_f32_e32 v24, v27, v27
	v_lshlrev_b32_e32 v22, 16, v25
	v_pk_fma_f32 v[24:25], v[26:27], v[26:27], v[24:25] op_sel_hi:[1,1,0]
	v_mov_b32_e32 v28, v34
	v_pk_fma_f32 v[24:25], v[22:23], v[22:23], v[24:25]
	v_mad_i64_i32 v[20:21], s[0:1], v59, s22, v[20:21]
	v_pk_mov_b32 v[24:25], v[34:35], v[24:25] op_sel:[1,0]
	v_lshl_add_u64 v[30:31], v[20:21], 0, v[0:1]
	v_pk_add_f32 v[24:25], v[28:29], v[24:25]
	v_mov_b32_e32 v29, v25
	v_mov_b32_e32 v28, v24
	s_nop 0
	v_permlane32_swap_b32_e32 v29, v25
	v_permlane32_swap_b32_e32 v28, v24
	v_lshl_add_u64 v[20:21], v[20:21], 0, v[12:13]
	s_waitcnt lgkmcnt(0)
	v_pk_add_f32 v[24:25], v[24:25], v[28:29]
	v_mov_b32_e32 v29, v25
	v_mov_b32_e32 v28, v24
	s_nop 0
	v_permlane16_swap_b32_e32 v29, v25
	v_permlane16_swap_b32_e32 v28, v24
	s_waitcnt lgkmcnt(0)
	v_pk_add_f32 v[24:25], v[24:25], v[28:29]
	s_nop 1
	v_add_f32_dpp v25, v25, v25 row_ror:8 row_mask:0xf bank_mask:0xf
	v_add_f32_dpp v24, v24, v24 row_ror:8 row_mask:0xf bank_mask:0xf
	s_waitcnt lgkmcnt(0)
	s_nop 1
	v_add_f32_dpp v25, v25, v25 row_ror:4 row_mask:0xf bank_mask:0xf
	v_add_f32_dpp v24, v24, v24 row_ror:4 row_mask:0xf bank_mask:0xf
	s_waitcnt lgkmcnt(0)
	s_nop 1
	v_add_f32_dpp v25, v25, v25 quad_perm:[2,3,0,1] row_mask:0xf bank_mask:0xf
	v_add_f32_dpp v24, v24, v24 quad_perm:[2,3,0,1] row_mask:0xf bank_mask:0xf
	s_waitcnt lgkmcnt(0)
	s_nop 1
	v_add_f32_dpp v25, v25, v25 quad_perm:[1,0,3,2] row_mask:0xf bank_mask:0xf
	v_add_f32_dpp v24, v24, v24 quad_perm:[1,0,3,2] row_mask:0xf bank_mask:0xf
	s_waitcnt lgkmcnt(0)
	s_nop 0
	v_pk_fma_f32 v[24:25], v[24:25], s[96:97], v[18:19] op_sel_hi:[1,1,0]
	s_nop 0
	v_mul_f32_e32 v28, 0x4b800000, v25
	v_cmp_gt_f32_e64 s[0:1], s77, v25
	v_cmp_gt_f32_e32 vcc, s77, v24
	s_nop 0
	v_cndmask_b32_e64 v25, v25, v28, s[0:1]
	v_rsq_f32_e32 v25, v25
	s_nop 0
	v_mul_f32_e32 v28, 0x45800000, v25
	v_cndmask_b32_e64 v28, v25, v28, s[0:1]
	v_pk_mul_f32 v[26:27], v[28:29], v[26:27] op_sel_hi:[0,1]
	v_pk_mul_f32 v[22:23], v[28:29], v[22:23] op_sel_hi:[0,1]
	v_pk_mul_f32 v[26:27], v[2:3], v[26:27]
	v_pk_mul_f32 v[22:23], v[4:5], v[22:23]
	v_cvt_pk_bf16_f32 v26, v26, v27
	v_cvt_pk_bf16_f32 v27, v22, v23
	v_mul_f32_e32 v22, 0x4b800000, v24
	v_cndmask_b32_e32 v22, v24, v22, vcc
	v_rsq_f32_e32 v22, v22
	s_waitcnt vmcnt(36)
; DI unsigned pk2(float lo, float hi) { const f32x2 v = {lo, hi}; return __builtin_bit_cast(unsigned, __builtin_convertvector(v, bf16v2_t)); }
; DI float wave_sum(float v) { for (int o = 32; o; o >>= 1) v += __shfl_xor(v, o); return v; }
; DI void run_phase(const Params& p, int ph, unsigned char* smem, const int tid, const int rep) {
;     ...
;                   for (int hq = 0; hq < 8; ++hq) { const unsigned v = vf[u][hq]; const float a0 = __uint_as_float(v << 16), a1 = __uint_as_float(v & 0xffff0000u);
;                     const float rs = rsqrtf(wave_sum(a0 * a0 + a1 * a1) * (1.f / 128.f) + NEPS) * ((hq < 4) ? 0.08838834764831845f * LOG2E : 1.f);
;                     *(unsigned*)(pr + 3520 + hq * 128 + 2 * lane) = pk2(a0 * rs * ((hq < 4) ? fq0 : fk0), a1 * rs * ((hq < 4) ? fq1 : fk1)); } } } }
	v_lshlrev_b32_e32 v24, 16, v57
	v_and_b32_e32 v25, 0xffff0000, v57
	global_store_dwordx2 v[30:31], v[26:27], off
	v_mul_f32_e32 v23, 0x45800000, v22
	v_cndmask_b32_e32 v22, v22, v23, vcc
	v_pk_mul_f32 v[22:23], v[22:23], v[32:33] op_sel_hi:[0,1]
	v_pk_mul_f32 v[22:23], v[6:7], v[22:23]
	v_pk_mul_f32 v[26:27], v[24:25], v[24:25]
	v_cvt_pk_bf16_f32 v22, v22, v23
	global_store_dword v[20:21], v22, off offset:512
	v_lshlrev_b32_e32 v20, 16, v58
	v_and_b32_e32 v21, 0xffff0000, v58
	v_pk_mul_f32 v[22:23], v[20:21], v[20:21]
	v_mov_b32_e32 v28, v26
	v_mov_b32_e32 v29, v22
	v_mov_b32_e32 v22, v27
	v_pk_add_f32 v[22:23], v[28:29], v[22:23]
	v_mov_b32_e32 v27, v23
	v_mov_b32_e32 v26, v22
	s_nop 0
	v_permlane32_swap_b32_e32 v27, v23
	v_permlane32_swap_b32_e32 v26, v22
	s_waitcnt lgkmcnt(0)
	v_pk_add_f32 v[22:23], v[22:23], v[26:27]
	v_mov_b32_e32 v27, v23
	v_mov_b32_e32 v26, v22
	s_nop 0
	v_permlane16_swap_b32_e32 v27, v23
	v_permlane16_swap_b32_e32 v26, v22
	s_waitcnt lgkmcnt(0)
	v_pk_add_f32 v[22:23], v[22:23], v[26:27]
	s_nop 1
	v_add_f32_dpp v23, v23, v23 row_ror:8 row_mask:0xf bank_mask:0xf
	v_add_f32_dpp v22, v22, v22 row_ror:8 row_mask:0xf bank_mask:0xf
	s_waitcnt lgkmcnt(0)
	s_nop 1
	v_add_f32_dpp v23, v23, v23 row_ror:4 row_mask:0xf bank_mask:0xf
	v_add_f32_dpp v22, v22, v22 row_ror:4 row_mask:0xf bank_mask:0xf
	s_waitcnt lgkmcnt(0)
	s_nop 1
	v_add_f32_dpp v23, v23, v23 quad_perm:[2,3,0,1] row_mask:0xf bank_mask:0xf
	v_add_f32_dpp v22, v22, v22 quad_perm:[2,3,0,1] row_mask:0xf bank_mask:0xf
	s_waitcnt lgkmcnt(0)
	s_nop 1
	v_add_f32_dpp v23, v23, v23 quad_perm:[1,0,3,2] row_mask:0xf bank_mask:0xf
	v_add_f32_dpp v22, v22, v22 quad_perm:[1,0,3,2] row_mask:0xf bank_mask:0xf
	s_waitcnt lgkmcnt(0)
	s_nop 0
	v_pk_fma_f32 v[22:23], v[22:23], s[96:97], v[18:19] op_sel_hi:[1,0,0]
	s_nop 0
	v_mul_f32_e32 v13, 0x4b800000, v23
	v_cmp_gt_f32_e64 s[0:1], s77, v23
	v_cmp_gt_f32_e32 vcc, s77, v22
	s_nop 0
	v_cndmask_b32_e64 v13, v23, v13, s[0:1]
	v_rsq_f32_e32 v13, v13
	s_nop 0
	v_mul_f32_e32 v23, 0x45800000, v13
	v_cndmask_b32_e64 v13, v13, v23, s[0:1]
	v_mul_f32_e32 v26, 0x3e0293ee, v13
	v_pk_mul_f32 v[20:21], v[26:27], v[20:21] op_sel_hi:[0,1]
	v_pk_mul_f32 v[20:21], v[8:9], v[20:21]
	s_waitcnt vmcnt(36)
	v_and_b32_e32 v23, 0xffff0000, v55
	v_cvt_pk_bf16_f32 v13, v20, v21
	global_store_dword v[16:17], v13, off offset:2944
	v_mul_f32_e32 v13, 0x4b800000, v22
	v_cndmask_b32_e32 v13, v22, v13, vcc
	v_rsq_f32_e32 v13, v13
	v_lshlrev_b32_e32 v22, 16, v55
	v_mul_f32_e32 v16, 0x45800000, v13
	v_cndmask_b32_e32 v13, v13, v16, vcc
	v_mul_f32_e32 v16, 0x3e0293ee, v13
	v_pk_mul_f32 v[16:17], v[16:17], v[24:25] op_sel_hi:[0,1]
	v_pk_mul_f32 v[16:17], v[8:9], v[16:17]
	v_pk_mul_f32 v[24:25], v[22:23], v[22:23]
	v_cvt_pk_bf16_f32 v13, v16, v17
	v_lshlrev_b32_e32 v16, 16, v56
	v_and_b32_e32 v17, 0xffff0000, v56
	v_pk_mul_f32 v[20:21], v[16:17], v[16:17]
	v_mov_b32_e32 v26, v24
	v_mov_b32_e32 v27, v20
	v_mov_b32_e32 v20, v25
	v_pk_add_f32 v[20:21], v[26:27], v[20:21]
	v_mov_b32_e32 v25, v21
	v_mov_b32_e32 v24, v20
	s_nop 0
	v_permlane32_swap_b32_e32 v25, v21
	v_permlane32_swap_b32_e32 v24, v20
	global_store_dword v[14:15], v13, off offset:256
	s_waitcnt lgkmcnt(0)
	v_pk_add_f32 v[20:21], v[20:21], v[24:25]
	v_mov_b32_e32 v25, v21
	v_mov_b32_e32 v24, v20
	s_nop 0
	v_permlane16_swap_b32_e32 v25, v21
	v_permlane16_swap_b32_e32 v24, v20
	s_waitcnt lgkmcnt(0)
	v_pk_add_f32 v[20:21], v[20:21], v[24:25]
	s_nop 1
	v_add_f32_dpp v21, v21, v21 row_ror:8 row_mask:0xf bank_mask:0xf
	v_add_f32_dpp v20, v20, v20 row_ror:8 row_mask:0xf bank_mask:0xf
	s_waitcnt lgkmcnt(0)
	s_nop 1
	v_add_f32_dpp v21, v21, v21 row_ror:4 row_mask:0xf bank_mask:0xf
	v_add_f32_dpp v20, v20, v20 row_ror:4 row_mask:0xf bank_mask:0xf
	s_waitcnt lgkmcnt(0)
	s_nop 1
	v_add_f32_dpp v21, v21, v21 quad_perm:[2,3,0,1] row_mask:0xf bank_mask:0xf
	v_add_f32_dpp v20, v20, v20 quad_perm:[2,3,0,1] row_mask:0xf bank_mask:0xf
	s_waitcnt lgkmcnt(0)
	s_nop 1
	v_add_f32_dpp v21, v21, v21 quad_perm:[1,0,3,2] row_mask:0xf bank_mask:0xf
	v_add_f32_dpp v20, v20, v20 quad_perm:[1,0,3,2] row_mask:0xf bank_mask:0xf
	s_waitcnt lgkmcnt(0)
	s_nop 0
	v_pk_fma_f32 v[20:21], v[20:21], s[96:97], v[18:19] op_sel_hi:[1,0,0]
	s_nop 0
	v_mul_f32_e32 v13, 0x4b800000, v21
	v_cmp_gt_f32_e64 s[0:1], s77, v21
	v_cmp_gt_f32_e32 vcc, s77, v20
	s_nop 0
	v_cndmask_b32_e64 v13, v21, v13, s[0:1]
	v_rsq_f32_e32 v13, v13
	s_nop 0
	v_mul_f32_e32 v21, 0x45800000, v13
	v_cndmask_b32_e64 v13, v13, v21, s[0:1]
	v_mul_f32_e32 v24, 0x3e0293ee, v13
	v_pk_mul_f32 v[16:17], v[24:25], v[16:17] op_sel_hi:[0,1]
	v_pk_mul_f32 v[16:17], v[8:9], v[16:17]
	s_nop 0
	v_cvt_pk_bf16_f32 v13, v16, v17
	global_store_dword v[14:15], v13, off offset:512
	v_mul_f32_e32 v13, 0x4b800000, v20
	v_cndmask_b32_e32 v13, v20, v13, vcc
	v_rsq_f32_e32 v13, v13
	s_nop 0
	v_mul_f32_e32 v16, 0x45800000, v13
	v_cndmask_b32_e32 v13, v13, v16, vcc
	v_mul_f32_e32 v16, 0x3e0293ee, v13
	v_pk_mul_f32 v[16:17], v[16:17], v[22:23] op_sel_hi:[0,1]
	v_pk_mul_f32 v[16:17], v[8:9], v[16:17]
	s_waitcnt vmcnt(37)
; DI unsigned pk2(float lo, float hi) { const f32x2 v = {lo, hi}; return __builtin_bit_cast(unsigned, __builtin_convertvector(v, bf16v2_t)); }
; DI float wave_sum(float v) { for (int o = 32; o; o >>= 1) v += __shfl_xor(v, o); return v; }
; DI void run_phase(const Params& p, int ph, unsigned char* smem, const int tid, const int rep) {
;     ...
;           for (int t0 = (blockIdx.x * 8 + wv) * 4; t0 < TS; t0 += gridDim.x * 32) {
;     ...
;                   for (int hq = 0; hq < 8; ++hq) { const unsigned v = vf[u][hq]; const float a0 = __uint_as_float(v << 16), a1 = __uint_as_float(v & 0xffff0000u);
;                     const float rs = rsqrtf(wave_sum(a0 * a0 + a1 * a1) * (1.f / 128.f) + NEPS) * ((hq < 4) ? 0.08838834764831845f * LOG2E : 1.f);
;                     *(unsigned*)(pr + 3520 + hq * 128 + 2 * lane) = pk2(a0 * rs * ((hq < 4) ? fq0 : fk0), a1 * rs * ((hq < 4) ? fq1 : fk1)); } } } }
	v_lshlrev_b32_e32 v22, 16, v53
	v_cvt_pk_bf16_f32 v13, v16, v17
	v_lshlrev_b32_e32 v16, 16, v54
	v_and_b32_e32 v17, 0xffff0000, v54
	v_and_b32_e32 v23, 0xffff0000, v53
	v_pk_mul_f32 v[20:21], v[16:17], v[16:17]
	v_pk_mul_f32 v[24:25], v[22:23], v[22:23]
	v_mov_b32_e32 v27, v20
	v_mov_b32_e32 v26, v24
	v_mov_b32_e32 v20, v25
	v_pk_add_f32 v[20:21], v[26:27], v[20:21]
	v_mov_b32_e32 v25, v21
	v_mov_b32_e32 v24, v20
	s_nop 0
	v_permlane32_swap_b32_e32 v25, v21
	v_permlane32_swap_b32_e32 v24, v20
	global_store_dword v[14:15], v13, off offset:768
	s_waitcnt lgkmcnt(0)
	v_pk_add_f32 v[20:21], v[20:21], v[24:25]
	v_mov_b32_e32 v25, v21
	v_mov_b32_e32 v24, v20
	s_nop 0
	v_permlane16_swap_b32_e32 v25, v21
	v_permlane16_swap_b32_e32 v24, v20
	s_waitcnt lgkmcnt(0)
	v_pk_add_f32 v[20:21], v[20:21], v[24:25]
	s_nop 1
	v_add_f32_dpp v21, v21, v21 row_ror:8 row_mask:0xf bank_mask:0xf
	v_add_f32_dpp v20, v20, v20 row_ror:8 row_mask:0xf bank_mask:0xf
	s_waitcnt lgkmcnt(0)
	s_nop 1
	v_add_f32_dpp v21, v21, v21 row_ror:4 row_mask:0xf bank_mask:0xf
	v_add_f32_dpp v20, v20, v20 row_ror:4 row_mask:0xf bank_mask:0xf
	s_waitcnt lgkmcnt(0)
	s_nop 1
	v_add_f32_dpp v21, v21, v21 quad_perm:[2,3,0,1] row_mask:0xf bank_mask:0xf
	v_add_f32_dpp v20, v20, v20 quad_perm:[2,3,0,1] row_mask:0xf bank_mask:0xf
	s_waitcnt lgkmcnt(0)
	s_nop 1
	v_add_f32_dpp v21, v21, v21 quad_perm:[1,0,3,2] row_mask:0xf bank_mask:0xf
	v_add_f32_dpp v20, v20, v20 quad_perm:[1,0,3,2] row_mask:0xf bank_mask:0xf
	s_waitcnt lgkmcnt(0)
	s_nop 0
	v_pk_fma_f32 v[20:21], v[20:21], s[96:97], v[18:19] op_sel_hi:[1,0,0]
	s_nop 0
	v_mul_f32_e32 v13, 0x4b800000, v21
	v_cmp_gt_f32_e64 s[0:1], s77, v21
	v_cmp_gt_f32_e32 vcc, s77, v20
	s_nop 0
	v_cndmask_b32_e64 v13, v21, v13, s[0:1]
	v_rsq_f32_e32 v13, v13
	s_nop 0
	v_mul_f32_e32 v21, 0x45800000, v13
	v_cndmask_b32_e64 v24, v13, v21, s[0:1]
	v_pk_mul_f32 v[16:17], v[24:25], v[16:17] op_sel_hi:[0,1]
	v_pk_mul_f32 v[16:17], v[10:11], v[16:17]
	s_nop 0
	v_cvt_pk_bf16_f32 v13, v16, v17
	global_store_dword v[14:15], v13, off offset:1024
	v_mul_f32_e32 v13, 0x4b800000, v20
	v_cndmask_b32_e32 v13, v20, v13, vcc
	v_rsq_f32_e32 v13, v13
	s_nop 0
	v_mul_f32_e32 v16, 0x45800000, v13
	v_cndmask_b32_e32 v16, v13, v16, vcc
	v_pk_mul_f32 v[16:17], v[16:17], v[22:23] op_sel_hi:[0,1]
	v_pk_mul_f32 v[16:17], v[10:11], v[16:17]
	s_waitcnt vmcnt(37)
	v_lshlrev_b32_e32 v22, 16, v51
	v_cvt_pk_bf16_f32 v13, v16, v17
	v_lshlrev_b32_e32 v16, 16, v52
	v_and_b32_e32 v17, 0xffff0000, v52
	v_and_b32_e32 v23, 0xffff0000, v51
	v_pk_mul_f32 v[20:21], v[16:17], v[16:17]
	v_pk_mul_f32 v[24:25], v[22:23], v[22:23]
	v_mov_b32_e32 v27, v20
	v_mov_b32_e32 v26, v24
	v_mov_b32_e32 v20, v25
	v_pk_add_f32 v[20:21], v[26:27], v[20:21]
	v_mov_b32_e32 v25, v21
	v_mov_b32_e32 v24, v20
	s_nop 0
	v_permlane32_swap_b32_e32 v25, v21
	v_permlane32_swap_b32_e32 v24, v20
	global_store_dword v[14:15], v13, off offset:1280
	s_waitcnt lgkmcnt(0)
	v_pk_add_f32 v[20:21], v[20:21], v[24:25]
	v_mov_b32_e32 v25, v21
	v_mov_b32_e32 v24, v20
	s_nop 0
	v_permlane16_swap_b32_e32 v25, v21
	v_permlane16_swap_b32_e32 v24, v20
	s_waitcnt lgkmcnt(0)
	v_pk_add_f32 v[20:21], v[20:21], v[24:25]
	s_nop 1
	v_add_f32_dpp v21, v21, v21 row_ror:8 row_mask:0xf bank_mask:0xf
	v_add_f32_dpp v20, v20, v20 row_ror:8 row_mask:0xf bank_mask:0xf
	s_waitcnt lgkmcnt(0)
	s_nop 1
	v_add_f32_dpp v21, v21, v21 row_ror:4 row_mask:0xf bank_mask:0xf
	v_add_f32_dpp v20, v20, v20 row_ror:4 row_mask:0xf bank_mask:0xf
	s_waitcnt lgkmcnt(0)
	s_nop 1
	v_add_f32_dpp v21, v21, v21 quad_perm:[2,3,0,1] row_mask:0xf bank_mask:0xf
	v_add_f32_dpp v20, v20, v20 quad_perm:[2,3,0,1] row_mask:0xf bank_mask:0xf
	s_waitcnt lgkmcnt(0)
	s_nop 1
	v_add_f32_dpp v21, v21, v21 quad_perm:[1,0,3,2] row_mask:0xf bank_mask:0xf
	v_add_f32_dpp v20, v20, v20 quad_perm:[1,0,3,2] row_mask:0xf bank_mask:0xf
	s_waitcnt lgkmcnt(0)
	s_nop 0
	v_pk_fma_f32 v[18:19], v[20:21], s[96:97], v[18:19] op_sel_hi:[1,0,0]
	s_nop 0
	v_mul_f32_e32 v13, 0x4b800000, v19
	v_cmp_gt_f32_e64 s[0:1], s77, v19
	v_cmp_gt_f32_e32 vcc, s77, v18
	s_nop 0
	v_cndmask_b32_e64 v13, v19, v13, s[0:1]
	v_rsq_f32_e32 v13, v13
	s_nop 0
	v_mul_f32_e32 v19, 0x45800000, v13
	v_cndmask_b32_e64 v20, v13, v19, s[0:1]
	v_pk_mul_f32 v[16:17], v[20:21], v[16:17] op_sel_hi:[0,1]
	v_pk_mul_f32 v[16:17], v[10:11], v[16:17]
	s_nop 0
	v_cvt_pk_bf16_f32 v13, v16, v17
	global_store_dword v[14:15], v13, off offset:1536
	v_mul_f32_e32 v13, 0x4b800000, v18
	v_cndmask_b32_e32 v13, v18, v13, vcc
	v_rsq_f32_e32 v13, v13
	s_nop 0
	v_mul_f32_e32 v16, 0x45800000, v13
	v_cndmask_b32_e32 v16, v13, v16, vcc
	v_pk_mul_f32 v[16:17], v[16:17], v[22:23] op_sel_hi:[0,1]
	v_pk_mul_f32 v[16:17], v[10:11], v[16:17]
	v_cmp_lt_i32_e32 vcc, s11, v44
	v_cvt_pk_bf16_f32 v13, v16, v17
	s_or_b64 s[40:41], vcc, s[40:41]
	global_store_dword v[14:15], v13, off offset:1792
	s_andn2_b64 exec, exec, s[40:41]
	s_cbranch_execnz .LBB0_372

; DI float wave_sum(float v) { for (int o = 32; o; o >>= 1) v += __shfl_xor(v, o); return v; }
; DI void rmsnorm_phase(const float* x, const float* g, bf16_t* h, int ntok, const int tid) {
;     ...
;     for (int t0 = (blockIdx.x * 8 + wv) * 2; t0 < ntok; t0 += gridDim.x * 16) {
;         f32x4 v[2][4];
; #pragma unroll
;         for (int u = 0; u < 2; ++u)
; #pragma unroll
;             for (int c = 0; c < 4; ++c) v[u][c] = ((const f32x4*)(x + (size_t)(t0 + u) * 1024))[lane + 64 * c];
; #pragma unroll
;         for (int u = 0; u < 2; ++u) { float ss = 0.f;
; #pragma unroll
;             for (int c = 0; c < 4; ++c) ss += v[u][c][0] * v[u][c][0] + v[u][c][1] * v[u][c][1] + v[u][c][2] * v[u][c][2] + v[u][c][3] * v[u][c][3];
;             ss = wave_sum(ss);
.LBB0_702:
	v_ashrrev_i32_e32 v51, 31, v50
	v_lshlrev_b64 v[18:19], 12, v[50:51]
	v_add_u32_e32 v56, 1, v50
	v_lshl_add_u64 v[18:19], v[52:53], 0, v[18:19]
	v_ashrrev_i32_e32 v57, 31, v56
	global_load_dwordx4 v[46:49], v[18:19], off
	global_load_dwordx4 v[42:45], v[18:19], off offset:1024
	global_load_dwordx4 v[38:41], v[18:19], off offset:2048
	global_load_dwordx4 v[34:37], v[18:19], off offset:3072
	v_lshlrev_b64 v[18:19], 12, v[56:57]
	v_lshl_add_u64 v[18:19], v[52:53], 0, v[18:19]
	global_load_dwordx4 v[30:33], v[18:19], off
	global_load_dwordx4 v[26:29], v[18:19], off offset:1024
	global_load_dwordx4 v[22:25], v[18:19], off offset:2048
	s_nop 0
	global_load_dwordx4 v[18:21], v[18:19], off offset:3072
	s_waitcnt vmcnt(7)
	v_mov_b32_e32 v66, v47
	s_waitcnt vmcnt(6)
	v_mov_b32_e32 v67, v43
	v_mov_b32_e32 v58, v46
	s_waitcnt vmcnt(3)
	v_mov_b32_e32 v72, v31
	s_waitcnt vmcnt(2)
	v_mov_b32_e32 v73, v27
	v_mov_b32_e32 v59, v42
	v_pk_mul_f32 v[66:67], v[66:67], v[66:67]
	v_mov_b32_e32 v70, v30
	v_mov_b32_e32 v71, v26
	v_pk_mul_f32 v[72:73], v[72:73], v[72:73]
	v_pk_fma_f32 v[58:59], v[58:59], v[58:59], v[66:67]
	v_mov_b32_e32 v66, v48
	v_mov_b32_e32 v67, v44
	v_pk_fma_f32 v[70:71], v[70:71], v[70:71], v[72:73]
	v_mov_b32_e32 v72, v32
	v_mov_b32_e32 v73, v28
	v_pk_fma_f32 v[58:59], v[66:67], v[66:67], v[58:59]
	v_mov_b32_e32 v66, v49
	v_mov_b32_e32 v67, v45
	v_mov_b32_e32 v68, v39
	v_mov_b32_e32 v69, v35
	v_pk_fma_f32 v[70:71], v[72:73], v[72:73], v[70:71]
	v_mov_b32_e32 v72, v33
	v_mov_b32_e32 v73, v29
	s_waitcnt vmcnt(1)
	v_mov_b32_e32 v74, v23
	s_waitcnt vmcnt(0)
	v_mov_b32_e32 v75, v19
	v_pk_fma_f32 v[66:67], v[66:67], v[66:67], v[58:59]
	v_mov_b32_e32 v58, v38
	v_mov_b32_e32 v59, v34
	v_pk_mul_f32 v[68:69], v[68:69], v[68:69]
	v_pk_fma_f32 v[70:71], v[72:73], v[72:73], v[70:71]
	v_mov_b32_e32 v72, v22
	v_mov_b32_e32 v73, v18
	v_pk_mul_f32 v[74:75], v[74:75], v[74:75]
	v_pk_fma_f32 v[58:59], v[58:59], v[58:59], v[68:69]
	v_mov_b32_e32 v68, v40
	v_mov_b32_e32 v69, v36
	v_pk_fma_f32 v[72:73], v[72:73], v[72:73], v[74:75]
	v_mov_b32_e32 v74, v24
	v_mov_b32_e32 v75, v20
	v_pk_fma_f32 v[58:59], v[68:69], v[68:69], v[58:59]
	v_mov_b32_e32 v68, v41
	v_mov_b32_e32 v69, v37
	v_pk_fma_f32 v[72:73], v[74:75], v[74:75], v[72:73]
	v_mov_b32_e32 v74, v25
	v_mov_b32_e32 v75, v21
	v_pk_fma_f32 v[68:69], v[68:69], v[68:69], v[58:59]
	v_pk_fma_f32 v[72:73], v[74:75], v[74:75], v[72:73]
	v_mov_b32_e32 v74, v70
	v_mov_b32_e32 v75, v66
	v_mov_b32_e32 v66, v71
	v_pk_add_f32 v[66:67], v[74:75], v[66:67]
	v_mov_b32_e32 v70, v72
	v_mov_b32_e32 v71, v68
	v_pk_add_f32 v[66:67], v[66:67], v[70:71]
	v_mov_b32_e32 v68, v73
	v_pk_add_f32 v[66:67], v[66:67], v[68:69]
	v_mov_b32_e32 v69, v67
	v_mov_b32_e32 v68, v66
	s_nop 0
	v_permlane32_swap_b32_e32 v69, v67
	v_permlane32_swap_b32_e32 v68, v66
	v_lshlrev_b64 v[58:59], 11, v[50:51]
	v_lshl_add_u64 v[58:59], v[54:55], 0, v[58:59]
	v_add_u32_e32 v50, s17, v50
	s_waitcnt lgkmcnt(0)
	v_pk_add_f32 v[66:67], v[66:67], v[68:69]
	v_mov_b32_e32 v69, v67
	v_mov_b32_e32 v68, v66
	s_nop 0
	v_permlane16_swap_b32_e32 v69, v67
	v_permlane16_swap_b32_e32 v68, v66
	s_waitcnt lgkmcnt(0)
	v_pk_add_f32 v[66:67], v[66:67], v[68:69]
	s_nop 1
	v_add_f32_dpp v67, v67, v67 row_ror:8 row_mask:0xf bank_mask:0xf
	v_add_f32_dpp v66, v66, v66 row_ror:8 row_mask:0xf bank_mask:0xf
	s_waitcnt lgkmcnt(0)
	s_nop 1
	v_add_f32_dpp v67, v67, v67 row_ror:4 row_mask:0xf bank_mask:0xf
	v_add_f32_dpp v66, v66, v66 row_ror:4 row_mask:0xf bank_mask:0xf
	s_waitcnt lgkmcnt(0)
; DI unsigned pk2(float lo, float hi) { const f32x2 v = {lo, hi}; return __builtin_bit_cast(unsigned, __builtin_convertvector(v, bf16v2_t)); }
; DI float wave_sum(float v) { for (int o = 32; o; o >>= 1) v += __shfl_xor(v, o); return v; }
; DI void rmsnorm_phase(const float* x, const float* g, bf16_t* h, int ntok, const int tid) {
;     ...
;         for (int u = 0; u < 2; ++u) { float ss = 0.f;
; #pragma unroll
;             for (int c = 0; c < 4; ++c) ss += v[u][c][0] * v[u][c][0] + v[u][c][1] * v[u][c][1] + v[u][c][2] * v[u][c][2] + v[u][c][3] * v[u][c][3];
;             ss = wave_sum(ss);
;             const float rs = rsqrtf(ss * (1.f / 1024.f) + NEPS);
; #pragma unroll
;             for (int c = 0; c < 4; ++c) { u32x2 o; o[0] = pk2(v[u][c][0] * rs * gg[c][0], v[u][c][1] * rs * gg[c][1]); o[1] = pk2(v[u][c][2] * rs * gg[c][2], v[u][c][3] * rs * gg[c][3]);
;                 *(u32x2*)(h + (size_t)(t0 + u) * 1024 + (lane + 64 * c) * 4) = o; } }
;     }
	s_nop 1
	v_add_f32_dpp v67, v67, v67 quad_perm:[2,3,0,1] row_mask:0xf bank_mask:0xf
	v_add_f32_dpp v66, v66, v66 quad_perm:[2,3,0,1] row_mask:0xf bank_mask:0xf
	s_waitcnt lgkmcnt(0)
	s_nop 1
	v_add_f32_dpp v67, v67, v67 quad_perm:[1,0,3,2] row_mask:0xf bank_mask:0xf
	v_add_f32_dpp v66, v66, v66 quad_perm:[1,0,3,2] row_mask:0xf bank_mask:0xf
	s_waitcnt lgkmcnt(0)
	s_nop 0
	v_pk_fma_f32 v[66:67], v[66:67], s[4:5], v[190:191] op_sel_hi:[1,0,0]
	s_nop 0
	v_mul_f32_e32 v0, 0x4b800000, v67
	v_cmp_gt_f32_e64 s[0:1], s77, v67
	v_cmp_gt_f32_e32 vcc, s77, v66
	s_nop 0
	v_cndmask_b32_e64 v0, v67, v0, s[0:1]
	v_rsq_f32_e32 v0, v0
	s_nop 0
	v_mul_f32_e32 v51, 0x45800000, v0
	v_cndmask_b32_e64 v0, v0, v51, s[0:1]
	v_pk_mul_f32 v[46:47], v[46:47], v[0:1] op_sel_hi:[1,0]
	v_pk_mul_f32 v[48:49], v[48:49], v[0:1] op_sel_hi:[1,0]
	v_pk_mul_f32 v[42:43], v[42:43], v[0:1] op_sel_hi:[1,0]
	v_pk_mul_f32 v[44:45], v[44:45], v[0:1] op_sel_hi:[1,0]
	v_pk_mul_f32 v[38:39], v[38:39], v[0:1] op_sel_hi:[1,0]
	v_pk_mul_f32 v[40:41], v[40:41], v[0:1] op_sel_hi:[1,0]
	v_pk_mul_f32 v[34:35], v[34:35], v[0:1] op_sel_hi:[1,0]
	v_pk_mul_f32 v[36:37], v[36:37], v[0:1] op_sel_hi:[1,0]
	v_mul_f32_e32 v0, 0x4b800000, v66
	v_cndmask_b32_e32 v0, v66, v0, vcc
	v_rsq_f32_e32 v0, v0
	v_pk_mul_f32 v[34:35], v[2:3], v[34:35]
	v_pk_mul_f32 v[36:37], v[4:5], v[36:37]
	v_cvt_pk_bf16_f32 v34, v34, v35
	v_cvt_pk_bf16_f32 v35, v36, v37
	global_store_dwordx2 v[58:59], v[34:35], off offset:1536
	v_mul_f32_e32 v34, 0x45800000, v0
	v_cndmask_b32_e32 v0, v0, v34, vcc
	v_pk_mul_f32 v[30:31], v[30:31], v[0:1] op_sel_hi:[1,0]
	v_pk_mul_f32 v[32:33], v[32:33], v[0:1] op_sel_hi:[1,0]
	v_pk_mul_f32 v[26:27], v[26:27], v[0:1] op_sel_hi:[1,0]
	v_pk_mul_f32 v[28:29], v[28:29], v[0:1] op_sel_hi:[1,0]
	v_pk_mul_f32 v[22:23], v[22:23], v[0:1] op_sel_hi:[1,0]
	v_pk_mul_f32 v[24:25], v[24:25], v[0:1] op_sel_hi:[1,0]
	v_pk_mul_f32 v[18:19], v[18:19], v[0:1] op_sel_hi:[1,0]
	v_pk_mul_f32 v[20:21], v[20:21], v[0:1] op_sel_hi:[1,0]
	v_pk_mul_f32 v[46:47], v[14:15], v[46:47]
	v_pk_mul_f32 v[48:49], v[16:17], v[48:49]
	v_pk_mul_f32 v[42:43], v[10:11], v[42:43]
	v_pk_mul_f32 v[44:45], v[12:13], v[44:45]
	v_pk_mul_f32 v[38:39], v[6:7], v[38:39]
	v_pk_mul_f32 v[40:41], v[8:9], v[40:41]
	v_lshlrev_b64 v[34:35], 11, v[56:57]
	v_pk_mul_f32 v[30:31], v[14:15], v[30:31]
	v_pk_mul_f32 v[32:33], v[16:17], v[32:33]
	v_pk_mul_f32 v[26:27], v[10:11], v[26:27]
	v_pk_mul_f32 v[28:29], v[12:13], v[28:29]
	v_pk_mul_f32 v[22:23], v[6:7], v[22:23]
	v_pk_mul_f32 v[24:25], v[8:9], v[24:25]
	v_pk_mul_f32 v[18:19], v[2:3], v[18:19]
	v_pk_mul_f32 v[20:21], v[4:5], v[20:21]
	v_cmp_lt_i32_e32 vcc, s16, v50
	v_cvt_pk_bf16_f32 v46, v46, v47
	v_cvt_pk_bf16_f32 v47, v48, v49
	v_cvt_pk_bf16_f32 v42, v42, v43
	v_cvt_pk_bf16_f32 v43, v44, v45
	v_cvt_pk_bf16_f32 v38, v38, v39
	v_cvt_pk_bf16_f32 v39, v40, v41
	v_cvt_pk_bf16_f32 v30, v30, v31
	v_cvt_pk_bf16_f32 v31, v32, v33
	v_lshl_add_u64 v[32:33], v[54:55], 0, v[34:35]
	v_cvt_pk_bf16_f32 v26, v26, v27
	v_cvt_pk_bf16_f32 v27, v28, v29
	v_cvt_pk_bf16_f32 v22, v22, v23
	v_cvt_pk_bf16_f32 v23, v24, v25
	v_cvt_pk_bf16_f32 v18, v18, v19
	v_cvt_pk_bf16_f32 v19, v20, v21
	s_or_b64 s[12:13], vcc, s[12:13]
	global_store_dwordx2 v[58:59], v[46:47], off
	global_store_dwordx2 v[58:59], v[42:43], off offset:512
	global_store_dwordx2 v[58:59], v[38:39], off offset:1024
	global_store_dwordx2 v[32:33], v[30:31], off
	global_store_dwordx2 v[32:33], v[26:27], off offset:512
	global_store_dwordx2 v[32:33], v[22:23], off offset:1024
	global_store_dwordx2 v[32:33], v[18:19], off offset:1536
	s_andn2_b64 exec, exec, s[12:13]
	s_cbranch_execnz .LBB0_702
	s_getpc_b64 s[98:99]
